# hand-written epilogues for IN_DA (Q/K/gate tiles, pipelined rope loads), RET_QKV and HG: tile-uniform region dispatch, math interleaved with 16-byte stores
# speedup vs baseline: 1.1563x; 1.0175x over previous
.LBB0_78:
	v_readfirstlane_b32 s100, v178
	s_nop 0
	s_lshr_b32 s100, s100, 6
	s_lshr_b32 s101, s100, 2
	s_and_b32 s100, s100, 3
	s_lshl_b32 s101, s101, 7
	s_add_i32 s101, s101, s16
	s_lshl_b32 s100, s100, 6
	s_mov_b32 s7, 0x8000
	s_mov_b32 s2, 11
	v_and_b32_e32 v242, 15, v178
	v_bfe_u32 v243, v178, 4, 1
	v_lshlrev_b32_e32 v242, s2, v242
	v_lshl_add_u32 v242, v243, 5, v242
	v_bfe_u32 v243, v178, 5, 1
	s_nop 0
	v_lshl_add_u32 v242, v243, 4, v242
	s_mov_b32 s6, s54
	s_cmpk_ge_u32 s58, 0xc00
	s_cbranch_scc1 .Lepi2_gate
	s_cmpk_ge_u32 s58, 0x400
	s_cbranch_scc1 .Lepi2_k
	s_add_i32 s3, s58, s100
	s_lshl_b32 s3, s3, 1
	s_lshl_b32 s5, s101, 11
	s_add_u32 s3, s3, s5
	s_add_u32 s98, s68, s3
	s_addc_u32 s99, s69, 0
	s_cmpk_ge_u32 s16, 0x2000
	s_cbranch_scc1 .Lepi2_qrope
	v_pk_mul_f32 v[124:125], v[124:125], s[6:7] op_sel_hi:[1,0]
	v_pk_mul_f32 v[126:127], v[126:127], s[6:7] op_sel_hi:[1,0]
	v_pk_mul_f32 v[120:121], v[120:121], s[6:7] op_sel_hi:[1,0]
	v_pk_mul_f32 v[122:123], v[122:123], s[6:7] op_sel_hi:[1,0]
	v_pk_mul_f32 v[116:117], v[116:117], s[6:7] op_sel_hi:[1,0]
	v_pk_mul_f32 v[118:119], v[118:119], s[6:7] op_sel_hi:[1,0]
	v_pk_mul_f32 v[112:113], v[112:113], s[6:7] op_sel_hi:[1,0]
	v_pk_mul_f32 v[114:115], v[114:115], s[6:7] op_sel_hi:[1,0]
	v_cvt_pk_bf16_f32 v124, v124, v125
	v_cvt_pk_bf16_f32 v125, v126, v127
	v_cvt_pk_bf16_f32 v126, v120, v121
	v_cvt_pk_bf16_f32 v127, v122, v123
	v_cvt_pk_bf16_f32 v116, v116, v117
	v_cvt_pk_bf16_f32 v117, v118, v119
	v_cvt_pk_bf16_f32 v118, v112, v113
	v_cvt_pk_bf16_f32 v119, v114, v115
	v_permlane16_swap_b32_e32 v124, v126
	v_permlane16_swap_b32_e32 v125, v127
	v_permlane16_swap_b32_e32 v116, v118
	v_permlane16_swap_b32_e32 v117, v119
	global_store_dwordx4 v242, v[124:127], s[98:99]
	global_store_dwordx4 v242, v[116:119], s[98:99] offset:64
	s_add_u32 s98, s98, s7
	s_addc_u32 s99, s99, 0
	v_pk_mul_f32 v[108:109], v[108:109], s[6:7] op_sel_hi:[1,0]
	v_pk_mul_f32 v[110:111], v[110:111], s[6:7] op_sel_hi:[1,0]
	v_pk_mul_f32 v[104:105], v[104:105], s[6:7] op_sel_hi:[1,0]
	v_pk_mul_f32 v[106:107], v[106:107], s[6:7] op_sel_hi:[1,0]
	v_pk_mul_f32 v[100:101], v[100:101], s[6:7] op_sel_hi:[1,0]
	v_pk_mul_f32 v[102:103], v[102:103], s[6:7] op_sel_hi:[1,0]
	v_pk_mul_f32 v[96:97], v[96:97], s[6:7] op_sel_hi:[1,0]
	v_pk_mul_f32 v[98:99], v[98:99], s[6:7] op_sel_hi:[1,0]
	v_cvt_pk_bf16_f32 v108, v108, v109
	v_cvt_pk_bf16_f32 v109, v110, v111
	v_cvt_pk_bf16_f32 v110, v104, v105
	v_cvt_pk_bf16_f32 v111, v106, v107
	v_cvt_pk_bf16_f32 v100, v100, v101
	v_cvt_pk_bf16_f32 v101, v102, v103
	v_cvt_pk_bf16_f32 v102, v96, v97
	v_cvt_pk_bf16_f32 v103, v98, v99
	v_permlane16_swap_b32_e32 v108, v110
	v_permlane16_swap_b32_e32 v109, v111
	v_permlane16_swap_b32_e32 v100, v102
	v_permlane16_swap_b32_e32 v101, v103
	global_store_dwordx4 v242, v[108:111], s[98:99]
	global_store_dwordx4 v242, v[100:103], s[98:99] offset:64
	s_add_u32 s98, s98, s7
	s_addc_u32 s99, s99, 0
	v_pk_mul_f32 v[92:93], v[92:93], s[6:7] op_sel_hi:[1,0]
	v_pk_mul_f32 v[94:95], v[94:95], s[6:7] op_sel_hi:[1,0]
	v_pk_mul_f32 v[88:89], v[88:89], s[6:7] op_sel_hi:[1,0]
	v_pk_mul_f32 v[90:91], v[90:91], s[6:7] op_sel_hi:[1,0]
	v_pk_mul_f32 v[84:85], v[84:85], s[6:7] op_sel_hi:[1,0]
	v_pk_mul_f32 v[86:87], v[86:87], s[6:7] op_sel_hi:[1,0]
	v_pk_mul_f32 v[80:81], v[80:81], s[6:7] op_sel_hi:[1,0]
	v_pk_mul_f32 v[82:83], v[82:83], s[6:7] op_sel_hi:[1,0]
	v_cvt_pk_bf16_f32 v92, v92, v93
	v_cvt_pk_bf16_f32 v93, v94, v95
	v_cvt_pk_bf16_f32 v94, v88, v89
	v_cvt_pk_bf16_f32 v95, v90, v91
	v_cvt_pk_bf16_f32 v84, v84, v85
	v_cvt_pk_bf16_f32 v85, v86, v87
	v_cvt_pk_bf16_f32 v86, v80, v81
	v_cvt_pk_bf16_f32 v87, v82, v83
	v_permlane16_swap_b32_e32 v92, v94
	v_permlane16_swap_b32_e32 v93, v95
	v_permlane16_swap_b32_e32 v84, v86
	v_permlane16_swap_b32_e32 v85, v87
	global_store_dwordx4 v242, v[92:95], s[98:99]
	global_store_dwordx4 v242, v[84:87], s[98:99] offset:64
	s_add_u32 s98, s98, s7
	s_addc_u32 s99, s99, 0
	v_pk_mul_f32 v[76:77], v[76:77], s[6:7] op_sel_hi:[1,0]
	v_pk_mul_f32 v[78:79], v[78:79], s[6:7] op_sel_hi:[1,0]
	v_pk_mul_f32 v[72:73], v[72:73], s[6:7] op_sel_hi:[1,0]
	v_pk_mul_f32 v[74:75], v[74:75], s[6:7] op_sel_hi:[1,0]
	v_pk_mul_f32 v[68:69], v[68:69], s[6:7] op_sel_hi:[1,0]
	v_pk_mul_f32 v[70:71], v[70:71], s[6:7] op_sel_hi:[1,0]
	v_pk_mul_f32 v[64:65], v[64:65], s[6:7] op_sel_hi:[1,0]
	v_pk_mul_f32 v[66:67], v[66:67], s[6:7] op_sel_hi:[1,0]
	v_cvt_pk_bf16_f32 v76, v76, v77
	v_cvt_pk_bf16_f32 v77, v78, v79
	v_cvt_pk_bf16_f32 v78, v72, v73
	v_cvt_pk_bf16_f32 v79, v74, v75
	v_cvt_pk_bf16_f32 v68, v68, v69
	v_cvt_pk_bf16_f32 v69, v70, v71
	v_cvt_pk_bf16_f32 v70, v64, v65
	v_cvt_pk_bf16_f32 v71, v66, v67
	v_permlane16_swap_b32_e32 v76, v78
	v_permlane16_swap_b32_e32 v77, v79
	v_permlane16_swap_b32_e32 v68, v70
	v_permlane16_swap_b32_e32 v69, v71
	global_store_dwordx4 v242, v[76:79], s[98:99]
	global_store_dwordx4 v242, v[68:71], s[98:99] offset:64
	s_add_u32 s98, s98, s7
	s_addc_u32 s99, s99, 0
	v_pk_mul_f32 v[60:61], v[60:61], s[6:7] op_sel_hi:[1,0]
	v_pk_mul_f32 v[62:63], v[62:63], s[6:7] op_sel_hi:[1,0]
	v_pk_mul_f32 v[56:57], v[56:57], s[6:7] op_sel_hi:[1,0]
	v_pk_mul_f32 v[58:59], v[58:59], s[6:7] op_sel_hi:[1,0]
	v_pk_mul_f32 v[52:53], v[52:53], s[6:7] op_sel_hi:[1,0]
	v_pk_mul_f32 v[54:55], v[54:55], s[6:7] op_sel_hi:[1,0]
	v_pk_mul_f32 v[48:49], v[48:49], s[6:7] op_sel_hi:[1,0]
	v_pk_mul_f32 v[50:51], v[50:51], s[6:7] op_sel_hi:[1,0]
	v_cvt_pk_bf16_f32 v60, v60, v61
	v_cvt_pk_bf16_f32 v61, v62, v63
	v_cvt_pk_bf16_f32 v62, v56, v57
	v_cvt_pk_bf16_f32 v63, v58, v59
	v_cvt_pk_bf16_f32 v52, v52, v53
	v_cvt_pk_bf16_f32 v53, v54, v55
	v_cvt_pk_bf16_f32 v54, v48, v49
	v_cvt_pk_bf16_f32 v55, v50, v51
	v_permlane16_swap_b32_e32 v60, v62
	v_permlane16_swap_b32_e32 v61, v63
	v_permlane16_swap_b32_e32 v52, v54
	v_permlane16_swap_b32_e32 v53, v55
	global_store_dwordx4 v242, v[60:63], s[98:99]
	global_store_dwordx4 v242, v[52:55], s[98:99] offset:64
	s_add_u32 s98, s98, s7
	s_addc_u32 s99, s99, 0
	v_pk_mul_f32 v[44:45], v[44:45], s[6:7] op_sel_hi:[1,0]
	v_pk_mul_f32 v[46:47], v[46:47], s[6:7] op_sel_hi:[1,0]
	v_pk_mul_f32 v[40:41], v[40:41], s[6:7] op_sel_hi:[1,0]
	v_pk_mul_f32 v[42:43], v[42:43], s[6:7] op_sel_hi:[1,0]
	v_pk_mul_f32 v[36:37], v[36:37], s[6:7] op_sel_hi:[1,0]
	v_pk_mul_f32 v[38:39], v[38:39], s[6:7] op_sel_hi:[1,0]
	v_pk_mul_f32 v[32:33], v[32:33], s[6:7] op_sel_hi:[1,0]
	v_pk_mul_f32 v[34:35], v[34:35], s[6:7] op_sel_hi:[1,0]
	v_cvt_pk_bf16_f32 v44, v44, v45
	v_cvt_pk_bf16_f32 v45, v46, v47
	v_cvt_pk_bf16_f32 v46, v40, v41
	v_cvt_pk_bf16_f32 v47, v42, v43
	v_cvt_pk_bf16_f32 v36, v36, v37
	v_cvt_pk_bf16_f32 v37, v38, v39
	v_cvt_pk_bf16_f32 v38, v32, v33
	v_cvt_pk_bf16_f32 v39, v34, v35
	v_permlane16_swap_b32_e32 v44, v46
	v_permlane16_swap_b32_e32 v45, v47
	v_permlane16_swap_b32_e32 v36, v38
	v_permlane16_swap_b32_e32 v37, v39
	global_store_dwordx4 v242, v[44:47], s[98:99]
	global_store_dwordx4 v242, v[36:39], s[98:99] offset:64
	s_add_u32 s98, s98, s7
	s_addc_u32 s99, s99, 0
	v_pk_mul_f32 v[28:29], v[28:29], s[6:7] op_sel_hi:[1,0]
	v_pk_mul_f32 v[30:31], v[30:31], s[6:7] op_sel_hi:[1,0]
	v_pk_mul_f32 v[24:25], v[24:25], s[6:7] op_sel_hi:[1,0]
	v_pk_mul_f32 v[26:27], v[26:27], s[6:7] op_sel_hi:[1,0]
	v_pk_mul_f32 v[20:21], v[20:21], s[6:7] op_sel_hi:[1,0]
	v_pk_mul_f32 v[22:23], v[22:23], s[6:7] op_sel_hi:[1,0]
	v_pk_mul_f32 v[16:17], v[16:17], s[6:7] op_sel_hi:[1,0]
	v_pk_mul_f32 v[18:19], v[18:19], s[6:7] op_sel_hi:[1,0]
	v_cvt_pk_bf16_f32 v28, v28, v29
	v_cvt_pk_bf16_f32 v29, v30, v31
	v_cvt_pk_bf16_f32 v30, v24, v25
	v_cvt_pk_bf16_f32 v31, v26, v27
	v_cvt_pk_bf16_f32 v20, v20, v21
	v_cvt_pk_bf16_f32 v21, v22, v23
	v_cvt_pk_bf16_f32 v22, v16, v17
	v_cvt_pk_bf16_f32 v23, v18, v19
	v_permlane16_swap_b32_e32 v28, v30
	v_permlane16_swap_b32_e32 v29, v31
	v_permlane16_swap_b32_e32 v20, v22
	v_permlane16_swap_b32_e32 v21, v23
	global_store_dwordx4 v242, v[28:31], s[98:99]
	global_store_dwordx4 v242, v[20:23], s[98:99] offset:64
	s_add_u32 s98, s98, s7
	s_addc_u32 s99, s99, 0
	v_pk_mul_f32 v[12:13], v[12:13], s[6:7] op_sel_hi:[1,0]
	v_pk_mul_f32 v[14:15], v[14:15], s[6:7] op_sel_hi:[1,0]
	v_pk_mul_f32 v[8:9], v[8:9], s[6:7] op_sel_hi:[1,0]
	v_pk_mul_f32 v[10:11], v[10:11], s[6:7] op_sel_hi:[1,0]
	v_pk_mul_f32 v[4:5], v[4:5], s[6:7] op_sel_hi:[1,0]
	v_pk_mul_f32 v[6:7], v[6:7], s[6:7] op_sel_hi:[1,0]
	v_pk_mul_f32 v[0:1], v[0:1], s[6:7] op_sel_hi:[1,0]
	v_pk_mul_f32 v[2:3], v[2:3], s[6:7] op_sel_hi:[1,0]
	v_cvt_pk_bf16_f32 v12, v12, v13
	v_cvt_pk_bf16_f32 v13, v14, v15
	v_cvt_pk_bf16_f32 v14, v8, v9
	v_cvt_pk_bf16_f32 v15, v10, v11
	v_cvt_pk_bf16_f32 v4, v4, v5
	v_cvt_pk_bf16_f32 v5, v6, v7
	v_cvt_pk_bf16_f32 v6, v0, v1
	v_cvt_pk_bf16_f32 v7, v2, v3
	v_permlane16_swap_b32_e32 v12, v14
	v_permlane16_swap_b32_e32 v13, v15
	v_permlane16_swap_b32_e32 v4, v6
	v_permlane16_swap_b32_e32 v5, v7
	global_store_dwordx4 v242, v[12:15], s[98:99]
	global_store_dwordx4 v242, v[4:7], s[98:99] offset:64
	s_branch .LBB0_61
.Lepi2_qrope:
	s_sub_i32 s3, s101, 0x2000
	s_and_b32 s3, s3, 0x7ff
	s_lshl_b32 s3, s3, 8
	s_add_u32 s2, s88, s3
	s_addc_u32 s3, s89, 0
	v_and_b32_e32 v243, 15, v178
	v_bfe_u32 v244, v178, 4, 2
	v_lshlrev_b32_e32 v243, 8, v243
	v_lshl_add_u32 v243, v244, 4, v243
	global_load_dwordx4 v[150:153], v243, s[2:3]
	global_load_dwordx4 v[194:197], v243, s[2:3] offset:64
	global_load_dwordx4 v[198:201], v243, s[2:3] offset:128
	global_load_dwordx4 v[202:205], v243, s[2:3] offset:192
	s_add_u32 s2, s2, 0x1000
	s_addc_u32 s3, s3, 0
	global_load_dwordx4 v[142:145], v243, s[2:3]
	global_load_dwordx4 v[246:249], v243, s[2:3] offset:64
	global_load_dwordx4 v[250:253], v243, s[2:3] offset:128
	s_waitcnt vmcnt(6)
	v_mul_f32_e32 v244, v125, v151
	v_mul_f32_e32 v245, v124, v151
	v_mul_f32_e32 v124, v124, v150
	v_fma_f32 v125, v125, v150, v245
	v_sub_f32_e32 v124, v124, v244
	v_mul_f32_e32 v244, v127, v153
	v_mul_f32_e32 v245, v126, v153
	v_fma_f32 v126, v126, v152, -v244
	v_fma_f32 v127, v127, v152, v245
	v_pk_mul_f32 v[124:125], v[124:125], s[6:7] op_sel_hi:[1,0]
	v_pk_mul_f32 v[126:127], v[126:127], s[6:7] op_sel_hi:[1,0]
	global_load_dwordx4 v[150:153], v243, s[2:3] offset:192
	s_waitcnt vmcnt(6)
	v_mul_f32_e32 v244, v121, v195
	v_mul_f32_e32 v245, v120, v195
	v_mul_f32_e32 v120, v120, v194
	v_fma_f32 v121, v121, v194, v245
	v_sub_f32_e32 v120, v120, v244
	v_mul_f32_e32 v244, v123, v197
	v_mul_f32_e32 v245, v122, v197
	v_fma_f32 v122, v122, v196, -v244
	v_fma_f32 v123, v123, v196, v245
	v_pk_mul_f32 v[120:121], v[120:121], s[6:7] op_sel_hi:[1,0]
	v_pk_mul_f32 v[122:123], v[122:123], s[6:7] op_sel_hi:[1,0]
	s_add_u32 s2, s2, 0x1000
	s_addc_u32 s3, s3, 0
	global_load_dwordx4 v[194:197], v243, s[2:3]
	s_waitcnt vmcnt(6)
	v_mul_f32_e32 v244, v117, v199
	v_mul_f32_e32 v245, v116, v199
	v_mul_f32_e32 v116, v116, v198
	v_fma_f32 v117, v117, v198, v245
	v_sub_f32_e32 v116, v116, v244
	v_mul_f32_e32 v244, v119, v201
	v_mul_f32_e32 v245, v118, v201
	v_fma_f32 v118, v118, v200, -v244
	v_fma_f32 v119, v119, v200, v245
	v_pk_mul_f32 v[116:117], v[116:117], s[6:7] op_sel_hi:[1,0]
	v_pk_mul_f32 v[118:119], v[118:119], s[6:7] op_sel_hi:[1,0]
	global_load_dwordx4 v[198:201], v243, s[2:3] offset:64
	s_waitcnt vmcnt(6)
	v_mul_f32_e32 v244, v113, v203
	v_mul_f32_e32 v245, v112, v203
	v_mul_f32_e32 v112, v112, v202
	v_fma_f32 v113, v113, v202, v245
	v_sub_f32_e32 v112, v112, v244
	v_mul_f32_e32 v244, v115, v205
	v_mul_f32_e32 v245, v114, v205
	v_fma_f32 v114, v114, v204, -v244
	v_fma_f32 v115, v115, v204, v245
	v_pk_mul_f32 v[112:113], v[112:113], s[6:7] op_sel_hi:[1,0]
	v_pk_mul_f32 v[114:115], v[114:115], s[6:7] op_sel_hi:[1,0]
	v_cvt_pk_bf16_f32 v124, v124, v125
	v_cvt_pk_bf16_f32 v125, v126, v127
	v_cvt_pk_bf16_f32 v126, v120, v121
	v_cvt_pk_bf16_f32 v127, v122, v123
	v_cvt_pk_bf16_f32 v116, v116, v117
	v_cvt_pk_bf16_f32 v117, v118, v119
	v_cvt_pk_bf16_f32 v118, v112, v113
	v_cvt_pk_bf16_f32 v119, v114, v115
	v_permlane16_swap_b32_e32 v124, v126
	v_permlane16_swap_b32_e32 v125, v127
	v_permlane16_swap_b32_e32 v116, v118
	v_permlane16_swap_b32_e32 v117, v119
	global_store_dwordx4 v242, v[124:127], s[98:99]
	global_store_dwordx4 v242, v[116:119], s[98:99] offset:64
	s_add_u32 s98, s98, s7
	s_addc_u32 s99, s99, 0
	global_load_dwordx4 v[202:205], v243, s[2:3] offset:128
	s_waitcnt vmcnt(8)
	v_mul_f32_e32 v244, v109, v143
	v_mul_f32_e32 v245, v108, v143
	v_mul_f32_e32 v108, v108, v142
	v_fma_f32 v109, v109, v142, v245
	v_sub_f32_e32 v108, v108, v244
	v_mul_f32_e32 v244, v111, v145
	v_mul_f32_e32 v245, v110, v145
	v_fma_f32 v110, v110, v144, -v244
	v_fma_f32 v111, v111, v144, v245
	v_pk_mul_f32 v[108:109], v[108:109], s[6:7] op_sel_hi:[1,0]
	v_pk_mul_f32 v[110:111], v[110:111], s[6:7] op_sel_hi:[1,0]
	global_load_dwordx4 v[142:145], v243, s[2:3] offset:192
	s_waitcnt vmcnt(8)
	v_mul_f32_e32 v244, v105, v247
	v_mul_f32_e32 v245, v104, v247
	v_mul_f32_e32 v104, v104, v246
	v_fma_f32 v105, v105, v246, v245
	v_sub_f32_e32 v104, v104, v244
	v_mul_f32_e32 v244, v107, v249
	v_mul_f32_e32 v245, v106, v249
	v_fma_f32 v106, v106, v248, -v244
	v_fma_f32 v107, v107, v248, v245
	v_pk_mul_f32 v[104:105], v[104:105], s[6:7] op_sel_hi:[1,0]
	v_pk_mul_f32 v[106:107], v[106:107], s[6:7] op_sel_hi:[1,0]
	s_add_u32 s2, s2, 0x1000
	s_addc_u32 s3, s3, 0
	global_load_dwordx4 v[246:249], v243, s[2:3]
	s_waitcnt vmcnt(8)
	v_mul_f32_e32 v244, v101, v251
	v_mul_f32_e32 v245, v100, v251
	v_mul_f32_e32 v100, v100, v250
	v_fma_f32 v101, v101, v250, v245
	v_sub_f32_e32 v100, v100, v244
	v_mul_f32_e32 v244, v103, v253
	v_mul_f32_e32 v245, v102, v253
	v_fma_f32 v102, v102, v252, -v244
	v_fma_f32 v103, v103, v252, v245
	v_pk_mul_f32 v[100:101], v[100:101], s[6:7] op_sel_hi:[1,0]
	v_pk_mul_f32 v[102:103], v[102:103], s[6:7] op_sel_hi:[1,0]
	global_load_dwordx4 v[250:253], v243, s[2:3] offset:64
	s_waitcnt vmcnt(8)
	v_mul_f32_e32 v244, v97, v151
	v_mul_f32_e32 v245, v96, v151
	v_mul_f32_e32 v96, v96, v150
	v_fma_f32 v97, v97, v150, v245
	v_sub_f32_e32 v96, v96, v244
	v_mul_f32_e32 v244, v99, v153
	v_mul_f32_e32 v245, v98, v153
	v_fma_f32 v98, v98, v152, -v244
	v_fma_f32 v99, v99, v152, v245
	v_pk_mul_f32 v[96:97], v[96:97], s[6:7] op_sel_hi:[1,0]
	v_pk_mul_f32 v[98:99], v[98:99], s[6:7] op_sel_hi:[1,0]
	v_cvt_pk_bf16_f32 v108, v108, v109
	v_cvt_pk_bf16_f32 v109, v110, v111
	v_cvt_pk_bf16_f32 v110, v104, v105
	v_cvt_pk_bf16_f32 v111, v106, v107
	v_cvt_pk_bf16_f32 v100, v100, v101
	v_cvt_pk_bf16_f32 v101, v102, v103
	v_cvt_pk_bf16_f32 v102, v96, v97
	v_cvt_pk_bf16_f32 v103, v98, v99
	v_permlane16_swap_b32_e32 v108, v110
	v_permlane16_swap_b32_e32 v109, v111
	v_permlane16_swap_b32_e32 v100, v102
	v_permlane16_swap_b32_e32 v101, v103
	global_store_dwordx4 v242, v[108:111], s[98:99]
	global_store_dwordx4 v242, v[100:103], s[98:99] offset:64
	s_add_u32 s98, s98, s7
	s_addc_u32 s99, s99, 0
	global_load_dwordx4 v[150:153], v243, s[2:3] offset:128
	s_waitcnt vmcnt(10)
	v_mul_f32_e32 v244, v93, v195
	v_mul_f32_e32 v245, v92, v195
	v_mul_f32_e32 v92, v92, v194
	v_fma_f32 v93, v93, v194, v245
	v_sub_f32_e32 v92, v92, v244
	v_mul_f32_e32 v244, v95, v197
	v_mul_f32_e32 v245, v94, v197
	v_fma_f32 v94, v94, v196, -v244
	v_fma_f32 v95, v95, v196, v245
	v_pk_mul_f32 v[92:93], v[92:93], s[6:7] op_sel_hi:[1,0]
	v_pk_mul_f32 v[94:95], v[94:95], s[6:7] op_sel_hi:[1,0]
	global_load_dwordx4 v[194:197], v243, s[2:3] offset:192
	s_waitcnt vmcnt(10)
	v_mul_f32_e32 v244, v89, v199
	v_mul_f32_e32 v245, v88, v199
	v_mul_f32_e32 v88, v88, v198
	v_fma_f32 v89, v89, v198, v245
	v_sub_f32_e32 v88, v88, v244
	v_mul_f32_e32 v244, v91, v201
	v_mul_f32_e32 v245, v90, v201
	v_fma_f32 v90, v90, v200, -v244
	v_fma_f32 v91, v91, v200, v245
	v_pk_mul_f32 v[88:89], v[88:89], s[6:7] op_sel_hi:[1,0]
	v_pk_mul_f32 v[90:91], v[90:91], s[6:7] op_sel_hi:[1,0]
	s_add_u32 s2, s2, 0x1000
	s_addc_u32 s3, s3, 0
	global_load_dwordx4 v[198:201], v243, s[2:3]
	s_waitcnt vmcnt(8)
	v_mul_f32_e32 v244, v85, v203
	v_mul_f32_e32 v245, v84, v203
	v_mul_f32_e32 v84, v84, v202
	v_fma_f32 v85, v85, v202, v245
	v_sub_f32_e32 v84, v84, v244
	v_mul_f32_e32 v244, v87, v205
	v_mul_f32_e32 v245, v86, v205
	v_fma_f32 v86, v86, v204, -v244
	v_fma_f32 v87, v87, v204, v245
	v_pk_mul_f32 v[84:85], v[84:85], s[6:7] op_sel_hi:[1,0]
	v_pk_mul_f32 v[86:87], v[86:87], s[6:7] op_sel_hi:[1,0]
	global_load_dwordx4 v[202:205], v243, s[2:3] offset:64
	s_waitcnt vmcnt(8)
	v_mul_f32_e32 v244, v81, v143
	v_mul_f32_e32 v245, v80, v143
	v_mul_f32_e32 v80, v80, v142
	v_fma_f32 v81, v81, v142, v245
	v_sub_f32_e32 v80, v80, v244
	v_mul_f32_e32 v244, v83, v145
	v_mul_f32_e32 v245, v82, v145
	v_fma_f32 v82, v82, v144, -v244
	v_fma_f32 v83, v83, v144, v245
	v_pk_mul_f32 v[80:81], v[80:81], s[6:7] op_sel_hi:[1,0]
	v_pk_mul_f32 v[82:83], v[82:83], s[6:7] op_sel_hi:[1,0]
	v_cvt_pk_bf16_f32 v92, v92, v93
	v_cvt_pk_bf16_f32 v93, v94, v95
	v_cvt_pk_bf16_f32 v94, v88, v89
	v_cvt_pk_bf16_f32 v95, v90, v91
	v_cvt_pk_bf16_f32 v84, v84, v85
	v_cvt_pk_bf16_f32 v85, v86, v87
	v_cvt_pk_bf16_f32 v86, v80, v81
	v_cvt_pk_bf16_f32 v87, v82, v83
	v_permlane16_swap_b32_e32 v92, v94
	v_permlane16_swap_b32_e32 v93, v95
	v_permlane16_swap_b32_e32 v84, v86
	v_permlane16_swap_b32_e32 v85, v87
	global_store_dwordx4 v242, v[92:95], s[98:99]
	global_store_dwordx4 v242, v[84:87], s[98:99] offset:64
	s_add_u32 s98, s98, s7
	s_addc_u32 s99, s99, 0
	global_load_dwordx4 v[142:145], v243, s[2:3] offset:128
	s_waitcnt vmcnt(10)
	v_mul_f32_e32 v244, v77, v247
	v_mul_f32_e32 v245, v76, v247
	v_mul_f32_e32 v76, v76, v246
	v_fma_f32 v77, v77, v246, v245
	v_sub_f32_e32 v76, v76, v244
	v_mul_f32_e32 v244, v79, v249
	v_mul_f32_e32 v245, v78, v249
	v_fma_f32 v78, v78, v248, -v244
	v_fma_f32 v79, v79, v248, v245
	v_pk_mul_f32 v[76:77], v[76:77], s[6:7] op_sel_hi:[1,0]
	v_pk_mul_f32 v[78:79], v[78:79], s[6:7] op_sel_hi:[1,0]
	global_load_dwordx4 v[246:249], v243, s[2:3] offset:192
	s_waitcnt vmcnt(10)
	v_mul_f32_e32 v244, v73, v251
	v_mul_f32_e32 v245, v72, v251
	v_mul_f32_e32 v72, v72, v250
	v_fma_f32 v73, v73, v250, v245
	v_sub_f32_e32 v72, v72, v244
	v_mul_f32_e32 v244, v75, v253
	v_mul_f32_e32 v245, v74, v253
	v_fma_f32 v74, v74, v252, -v244
	v_fma_f32 v75, v75, v252, v245
	v_pk_mul_f32 v[72:73], v[72:73], s[6:7] op_sel_hi:[1,0]
	v_pk_mul_f32 v[74:75], v[74:75], s[6:7] op_sel_hi:[1,0]
	s_add_u32 s2, s2, 0x1000
	s_addc_u32 s3, s3, 0
	global_load_dwordx4 v[250:253], v243, s[2:3]
	s_waitcnt vmcnt(8)
	v_mul_f32_e32 v244, v69, v151
	v_mul_f32_e32 v245, v68, v151
	v_mul_f32_e32 v68, v68, v150
	v_fma_f32 v69, v69, v150, v245
	v_sub_f32_e32 v68, v68, v244
	v_mul_f32_e32 v244, v71, v153
	v_mul_f32_e32 v245, v70, v153
	v_fma_f32 v70, v70, v152, -v244
	v_fma_f32 v71, v71, v152, v245
	v_pk_mul_f32 v[68:69], v[68:69], s[6:7] op_sel_hi:[1,0]
	v_pk_mul_f32 v[70:71], v[70:71], s[6:7] op_sel_hi:[1,0]
	global_load_dwordx4 v[150:153], v243, s[2:3] offset:64
	s_waitcnt vmcnt(8)
	v_mul_f32_e32 v244, v65, v195
	v_mul_f32_e32 v245, v64, v195
	v_mul_f32_e32 v64, v64, v194
	v_fma_f32 v65, v65, v194, v245
	v_sub_f32_e32 v64, v64, v244
	v_mul_f32_e32 v244, v67, v197
	v_mul_f32_e32 v245, v66, v197
	v_fma_f32 v66, v66, v196, -v244
	v_fma_f32 v67, v67, v196, v245
	v_pk_mul_f32 v[64:65], v[64:65], s[6:7] op_sel_hi:[1,0]
	v_pk_mul_f32 v[66:67], v[66:67], s[6:7] op_sel_hi:[1,0]
	v_cvt_pk_bf16_f32 v76, v76, v77
	v_cvt_pk_bf16_f32 v77, v78, v79
	v_cvt_pk_bf16_f32 v78, v72, v73
	v_cvt_pk_bf16_f32 v79, v74, v75
	v_cvt_pk_bf16_f32 v68, v68, v69
	v_cvt_pk_bf16_f32 v69, v70, v71
	v_cvt_pk_bf16_f32 v70, v64, v65
	v_cvt_pk_bf16_f32 v71, v66, v67
	v_permlane16_swap_b32_e32 v76, v78
	v_permlane16_swap_b32_e32 v77, v79
	v_permlane16_swap_b32_e32 v68, v70
	v_permlane16_swap_b32_e32 v69, v71
	global_store_dwordx4 v242, v[76:79], s[98:99]
	global_store_dwordx4 v242, v[68:71], s[98:99] offset:64
	s_add_u32 s98, s98, s7
	s_addc_u32 s99, s99, 0
	global_load_dwordx4 v[194:197], v243, s[2:3] offset:128
	s_waitcnt vmcnt(10)
	v_mul_f32_e32 v244, v61, v199
	v_mul_f32_e32 v245, v60, v199
	v_mul_f32_e32 v60, v60, v198
	v_fma_f32 v61, v61, v198, v245
	v_sub_f32_e32 v60, v60, v244
	v_mul_f32_e32 v244, v63, v201
	v_mul_f32_e32 v245, v62, v201
	v_fma_f32 v62, v62, v200, -v244
	v_fma_f32 v63, v63, v200, v245
	v_pk_mul_f32 v[60:61], v[60:61], s[6:7] op_sel_hi:[1,0]
	v_pk_mul_f32 v[62:63], v[62:63], s[6:7] op_sel_hi:[1,0]
	global_load_dwordx4 v[198:201], v243, s[2:3] offset:192
	s_waitcnt vmcnt(10)
	v_mul_f32_e32 v244, v57, v203
	v_mul_f32_e32 v245, v56, v203
	v_mul_f32_e32 v56, v56, v202
	v_fma_f32 v57, v57, v202, v245
	v_sub_f32_e32 v56, v56, v244
	v_mul_f32_e32 v244, v59, v205
	v_mul_f32_e32 v245, v58, v205
	v_fma_f32 v58, v58, v204, -v244
	v_fma_f32 v59, v59, v204, v245
	v_pk_mul_f32 v[56:57], v[56:57], s[6:7] op_sel_hi:[1,0]
	v_pk_mul_f32 v[58:59], v[58:59], s[6:7] op_sel_hi:[1,0]
	s_add_u32 s2, s2, 0x1000
	s_addc_u32 s3, s3, 0
	global_load_dwordx4 v[202:205], v243, s[2:3]
	s_waitcnt vmcnt(8)
	v_mul_f32_e32 v244, v53, v143
	v_mul_f32_e32 v245, v52, v143
	v_mul_f32_e32 v52, v52, v142
	v_fma_f32 v53, v53, v142, v245
	v_sub_f32_e32 v52, v52, v244
	v_mul_f32_e32 v244, v55, v145
	v_mul_f32_e32 v245, v54, v145
	v_fma_f32 v54, v54, v144, -v244
	v_fma_f32 v55, v55, v144, v245
	v_pk_mul_f32 v[52:53], v[52:53], s[6:7] op_sel_hi:[1,0]
	v_pk_mul_f32 v[54:55], v[54:55], s[6:7] op_sel_hi:[1,0]
	global_load_dwordx4 v[142:145], v243, s[2:3] offset:64
	s_waitcnt vmcnt(8)
	v_mul_f32_e32 v244, v49, v247
	v_mul_f32_e32 v245, v48, v247
	v_mul_f32_e32 v48, v48, v246
	v_fma_f32 v49, v49, v246, v245
	v_sub_f32_e32 v48, v48, v244
	v_mul_f32_e32 v244, v51, v249
	v_mul_f32_e32 v245, v50, v249
	v_fma_f32 v50, v50, v248, -v244
	v_fma_f32 v51, v51, v248, v245
	v_pk_mul_f32 v[48:49], v[48:49], s[6:7] op_sel_hi:[1,0]
	v_pk_mul_f32 v[50:51], v[50:51], s[6:7] op_sel_hi:[1,0]
	v_cvt_pk_bf16_f32 v60, v60, v61
	v_cvt_pk_bf16_f32 v61, v62, v63
	v_cvt_pk_bf16_f32 v62, v56, v57
	v_cvt_pk_bf16_f32 v63, v58, v59
	v_cvt_pk_bf16_f32 v52, v52, v53
	v_cvt_pk_bf16_f32 v53, v54, v55
	v_cvt_pk_bf16_f32 v54, v48, v49
	v_cvt_pk_bf16_f32 v55, v50, v51
	v_permlane16_swap_b32_e32 v60, v62
	v_permlane16_swap_b32_e32 v61, v63
	v_permlane16_swap_b32_e32 v52, v54
	v_permlane16_swap_b32_e32 v53, v55
	global_store_dwordx4 v242, v[60:63], s[98:99]
	global_store_dwordx4 v242, v[52:55], s[98:99] offset:64
	s_add_u32 s98, s98, s7
	s_addc_u32 s99, s99, 0
	global_load_dwordx4 v[246:249], v243, s[2:3] offset:128
	s_waitcnt vmcnt(10)
	v_mul_f32_e32 v244, v45, v251
	v_mul_f32_e32 v245, v44, v251
	v_mul_f32_e32 v44, v44, v250
	v_fma_f32 v45, v45, v250, v245
	v_sub_f32_e32 v44, v44, v244
	v_mul_f32_e32 v244, v47, v253
	v_mul_f32_e32 v245, v46, v253
	v_fma_f32 v46, v46, v252, -v244
	v_fma_f32 v47, v47, v252, v245
	v_pk_mul_f32 v[44:45], v[44:45], s[6:7] op_sel_hi:[1,0]
	v_pk_mul_f32 v[46:47], v[46:47], s[6:7] op_sel_hi:[1,0]
	global_load_dwordx4 v[250:253], v243, s[2:3] offset:192
	s_waitcnt vmcnt(10)
	v_mul_f32_e32 v244, v41, v151
	v_mul_f32_e32 v245, v40, v151
	v_mul_f32_e32 v40, v40, v150
	v_fma_f32 v41, v41, v150, v245
	v_sub_f32_e32 v40, v40, v244
	v_mul_f32_e32 v244, v43, v153
	v_mul_f32_e32 v245, v42, v153
	v_fma_f32 v42, v42, v152, -v244
	v_fma_f32 v43, v43, v152, v245
	v_pk_mul_f32 v[40:41], v[40:41], s[6:7] op_sel_hi:[1,0]
	v_pk_mul_f32 v[42:43], v[42:43], s[6:7] op_sel_hi:[1,0]
	s_add_u32 s2, s2, 0x1000
	s_addc_u32 s3, s3, 0
	global_load_dwordx4 v[150:153], v243, s[2:3]
	s_waitcnt vmcnt(8)
	v_mul_f32_e32 v244, v37, v195
	v_mul_f32_e32 v245, v36, v195
	v_mul_f32_e32 v36, v36, v194
	v_fma_f32 v37, v37, v194, v245
	v_sub_f32_e32 v36, v36, v244
	v_mul_f32_e32 v244, v39, v197
	v_mul_f32_e32 v245, v38, v197
	v_fma_f32 v38, v38, v196, -v244
	v_fma_f32 v39, v39, v196, v245
	v_pk_mul_f32 v[36:37], v[36:37], s[6:7] op_sel_hi:[1,0]
	v_pk_mul_f32 v[38:39], v[38:39], s[6:7] op_sel_hi:[1,0]
	global_load_dwordx4 v[194:197], v243, s[2:3] offset:64
	s_waitcnt vmcnt(8)
	v_mul_f32_e32 v244, v33, v199
	v_mul_f32_e32 v245, v32, v199
	v_mul_f32_e32 v32, v32, v198
	v_fma_f32 v33, v33, v198, v245
	v_sub_f32_e32 v32, v32, v244
	v_mul_f32_e32 v244, v35, v201
	v_mul_f32_e32 v245, v34, v201
	v_fma_f32 v34, v34, v200, -v244
	v_fma_f32 v35, v35, v200, v245
	v_pk_mul_f32 v[32:33], v[32:33], s[6:7] op_sel_hi:[1,0]
	v_pk_mul_f32 v[34:35], v[34:35], s[6:7] op_sel_hi:[1,0]
	v_cvt_pk_bf16_f32 v44, v44, v45
	v_cvt_pk_bf16_f32 v45, v46, v47
	v_cvt_pk_bf16_f32 v46, v40, v41
	v_cvt_pk_bf16_f32 v47, v42, v43
	v_cvt_pk_bf16_f32 v36, v36, v37
	v_cvt_pk_bf16_f32 v37, v38, v39
	v_cvt_pk_bf16_f32 v38, v32, v33
	v_cvt_pk_bf16_f32 v39, v34, v35
	v_permlane16_swap_b32_e32 v44, v46
	v_permlane16_swap_b32_e32 v45, v47
	v_permlane16_swap_b32_e32 v36, v38
	v_permlane16_swap_b32_e32 v37, v39
	global_store_dwordx4 v242, v[44:47], s[98:99]
	global_store_dwordx4 v242, v[36:39], s[98:99] offset:64
	s_add_u32 s98, s98, s7
	s_addc_u32 s99, s99, 0
	global_load_dwordx4 v[198:201], v243, s[2:3] offset:128
	s_waitcnt vmcnt(10)
	v_mul_f32_e32 v244, v29, v203
	v_mul_f32_e32 v245, v28, v203
	v_mul_f32_e32 v28, v28, v202
	v_fma_f32 v29, v29, v202, v245
	v_sub_f32_e32 v28, v28, v244
	v_mul_f32_e32 v244, v31, v205
	v_mul_f32_e32 v245, v30, v205
	v_fma_f32 v30, v30, v204, -v244
	v_fma_f32 v31, v31, v204, v245
	v_pk_mul_f32 v[28:29], v[28:29], s[6:7] op_sel_hi:[1,0]
	v_pk_mul_f32 v[30:31], v[30:31], s[6:7] op_sel_hi:[1,0]
	global_load_dwordx4 v[202:205], v243, s[2:3] offset:192
	s_waitcnt vmcnt(10)
	v_mul_f32_e32 v244, v25, v143
	v_mul_f32_e32 v245, v24, v143
	v_mul_f32_e32 v24, v24, v142
	v_fma_f32 v25, v25, v142, v245
	v_sub_f32_e32 v24, v24, v244
	v_mul_f32_e32 v244, v27, v145
	v_mul_f32_e32 v245, v26, v145
	v_fma_f32 v26, v26, v144, -v244
	v_fma_f32 v27, v27, v144, v245
	v_pk_mul_f32 v[24:25], v[24:25], s[6:7] op_sel_hi:[1,0]
	v_pk_mul_f32 v[26:27], v[26:27], s[6:7] op_sel_hi:[1,0]
	s_waitcnt vmcnt(7)
	v_mul_f32_e32 v244, v21, v247
	v_mul_f32_e32 v245, v20, v247
	v_mul_f32_e32 v20, v20, v246
	v_fma_f32 v21, v21, v246, v245
	v_sub_f32_e32 v20, v20, v244
	v_mul_f32_e32 v244, v23, v249
	v_mul_f32_e32 v245, v22, v249
	v_fma_f32 v22, v22, v248, -v244
	v_fma_f32 v23, v23, v248, v245
	v_pk_mul_f32 v[20:21], v[20:21], s[6:7] op_sel_hi:[1,0]
	v_pk_mul_f32 v[22:23], v[22:23], s[6:7] op_sel_hi:[1,0]
	s_waitcnt vmcnt(6)
	v_mul_f32_e32 v244, v17, v251
	v_mul_f32_e32 v245, v16, v251
	v_mul_f32_e32 v16, v16, v250
	v_fma_f32 v17, v17, v250, v245
	v_sub_f32_e32 v16, v16, v244
	v_mul_f32_e32 v244, v19, v253
	v_mul_f32_e32 v245, v18, v253
	v_fma_f32 v18, v18, v252, -v244
	v_fma_f32 v19, v19, v252, v245
	v_pk_mul_f32 v[16:17], v[16:17], s[6:7] op_sel_hi:[1,0]
	v_pk_mul_f32 v[18:19], v[18:19], s[6:7] op_sel_hi:[1,0]
	v_cvt_pk_bf16_f32 v28, v28, v29
	v_cvt_pk_bf16_f32 v29, v30, v31
	v_cvt_pk_bf16_f32 v30, v24, v25
	v_cvt_pk_bf16_f32 v31, v26, v27
	v_cvt_pk_bf16_f32 v20, v20, v21
	v_cvt_pk_bf16_f32 v21, v22, v23
	v_cvt_pk_bf16_f32 v22, v16, v17
	v_cvt_pk_bf16_f32 v23, v18, v19
	v_permlane16_swap_b32_e32 v28, v30
	v_permlane16_swap_b32_e32 v29, v31
	v_permlane16_swap_b32_e32 v20, v22
	v_permlane16_swap_b32_e32 v21, v23
	global_store_dwordx4 v242, v[28:31], s[98:99]
	global_store_dwordx4 v242, v[20:23], s[98:99] offset:64
	s_add_u32 s98, s98, s7
	s_addc_u32 s99, s99, 0
	s_waitcnt vmcnt(7)
	v_mul_f32_e32 v244, v13, v151
	v_mul_f32_e32 v245, v12, v151
	v_mul_f32_e32 v12, v12, v150
	v_fma_f32 v13, v13, v150, v245
	v_sub_f32_e32 v12, v12, v244
	v_mul_f32_e32 v244, v15, v153
	v_mul_f32_e32 v245, v14, v153
	v_fma_f32 v14, v14, v152, -v244
	v_fma_f32 v15, v15, v152, v245
	v_pk_mul_f32 v[12:13], v[12:13], s[6:7] op_sel_hi:[1,0]
	v_pk_mul_f32 v[14:15], v[14:15], s[6:7] op_sel_hi:[1,0]
	s_waitcnt vmcnt(6)
	v_mul_f32_e32 v244, v9, v195
	v_mul_f32_e32 v245, v8, v195
	v_mul_f32_e32 v8, v8, v194
	v_fma_f32 v9, v9, v194, v245
	v_sub_f32_e32 v8, v8, v244
	v_mul_f32_e32 v244, v11, v197
	v_mul_f32_e32 v245, v10, v197
	v_fma_f32 v10, v10, v196, -v244
	v_fma_f32 v11, v11, v196, v245
	v_pk_mul_f32 v[8:9], v[8:9], s[6:7] op_sel_hi:[1,0]
	v_pk_mul_f32 v[10:11], v[10:11], s[6:7] op_sel_hi:[1,0]
	s_waitcnt vmcnt(3)
	v_mul_f32_e32 v244, v5, v199
	v_mul_f32_e32 v245, v4, v199
	v_mul_f32_e32 v4, v4, v198
	v_fma_f32 v5, v5, v198, v245
	v_sub_f32_e32 v4, v4, v244
	v_mul_f32_e32 v244, v7, v201
	v_mul_f32_e32 v245, v6, v201
	v_fma_f32 v6, v6, v200, -v244
	v_fma_f32 v7, v7, v200, v245
	v_pk_mul_f32 v[4:5], v[4:5], s[6:7] op_sel_hi:[1,0]
	v_pk_mul_f32 v[6:7], v[6:7], s[6:7] op_sel_hi:[1,0]
	s_waitcnt vmcnt(2)
	v_mul_f32_e32 v244, v1, v203
	v_mul_f32_e32 v245, v0, v203
	v_mul_f32_e32 v0, v0, v202
	v_fma_f32 v1, v1, v202, v245
	v_sub_f32_e32 v0, v0, v244
	v_mul_f32_e32 v244, v3, v205
	v_mul_f32_e32 v245, v2, v205
	v_fma_f32 v2, v2, v204, -v244
	v_fma_f32 v3, v3, v204, v245
	v_pk_mul_f32 v[0:1], v[0:1], s[6:7] op_sel_hi:[1,0]
	v_pk_mul_f32 v[2:3], v[2:3], s[6:7] op_sel_hi:[1,0]
	v_cvt_pk_bf16_f32 v12, v12, v13
	v_cvt_pk_bf16_f32 v13, v14, v15
	v_cvt_pk_bf16_f32 v14, v8, v9
	v_cvt_pk_bf16_f32 v15, v10, v11
	v_cvt_pk_bf16_f32 v4, v4, v5
	v_cvt_pk_bf16_f32 v5, v6, v7
	v_cvt_pk_bf16_f32 v6, v0, v1
	v_cvt_pk_bf16_f32 v7, v2, v3
	v_permlane16_swap_b32_e32 v12, v14
	v_permlane16_swap_b32_e32 v13, v15
	v_permlane16_swap_b32_e32 v4, v6
	v_permlane16_swap_b32_e32 v5, v7
	global_store_dwordx4 v242, v[12:15], s[98:99]
	global_store_dwordx4 v242, v[4:7], s[98:99] offset:64
	s_branch .LBB0_61
.Lepi2_k:
	s_cmpk_ge_u32 s16, 0x2000
	s_cbranch_scc1 .Lepi2_krope
	s_lshr_b32 s4, s16, 8
	s_lshl_b32 s4, s4, 1
	s_lshl_b32 s4, s4, 8
	s_sub_i32 s5, s101, s16
	s_add_i32 s4, s4, s5
	s_lshl_b32 s4, s4, 12
	s_sub_i32 s5, s58, 0x400
	s_add_i32 s5, s5, s100
	s_lshl_b32 vcc_lo, s5, 2
	s_add_u32 s4, s4, vcc_lo
	s_add_u32 s2, s92, s4
	s_addc_u32 s3, s93, 0
	s_lshl_b32 s5, s5, 1
	s_lshl_b32 vcc_lo, s101, 11
	s_add_u32 s5, s5, vcc_lo
	s_add_u32 s98, s20, s5
	s_addc_u32 s99, s21, 0
	v_and_b32_e32 v243, 15, v178
	v_bfe_u32 v244, v178, 4, 2
	v_lshlrev_b32_e32 v243, 12, v243
	v_lshl_add_u32 v243, v244, 4, v243
	global_store_dwordx4 v243, v[124:127], s[2:3]
	global_store_dwordx4 v243, v[120:123], s[2:3] offset:64
	global_store_dwordx4 v243, v[116:119], s[2:3] offset:128
	global_store_dwordx4 v243, v[112:115], s[2:3] offset:192
	s_add_u32 s2, s2, 0x10000
	s_addc_u32 s3, s3, 0
	v_cvt_pk_bf16_f32 v124, v124, v125
	v_cvt_pk_bf16_f32 v125, v126, v127
	v_cvt_pk_bf16_f32 v126, v120, v121
	v_cvt_pk_bf16_f32 v127, v122, v123
	v_cvt_pk_bf16_f32 v116, v116, v117
	v_cvt_pk_bf16_f32 v117, v118, v119
	v_cvt_pk_bf16_f32 v118, v112, v113
	v_cvt_pk_bf16_f32 v119, v114, v115
	v_permlane16_swap_b32_e32 v124, v126
	v_permlane16_swap_b32_e32 v125, v127
	v_permlane16_swap_b32_e32 v116, v118
	v_permlane16_swap_b32_e32 v117, v119
	global_store_dwordx4 v242, v[124:127], s[98:99]
	global_store_dwordx4 v242, v[116:119], s[98:99] offset:64
	s_add_u32 s98, s98, s7
	s_addc_u32 s99, s99, 0
	global_store_dwordx4 v243, v[108:111], s[2:3]
	global_store_dwordx4 v243, v[104:107], s[2:3] offset:64
	global_store_dwordx4 v243, v[100:103], s[2:3] offset:128
	global_store_dwordx4 v243, v[96:99], s[2:3] offset:192
	s_add_u32 s2, s2, 0x10000
	s_addc_u32 s3, s3, 0
	v_cvt_pk_bf16_f32 v108, v108, v109
	v_cvt_pk_bf16_f32 v109, v110, v111
	v_cvt_pk_bf16_f32 v110, v104, v105
	v_cvt_pk_bf16_f32 v111, v106, v107
	v_cvt_pk_bf16_f32 v100, v100, v101
	v_cvt_pk_bf16_f32 v101, v102, v103
	v_cvt_pk_bf16_f32 v102, v96, v97
	v_cvt_pk_bf16_f32 v103, v98, v99
	v_permlane16_swap_b32_e32 v108, v110
	v_permlane16_swap_b32_e32 v109, v111
	v_permlane16_swap_b32_e32 v100, v102
	v_permlane16_swap_b32_e32 v101, v103
	global_store_dwordx4 v242, v[108:111], s[98:99]
	global_store_dwordx4 v242, v[100:103], s[98:99] offset:64
	s_add_u32 s98, s98, s7
	s_addc_u32 s99, s99, 0
	global_store_dwordx4 v243, v[92:95], s[2:3]
	global_store_dwordx4 v243, v[88:91], s[2:3] offset:64
	global_store_dwordx4 v243, v[84:87], s[2:3] offset:128
	global_store_dwordx4 v243, v[80:83], s[2:3] offset:192
	s_add_u32 s2, s2, 0x10000
	s_addc_u32 s3, s3, 0
	v_cvt_pk_bf16_f32 v92, v92, v93
	v_cvt_pk_bf16_f32 v93, v94, v95
	v_cvt_pk_bf16_f32 v94, v88, v89
	v_cvt_pk_bf16_f32 v95, v90, v91
	v_cvt_pk_bf16_f32 v84, v84, v85
	v_cvt_pk_bf16_f32 v85, v86, v87
	v_cvt_pk_bf16_f32 v86, v80, v81
	v_cvt_pk_bf16_f32 v87, v82, v83
	v_permlane16_swap_b32_e32 v92, v94
	v_permlane16_swap_b32_e32 v93, v95
	v_permlane16_swap_b32_e32 v84, v86
	v_permlane16_swap_b32_e32 v85, v87
	global_store_dwordx4 v242, v[92:95], s[98:99]
	global_store_dwordx4 v242, v[84:87], s[98:99] offset:64
	s_add_u32 s98, s98, s7
	s_addc_u32 s99, s99, 0
	global_store_dwordx4 v243, v[76:79], s[2:3]
	global_store_dwordx4 v243, v[72:75], s[2:3] offset:64
	global_store_dwordx4 v243, v[68:71], s[2:3] offset:128
	global_store_dwordx4 v243, v[64:67], s[2:3] offset:192
	s_add_u32 s2, s2, 0x10000
	s_addc_u32 s3, s3, 0
	v_cvt_pk_bf16_f32 v76, v76, v77
	v_cvt_pk_bf16_f32 v77, v78, v79
	v_cvt_pk_bf16_f32 v78, v72, v73
	v_cvt_pk_bf16_f32 v79, v74, v75
	v_cvt_pk_bf16_f32 v68, v68, v69
	v_cvt_pk_bf16_f32 v69, v70, v71
	v_cvt_pk_bf16_f32 v70, v64, v65
	v_cvt_pk_bf16_f32 v71, v66, v67
	v_permlane16_swap_b32_e32 v76, v78
	v_permlane16_swap_b32_e32 v77, v79
	v_permlane16_swap_b32_e32 v68, v70
	v_permlane16_swap_b32_e32 v69, v71
	global_store_dwordx4 v242, v[76:79], s[98:99]
	global_store_dwordx4 v242, v[68:71], s[98:99] offset:64
	s_add_u32 s98, s98, s7
	s_addc_u32 s99, s99, 0
	global_store_dwordx4 v243, v[60:63], s[2:3]
	global_store_dwordx4 v243, v[56:59], s[2:3] offset:64
	global_store_dwordx4 v243, v[52:55], s[2:3] offset:128
	global_store_dwordx4 v243, v[48:51], s[2:3] offset:192
	s_add_u32 s2, s2, 0x10000
	s_addc_u32 s3, s3, 0
	v_cvt_pk_bf16_f32 v60, v60, v61
	v_cvt_pk_bf16_f32 v61, v62, v63
	v_cvt_pk_bf16_f32 v62, v56, v57
	v_cvt_pk_bf16_f32 v63, v58, v59
	v_cvt_pk_bf16_f32 v52, v52, v53
	v_cvt_pk_bf16_f32 v53, v54, v55
	v_cvt_pk_bf16_f32 v54, v48, v49
	v_cvt_pk_bf16_f32 v55, v50, v51
	v_permlane16_swap_b32_e32 v60, v62
	v_permlane16_swap_b32_e32 v61, v63
	v_permlane16_swap_b32_e32 v52, v54
	v_permlane16_swap_b32_e32 v53, v55
	global_store_dwordx4 v242, v[60:63], s[98:99]
	global_store_dwordx4 v242, v[52:55], s[98:99] offset:64
	s_add_u32 s98, s98, s7
	s_addc_u32 s99, s99, 0
	global_store_dwordx4 v243, v[44:47], s[2:3]
	global_store_dwordx4 v243, v[40:43], s[2:3] offset:64
	global_store_dwordx4 v243, v[36:39], s[2:3] offset:128
	global_store_dwordx4 v243, v[32:35], s[2:3] offset:192
	s_add_u32 s2, s2, 0x10000
	s_addc_u32 s3, s3, 0
	v_cvt_pk_bf16_f32 v44, v44, v45
	v_cvt_pk_bf16_f32 v45, v46, v47
	v_cvt_pk_bf16_f32 v46, v40, v41
	v_cvt_pk_bf16_f32 v47, v42, v43
	v_cvt_pk_bf16_f32 v36, v36, v37
	v_cvt_pk_bf16_f32 v37, v38, v39
	v_cvt_pk_bf16_f32 v38, v32, v33
	v_cvt_pk_bf16_f32 v39, v34, v35
	v_permlane16_swap_b32_e32 v44, v46
	v_permlane16_swap_b32_e32 v45, v47
	v_permlane16_swap_b32_e32 v36, v38
	v_permlane16_swap_b32_e32 v37, v39
	global_store_dwordx4 v242, v[44:47], s[98:99]
	global_store_dwordx4 v242, v[36:39], s[98:99] offset:64
	s_add_u32 s98, s98, s7
	s_addc_u32 s99, s99, 0
	global_store_dwordx4 v243, v[28:31], s[2:3]
	global_store_dwordx4 v243, v[24:27], s[2:3] offset:64
	global_store_dwordx4 v243, v[20:23], s[2:3] offset:128
	global_store_dwordx4 v243, v[16:19], s[2:3] offset:192
	s_add_u32 s2, s2, 0x10000
	s_addc_u32 s3, s3, 0
	v_cvt_pk_bf16_f32 v28, v28, v29
	v_cvt_pk_bf16_f32 v29, v30, v31
	v_cvt_pk_bf16_f32 v30, v24, v25
	v_cvt_pk_bf16_f32 v31, v26, v27
	v_cvt_pk_bf16_f32 v20, v20, v21
	v_cvt_pk_bf16_f32 v21, v22, v23
	v_cvt_pk_bf16_f32 v22, v16, v17
	v_cvt_pk_bf16_f32 v23, v18, v19
	v_permlane16_swap_b32_e32 v28, v30
	v_permlane16_swap_b32_e32 v29, v31
	v_permlane16_swap_b32_e32 v20, v22
	v_permlane16_swap_b32_e32 v21, v23
	global_store_dwordx4 v242, v[28:31], s[98:99]
	global_store_dwordx4 v242, v[20:23], s[98:99] offset:64
	s_add_u32 s98, s98, s7
	s_addc_u32 s99, s99, 0
	global_store_dwordx4 v243, v[12:15], s[2:3]
	global_store_dwordx4 v243, v[8:11], s[2:3] offset:64
	global_store_dwordx4 v243, v[4:7], s[2:3] offset:128
	global_store_dwordx4 v243, v[0:3], s[2:3] offset:192
	v_cvt_pk_bf16_f32 v12, v12, v13
	v_cvt_pk_bf16_f32 v13, v14, v15
	v_cvt_pk_bf16_f32 v14, v8, v9
	v_cvt_pk_bf16_f32 v15, v10, v11
	v_cvt_pk_bf16_f32 v4, v4, v5
	v_cvt_pk_bf16_f32 v5, v6, v7
	v_cvt_pk_bf16_f32 v6, v0, v1
	v_cvt_pk_bf16_f32 v7, v2, v3
	v_permlane16_swap_b32_e32 v12, v14
	v_permlane16_swap_b32_e32 v13, v15
	v_permlane16_swap_b32_e32 v4, v6
	v_permlane16_swap_b32_e32 v5, v7
	global_store_dwordx4 v242, v[12:15], s[98:99]
	global_store_dwordx4 v242, v[4:7], s[98:99] offset:64
	s_branch .LBB0_61
.Lepi2_krope:
	s_sub_i32 s3, s101, 0x2000
	s_sub_i32 s4, s16, 0x2000
	s_lshr_b32 s4, s4, 11
	s_lshl_b32 s5, s4, 9
	s_add_i32 s5, s5, s3
	s_lshl_b32 s5, s5, 11
	s_sub_i32 s4, s58, 0x400
	s_add_i32 s4, s4, s100
	s_lshl_b32 s4, s4, 1
	s_add_u32 s5, s5, s4
	s_add_u32 s98, s22, s5
	s_addc_u32 s99, s23, 0
	s_sub_i32 s3, s101, 0x2000
	s_and_b32 s3, s3, 0x7ff
	s_lshl_b32 s3, s3, 8
	s_add_u32 s2, s88, s3
	s_addc_u32 s3, s89, 0
	v_and_b32_e32 v243, 15, v178
	v_bfe_u32 v244, v178, 4, 2
	v_lshlrev_b32_e32 v243, 8, v243
	v_lshl_add_u32 v243, v244, 4, v243
	global_load_dwordx4 v[150:153], v243, s[2:3]
	global_load_dwordx4 v[194:197], v243, s[2:3] offset:64
	global_load_dwordx4 v[198:201], v243, s[2:3] offset:128
	global_load_dwordx4 v[202:205], v243, s[2:3] offset:192
	s_add_u32 s2, s2, 0x1000
	s_addc_u32 s3, s3, 0
	global_load_dwordx4 v[142:145], v243, s[2:3]
	global_load_dwordx4 v[246:249], v243, s[2:3] offset:64
	global_load_dwordx4 v[250:253], v243, s[2:3] offset:128
	s_waitcnt vmcnt(6)
	v_mul_f32_e32 v244, v125, v151
	v_mul_f32_e32 v245, v124, v151
	v_mul_f32_e32 v124, v124, v150
	v_fma_f32 v125, v125, v150, v245
	v_sub_f32_e32 v124, v124, v244
	v_mul_f32_e32 v244, v127, v153
	v_mul_f32_e32 v245, v126, v153
	v_fma_f32 v126, v126, v152, -v244
	v_fma_f32 v127, v127, v152, v245
	global_load_dwordx4 v[150:153], v243, s[2:3] offset:192
	s_waitcnt vmcnt(6)
	v_mul_f32_e32 v244, v121, v195
	v_mul_f32_e32 v245, v120, v195
	v_mul_f32_e32 v120, v120, v194
	v_fma_f32 v121, v121, v194, v245
	v_sub_f32_e32 v120, v120, v244
	v_mul_f32_e32 v244, v123, v197
	v_mul_f32_e32 v245, v122, v197
	v_fma_f32 v122, v122, v196, -v244
	v_fma_f32 v123, v123, v196, v245
	s_add_u32 s2, s2, 0x1000
	s_addc_u32 s3, s3, 0
	global_load_dwordx4 v[194:197], v243, s[2:3]
	s_waitcnt vmcnt(6)
	v_mul_f32_e32 v244, v117, v199
	v_mul_f32_e32 v245, v116, v199
	v_mul_f32_e32 v116, v116, v198
	v_fma_f32 v117, v117, v198, v245
	v_sub_f32_e32 v116, v116, v244
	v_mul_f32_e32 v244, v119, v201
	v_mul_f32_e32 v245, v118, v201
	v_fma_f32 v118, v118, v200, -v244
	v_fma_f32 v119, v119, v200, v245
	global_load_dwordx4 v[198:201], v243, s[2:3] offset:64
	s_waitcnt vmcnt(6)
	v_mul_f32_e32 v244, v113, v203
	v_mul_f32_e32 v245, v112, v203
	v_mul_f32_e32 v112, v112, v202
	v_fma_f32 v113, v113, v202, v245
	v_sub_f32_e32 v112, v112, v244
	v_mul_f32_e32 v244, v115, v205
	v_mul_f32_e32 v245, v114, v205
	v_fma_f32 v114, v114, v204, -v244
	v_fma_f32 v115, v115, v204, v245
	v_cvt_pk_bf16_f32 v124, v124, v125
	v_cvt_pk_bf16_f32 v125, v126, v127
	v_cvt_pk_bf16_f32 v126, v120, v121
	v_cvt_pk_bf16_f32 v127, v122, v123
	v_cvt_pk_bf16_f32 v116, v116, v117
	v_cvt_pk_bf16_f32 v117, v118, v119
	v_cvt_pk_bf16_f32 v118, v112, v113
	v_cvt_pk_bf16_f32 v119, v114, v115
	v_permlane16_swap_b32_e32 v124, v126
	v_permlane16_swap_b32_e32 v125, v127
	v_permlane16_swap_b32_e32 v116, v118
	v_permlane16_swap_b32_e32 v117, v119
	global_store_dwordx4 v242, v[124:127], s[98:99]
	global_store_dwordx4 v242, v[116:119], s[98:99] offset:64
	s_add_u32 s98, s98, s7
	s_addc_u32 s99, s99, 0
	global_load_dwordx4 v[202:205], v243, s[2:3] offset:128
	s_waitcnt vmcnt(8)
	v_mul_f32_e32 v244, v109, v143
	v_mul_f32_e32 v245, v108, v143
	v_mul_f32_e32 v108, v108, v142
	v_fma_f32 v109, v109, v142, v245
	v_sub_f32_e32 v108, v108, v244
	v_mul_f32_e32 v244, v111, v145
	v_mul_f32_e32 v245, v110, v145
	v_fma_f32 v110, v110, v144, -v244
	v_fma_f32 v111, v111, v144, v245
	global_load_dwordx4 v[142:145], v243, s[2:3] offset:192
	s_waitcnt vmcnt(8)
	v_mul_f32_e32 v244, v105, v247
	v_mul_f32_e32 v245, v104, v247
	v_mul_f32_e32 v104, v104, v246
	v_fma_f32 v105, v105, v246, v245
	v_sub_f32_e32 v104, v104, v244
	v_mul_f32_e32 v244, v107, v249
	v_mul_f32_e32 v245, v106, v249
	v_fma_f32 v106, v106, v248, -v244
	v_fma_f32 v107, v107, v248, v245
	s_add_u32 s2, s2, 0x1000
	s_addc_u32 s3, s3, 0
	global_load_dwordx4 v[246:249], v243, s[2:3]
	s_waitcnt vmcnt(8)
	v_mul_f32_e32 v244, v101, v251
	v_mul_f32_e32 v245, v100, v251
	v_mul_f32_e32 v100, v100, v250
	v_fma_f32 v101, v101, v250, v245
	v_sub_f32_e32 v100, v100, v244
	v_mul_f32_e32 v244, v103, v253
	v_mul_f32_e32 v245, v102, v253
	v_fma_f32 v102, v102, v252, -v244
	v_fma_f32 v103, v103, v252, v245
	global_load_dwordx4 v[250:253], v243, s[2:3] offset:64
	s_waitcnt vmcnt(8)
	v_mul_f32_e32 v244, v97, v151
	v_mul_f32_e32 v245, v96, v151
	v_mul_f32_e32 v96, v96, v150
	v_fma_f32 v97, v97, v150, v245
	v_sub_f32_e32 v96, v96, v244
	v_mul_f32_e32 v244, v99, v153
	v_mul_f32_e32 v245, v98, v153
	v_fma_f32 v98, v98, v152, -v244
	v_fma_f32 v99, v99, v152, v245
	v_cvt_pk_bf16_f32 v108, v108, v109
	v_cvt_pk_bf16_f32 v109, v110, v111
	v_cvt_pk_bf16_f32 v110, v104, v105
	v_cvt_pk_bf16_f32 v111, v106, v107
	v_cvt_pk_bf16_f32 v100, v100, v101
	v_cvt_pk_bf16_f32 v101, v102, v103
	v_cvt_pk_bf16_f32 v102, v96, v97
	v_cvt_pk_bf16_f32 v103, v98, v99
	v_permlane16_swap_b32_e32 v108, v110
	v_permlane16_swap_b32_e32 v109, v111
	v_permlane16_swap_b32_e32 v100, v102
	v_permlane16_swap_b32_e32 v101, v103
	global_store_dwordx4 v242, v[108:111], s[98:99]
	global_store_dwordx4 v242, v[100:103], s[98:99] offset:64
	s_add_u32 s98, s98, s7
	s_addc_u32 s99, s99, 0
	global_load_dwordx4 v[150:153], v243, s[2:3] offset:128
	s_waitcnt vmcnt(10)
	v_mul_f32_e32 v244, v93, v195
	v_mul_f32_e32 v245, v92, v195
	v_mul_f32_e32 v92, v92, v194
	v_fma_f32 v93, v93, v194, v245
	v_sub_f32_e32 v92, v92, v244
	v_mul_f32_e32 v244, v95, v197
	v_mul_f32_e32 v245, v94, v197
	v_fma_f32 v94, v94, v196, -v244
	v_fma_f32 v95, v95, v196, v245
	global_load_dwordx4 v[194:197], v243, s[2:3] offset:192
	s_waitcnt vmcnt(10)
	v_mul_f32_e32 v244, v89, v199
	v_mul_f32_e32 v245, v88, v199
	v_mul_f32_e32 v88, v88, v198
	v_fma_f32 v89, v89, v198, v245
	v_sub_f32_e32 v88, v88, v244
	v_mul_f32_e32 v244, v91, v201
	v_mul_f32_e32 v245, v90, v201
	v_fma_f32 v90, v90, v200, -v244
	v_fma_f32 v91, v91, v200, v245
	s_add_u32 s2, s2, 0x1000
	s_addc_u32 s3, s3, 0
	global_load_dwordx4 v[198:201], v243, s[2:3]
	s_waitcnt vmcnt(8)
	v_mul_f32_e32 v244, v85, v203
	v_mul_f32_e32 v245, v84, v203
	v_mul_f32_e32 v84, v84, v202
	v_fma_f32 v85, v85, v202, v245
	v_sub_f32_e32 v84, v84, v244
	v_mul_f32_e32 v244, v87, v205
	v_mul_f32_e32 v245, v86, v205
	v_fma_f32 v86, v86, v204, -v244
	v_fma_f32 v87, v87, v204, v245
	global_load_dwordx4 v[202:205], v243, s[2:3] offset:64
	s_waitcnt vmcnt(8)
	v_mul_f32_e32 v244, v81, v143
	v_mul_f32_e32 v245, v80, v143
	v_mul_f32_e32 v80, v80, v142
	v_fma_f32 v81, v81, v142, v245
	v_sub_f32_e32 v80, v80, v244
	v_mul_f32_e32 v244, v83, v145
	v_mul_f32_e32 v245, v82, v145
	v_fma_f32 v82, v82, v144, -v244
	v_fma_f32 v83, v83, v144, v245
	v_cvt_pk_bf16_f32 v92, v92, v93
	v_cvt_pk_bf16_f32 v93, v94, v95
	v_cvt_pk_bf16_f32 v94, v88, v89
	v_cvt_pk_bf16_f32 v95, v90, v91
	v_cvt_pk_bf16_f32 v84, v84, v85
	v_cvt_pk_bf16_f32 v85, v86, v87
	v_cvt_pk_bf16_f32 v86, v80, v81
	v_cvt_pk_bf16_f32 v87, v82, v83
	v_permlane16_swap_b32_e32 v92, v94
	v_permlane16_swap_b32_e32 v93, v95
	v_permlane16_swap_b32_e32 v84, v86
	v_permlane16_swap_b32_e32 v85, v87
	global_store_dwordx4 v242, v[92:95], s[98:99]
	global_store_dwordx4 v242, v[84:87], s[98:99] offset:64
	s_add_u32 s98, s98, s7
	s_addc_u32 s99, s99, 0
	global_load_dwordx4 v[142:145], v243, s[2:3] offset:128
	s_waitcnt vmcnt(10)
	v_mul_f32_e32 v244, v77, v247
	v_mul_f32_e32 v245, v76, v247
	v_mul_f32_e32 v76, v76, v246
	v_fma_f32 v77, v77, v246, v245
	v_sub_f32_e32 v76, v76, v244
	v_mul_f32_e32 v244, v79, v249
	v_mul_f32_e32 v245, v78, v249
	v_fma_f32 v78, v78, v248, -v244
	v_fma_f32 v79, v79, v248, v245
	global_load_dwordx4 v[246:249], v243, s[2:3] offset:192
	s_waitcnt vmcnt(10)
	v_mul_f32_e32 v244, v73, v251
	v_mul_f32_e32 v245, v72, v251
	v_mul_f32_e32 v72, v72, v250
	v_fma_f32 v73, v73, v250, v245
	v_sub_f32_e32 v72, v72, v244
	v_mul_f32_e32 v244, v75, v253
	v_mul_f32_e32 v245, v74, v253
	v_fma_f32 v74, v74, v252, -v244
	v_fma_f32 v75, v75, v252, v245
	s_add_u32 s2, s2, 0x1000
	s_addc_u32 s3, s3, 0
	global_load_dwordx4 v[250:253], v243, s[2:3]
	s_waitcnt vmcnt(8)
	v_mul_f32_e32 v244, v69, v151
	v_mul_f32_e32 v245, v68, v151
	v_mul_f32_e32 v68, v68, v150
	v_fma_f32 v69, v69, v150, v245
	v_sub_f32_e32 v68, v68, v244
	v_mul_f32_e32 v244, v71, v153
	v_mul_f32_e32 v245, v70, v153
	v_fma_f32 v70, v70, v152, -v244
	v_fma_f32 v71, v71, v152, v245
	global_load_dwordx4 v[150:153], v243, s[2:3] offset:64
	s_waitcnt vmcnt(8)
	v_mul_f32_e32 v244, v65, v195
	v_mul_f32_e32 v245, v64, v195
	v_mul_f32_e32 v64, v64, v194
	v_fma_f32 v65, v65, v194, v245
	v_sub_f32_e32 v64, v64, v244
	v_mul_f32_e32 v244, v67, v197
	v_mul_f32_e32 v245, v66, v197
	v_fma_f32 v66, v66, v196, -v244
	v_fma_f32 v67, v67, v196, v245
	v_cvt_pk_bf16_f32 v76, v76, v77
	v_cvt_pk_bf16_f32 v77, v78, v79
	v_cvt_pk_bf16_f32 v78, v72, v73
	v_cvt_pk_bf16_f32 v79, v74, v75
	v_cvt_pk_bf16_f32 v68, v68, v69
	v_cvt_pk_bf16_f32 v69, v70, v71
	v_cvt_pk_bf16_f32 v70, v64, v65
	v_cvt_pk_bf16_f32 v71, v66, v67
	v_permlane16_swap_b32_e32 v76, v78
	v_permlane16_swap_b32_e32 v77, v79
	v_permlane16_swap_b32_e32 v68, v70
	v_permlane16_swap_b32_e32 v69, v71
	global_store_dwordx4 v242, v[76:79], s[98:99]
	global_store_dwordx4 v242, v[68:71], s[98:99] offset:64
	s_add_u32 s98, s98, s7
	s_addc_u32 s99, s99, 0
	global_load_dwordx4 v[194:197], v243, s[2:3] offset:128
	s_waitcnt vmcnt(10)
	v_mul_f32_e32 v244, v61, v199
	v_mul_f32_e32 v245, v60, v199
	v_mul_f32_e32 v60, v60, v198
	v_fma_f32 v61, v61, v198, v245
	v_sub_f32_e32 v60, v60, v244
	v_mul_f32_e32 v244, v63, v201
	v_mul_f32_e32 v245, v62, v201
	v_fma_f32 v62, v62, v200, -v244
	v_fma_f32 v63, v63, v200, v245
	global_load_dwordx4 v[198:201], v243, s[2:3] offset:192
	s_waitcnt vmcnt(10)
	v_mul_f32_e32 v244, v57, v203
	v_mul_f32_e32 v245, v56, v203
	v_mul_f32_e32 v56, v56, v202
	v_fma_f32 v57, v57, v202, v245
	v_sub_f32_e32 v56, v56, v244
	v_mul_f32_e32 v244, v59, v205
	v_mul_f32_e32 v245, v58, v205
	v_fma_f32 v58, v58, v204, -v244
	v_fma_f32 v59, v59, v204, v245
	s_add_u32 s2, s2, 0x1000
	s_addc_u32 s3, s3, 0
	global_load_dwordx4 v[202:205], v243, s[2:3]
	s_waitcnt vmcnt(8)
	v_mul_f32_e32 v244, v53, v143
	v_mul_f32_e32 v245, v52, v143
	v_mul_f32_e32 v52, v52, v142
	v_fma_f32 v53, v53, v142, v245
	v_sub_f32_e32 v52, v52, v244
	v_mul_f32_e32 v244, v55, v145
	v_mul_f32_e32 v245, v54, v145
	v_fma_f32 v54, v54, v144, -v244
	v_fma_f32 v55, v55, v144, v245
	global_load_dwordx4 v[142:145], v243, s[2:3] offset:64
	s_waitcnt vmcnt(8)
	v_mul_f32_e32 v244, v49, v247
	v_mul_f32_e32 v245, v48, v247
	v_mul_f32_e32 v48, v48, v246
	v_fma_f32 v49, v49, v246, v245
	v_sub_f32_e32 v48, v48, v244
	v_mul_f32_e32 v244, v51, v249
	v_mul_f32_e32 v245, v50, v249
	v_fma_f32 v50, v50, v248, -v244
	v_fma_f32 v51, v51, v248, v245
	v_cvt_pk_bf16_f32 v60, v60, v61
	v_cvt_pk_bf16_f32 v61, v62, v63
	v_cvt_pk_bf16_f32 v62, v56, v57
	v_cvt_pk_bf16_f32 v63, v58, v59
	v_cvt_pk_bf16_f32 v52, v52, v53
	v_cvt_pk_bf16_f32 v53, v54, v55
	v_cvt_pk_bf16_f32 v54, v48, v49
	v_cvt_pk_bf16_f32 v55, v50, v51
	v_permlane16_swap_b32_e32 v60, v62
	v_permlane16_swap_b32_e32 v61, v63
	v_permlane16_swap_b32_e32 v52, v54
	v_permlane16_swap_b32_e32 v53, v55
	global_store_dwordx4 v242, v[60:63], s[98:99]
	global_store_dwordx4 v242, v[52:55], s[98:99] offset:64
	s_add_u32 s98, s98, s7
	s_addc_u32 s99, s99, 0
	global_load_dwordx4 v[246:249], v243, s[2:3] offset:128
	s_waitcnt vmcnt(10)
	v_mul_f32_e32 v244, v45, v251
	v_mul_f32_e32 v245, v44, v251
	v_mul_f32_e32 v44, v44, v250
	v_fma_f32 v45, v45, v250, v245
	v_sub_f32_e32 v44, v44, v244
	v_mul_f32_e32 v244, v47, v253
	v_mul_f32_e32 v245, v46, v253
	v_fma_f32 v46, v46, v252, -v244
	v_fma_f32 v47, v47, v252, v245
	global_load_dwordx4 v[250:253], v243, s[2:3] offset:192
	s_waitcnt vmcnt(10)
	v_mul_f32_e32 v244, v41, v151
	v_mul_f32_e32 v245, v40, v151
	v_mul_f32_e32 v40, v40, v150
	v_fma_f32 v41, v41, v150, v245
	v_sub_f32_e32 v40, v40, v244
	v_mul_f32_e32 v244, v43, v153
	v_mul_f32_e32 v245, v42, v153
	v_fma_f32 v42, v42, v152, -v244
	v_fma_f32 v43, v43, v152, v245
	s_add_u32 s2, s2, 0x1000
	s_addc_u32 s3, s3, 0
	global_load_dwordx4 v[150:153], v243, s[2:3]
	s_waitcnt vmcnt(8)
	v_mul_f32_e32 v244, v37, v195
	v_mul_f32_e32 v245, v36, v195
	v_mul_f32_e32 v36, v36, v194
	v_fma_f32 v37, v37, v194, v245
	v_sub_f32_e32 v36, v36, v244
	v_mul_f32_e32 v244, v39, v197
	v_mul_f32_e32 v245, v38, v197
	v_fma_f32 v38, v38, v196, -v244
	v_fma_f32 v39, v39, v196, v245
	global_load_dwordx4 v[194:197], v243, s[2:3] offset:64
	s_waitcnt vmcnt(8)
	v_mul_f32_e32 v244, v33, v199
	v_mul_f32_e32 v245, v32, v199
	v_mul_f32_e32 v32, v32, v198
	v_fma_f32 v33, v33, v198, v245
	v_sub_f32_e32 v32, v32, v244
	v_mul_f32_e32 v244, v35, v201
	v_mul_f32_e32 v245, v34, v201
	v_fma_f32 v34, v34, v200, -v244
	v_fma_f32 v35, v35, v200, v245
	v_cvt_pk_bf16_f32 v44, v44, v45
	v_cvt_pk_bf16_f32 v45, v46, v47
	v_cvt_pk_bf16_f32 v46, v40, v41
	v_cvt_pk_bf16_f32 v47, v42, v43
	v_cvt_pk_bf16_f32 v36, v36, v37
	v_cvt_pk_bf16_f32 v37, v38, v39
	v_cvt_pk_bf16_f32 v38, v32, v33
	v_cvt_pk_bf16_f32 v39, v34, v35
	v_permlane16_swap_b32_e32 v44, v46
	v_permlane16_swap_b32_e32 v45, v47
	v_permlane16_swap_b32_e32 v36, v38
	v_permlane16_swap_b32_e32 v37, v39
	global_store_dwordx4 v242, v[44:47], s[98:99]
	global_store_dwordx4 v242, v[36:39], s[98:99] offset:64
	s_add_u32 s98, s98, s7
	s_addc_u32 s99, s99, 0
	global_load_dwordx4 v[198:201], v243, s[2:3] offset:128
	s_waitcnt vmcnt(10)
	v_mul_f32_e32 v244, v29, v203
	v_mul_f32_e32 v245, v28, v203
	v_mul_f32_e32 v28, v28, v202
	v_fma_f32 v29, v29, v202, v245
	v_sub_f32_e32 v28, v28, v244
	v_mul_f32_e32 v244, v31, v205
	v_mul_f32_e32 v245, v30, v205
	v_fma_f32 v30, v30, v204, -v244
	v_fma_f32 v31, v31, v204, v245
	global_load_dwordx4 v[202:205], v243, s[2:3] offset:192
	s_waitcnt vmcnt(10)
	v_mul_f32_e32 v244, v25, v143
	v_mul_f32_e32 v245, v24, v143
	v_mul_f32_e32 v24, v24, v142
	v_fma_f32 v25, v25, v142, v245
	v_sub_f32_e32 v24, v24, v244
	v_mul_f32_e32 v244, v27, v145
	v_mul_f32_e32 v245, v26, v145
	v_fma_f32 v26, v26, v144, -v244
	v_fma_f32 v27, v27, v144, v245
	s_waitcnt vmcnt(7)
	v_mul_f32_e32 v244, v21, v247
	v_mul_f32_e32 v245, v20, v247
	v_mul_f32_e32 v20, v20, v246
	v_fma_f32 v21, v21, v246, v245
	v_sub_f32_e32 v20, v20, v244
	v_mul_f32_e32 v244, v23, v249
	v_mul_f32_e32 v245, v22, v249
	v_fma_f32 v22, v22, v248, -v244
	v_fma_f32 v23, v23, v248, v245
	s_waitcnt vmcnt(6)
	v_mul_f32_e32 v244, v17, v251
	v_mul_f32_e32 v245, v16, v251
	v_mul_f32_e32 v16, v16, v250
	v_fma_f32 v17, v17, v250, v245
	v_sub_f32_e32 v16, v16, v244
	v_mul_f32_e32 v244, v19, v253
	v_mul_f32_e32 v245, v18, v253
	v_fma_f32 v18, v18, v252, -v244
	v_fma_f32 v19, v19, v252, v245
	v_cvt_pk_bf16_f32 v28, v28, v29
	v_cvt_pk_bf16_f32 v29, v30, v31
	v_cvt_pk_bf16_f32 v30, v24, v25
	v_cvt_pk_bf16_f32 v31, v26, v27
	v_cvt_pk_bf16_f32 v20, v20, v21
	v_cvt_pk_bf16_f32 v21, v22, v23
	v_cvt_pk_bf16_f32 v22, v16, v17
	v_cvt_pk_bf16_f32 v23, v18, v19
	v_permlane16_swap_b32_e32 v28, v30
	v_permlane16_swap_b32_e32 v29, v31
	v_permlane16_swap_b32_e32 v20, v22
	v_permlane16_swap_b32_e32 v21, v23
	global_store_dwordx4 v242, v[28:31], s[98:99]
	global_store_dwordx4 v242, v[20:23], s[98:99] offset:64
	s_add_u32 s98, s98, s7
	s_addc_u32 s99, s99, 0
	s_waitcnt vmcnt(7)
	v_mul_f32_e32 v244, v13, v151
	v_mul_f32_e32 v245, v12, v151
	v_mul_f32_e32 v12, v12, v150
	v_fma_f32 v13, v13, v150, v245
	v_sub_f32_e32 v12, v12, v244
	v_mul_f32_e32 v244, v15, v153
	v_mul_f32_e32 v245, v14, v153
	v_fma_f32 v14, v14, v152, -v244
	v_fma_f32 v15, v15, v152, v245
	s_waitcnt vmcnt(6)
	v_mul_f32_e32 v244, v9, v195
	v_mul_f32_e32 v245, v8, v195
	v_mul_f32_e32 v8, v8, v194
	v_fma_f32 v9, v9, v194, v245
	v_sub_f32_e32 v8, v8, v244
	v_mul_f32_e32 v244, v11, v197
	v_mul_f32_e32 v245, v10, v197
	v_fma_f32 v10, v10, v196, -v244
	v_fma_f32 v11, v11, v196, v245
	s_waitcnt vmcnt(3)
	v_mul_f32_e32 v244, v5, v199
	v_mul_f32_e32 v245, v4, v199
	v_mul_f32_e32 v4, v4, v198
	v_fma_f32 v5, v5, v198, v245
	v_sub_f32_e32 v4, v4, v244
	v_mul_f32_e32 v244, v7, v201
	v_mul_f32_e32 v245, v6, v201
	v_fma_f32 v6, v6, v200, -v244
	v_fma_f32 v7, v7, v200, v245
	s_waitcnt vmcnt(2)
	v_mul_f32_e32 v244, v1, v203
	v_mul_f32_e32 v245, v0, v203
	v_mul_f32_e32 v0, v0, v202
	v_fma_f32 v1, v1, v202, v245
	v_sub_f32_e32 v0, v0, v244
	v_mul_f32_e32 v244, v3, v205
	v_mul_f32_e32 v245, v2, v205
	v_fma_f32 v2, v2, v204, -v244
	v_fma_f32 v3, v3, v204, v245
	v_cvt_pk_bf16_f32 v12, v12, v13
	v_cvt_pk_bf16_f32 v13, v14, v15
	v_cvt_pk_bf16_f32 v14, v8, v9
	v_cvt_pk_bf16_f32 v15, v10, v11
	v_cvt_pk_bf16_f32 v4, v4, v5
	v_cvt_pk_bf16_f32 v5, v6, v7
	v_cvt_pk_bf16_f32 v6, v0, v1
	v_cvt_pk_bf16_f32 v7, v2, v3
	v_permlane16_swap_b32_e32 v12, v14
	v_permlane16_swap_b32_e32 v13, v15
	v_permlane16_swap_b32_e32 v4, v6
	v_permlane16_swap_b32_e32 v5, v7
	global_store_dwordx4 v242, v[12:15], s[98:99]
	global_store_dwordx4 v242, v[4:7], s[98:99] offset:64
	s_branch .LBB0_61
.Lepi2_gate:
	s_sub_i32 s3, s58, 0xc00
	s_add_i32 s3, s3, s100
	s_lshl_b32 s3, s3, 1
	s_lshl_b32 s5, s101, 11
	s_add_u32 s3, s3, s5
	s_add_u32 s3, s3, 0xa000000
	s_add_u32 s98, s68, s3
	s_addc_u32 s99, s69, 0
	v_mul_f32_e32 v246, 0xbfb8aa3b, v124
	v_mul_f32_e32 v247, 0xbfb8aa3b, v125
	v_mul_f32_e32 v248, 0xbfb8aa3b, v126
	v_mul_f32_e32 v249, 0xbfb8aa3b, v127
	v_exp_f32_e32 v246, v246
	v_exp_f32_e32 v247, v247
	v_exp_f32_e32 v248, v248
	v_exp_f32_e32 v249, v249
	v_add_f32_e32 v246, 1.0, v246
	v_add_f32_e32 v247, 1.0, v247
	v_add_f32_e32 v248, 1.0, v248
	v_add_f32_e32 v249, 1.0, v249
	v_rcp_f32_e32 v246, v246
	v_rcp_f32_e32 v247, v247
	v_rcp_f32_e32 v248, v248
	v_rcp_f32_e32 v249, v249
	v_mul_f32_e32 v124, v124, v246
	v_mul_f32_e32 v125, v125, v247
	v_mul_f32_e32 v126, v126, v248
	v_mul_f32_e32 v127, v127, v249
	v_mul_f32_e32 v250, 0xbfb8aa3b, v120
	v_mul_f32_e32 v251, 0xbfb8aa3b, v121
	v_mul_f32_e32 v252, 0xbfb8aa3b, v122
	v_mul_f32_e32 v253, 0xbfb8aa3b, v123
	v_exp_f32_e32 v250, v250
	v_exp_f32_e32 v251, v251
	v_exp_f32_e32 v252, v252
	v_exp_f32_e32 v253, v253
	v_add_f32_e32 v250, 1.0, v250
	v_add_f32_e32 v251, 1.0, v251
	v_add_f32_e32 v252, 1.0, v252
	v_add_f32_e32 v253, 1.0, v253
	v_rcp_f32_e32 v250, v250
	v_rcp_f32_e32 v251, v251
	v_rcp_f32_e32 v252, v252
	v_rcp_f32_e32 v253, v253
	v_mul_f32_e32 v120, v120, v250
	v_mul_f32_e32 v121, v121, v251
	v_mul_f32_e32 v122, v122, v252
	v_mul_f32_e32 v123, v123, v253
	v_mul_f32_e32 v246, 0xbfb8aa3b, v116
	v_mul_f32_e32 v247, 0xbfb8aa3b, v117
	v_mul_f32_e32 v248, 0xbfb8aa3b, v118
	v_mul_f32_e32 v249, 0xbfb8aa3b, v119
	v_exp_f32_e32 v246, v246
	v_exp_f32_e32 v247, v247
	v_exp_f32_e32 v248, v248
	v_exp_f32_e32 v249, v249
	v_add_f32_e32 v246, 1.0, v246
	v_add_f32_e32 v247, 1.0, v247
	v_add_f32_e32 v248, 1.0, v248
	v_add_f32_e32 v249, 1.0, v249
	v_rcp_f32_e32 v246, v246
	v_rcp_f32_e32 v247, v247
	v_rcp_f32_e32 v248, v248
	v_rcp_f32_e32 v249, v249
	v_mul_f32_e32 v116, v116, v246
	v_mul_f32_e32 v117, v117, v247
	v_mul_f32_e32 v118, v118, v248
	v_mul_f32_e32 v119, v119, v249
	v_mul_f32_e32 v250, 0xbfb8aa3b, v112
	v_mul_f32_e32 v251, 0xbfb8aa3b, v113
	v_mul_f32_e32 v252, 0xbfb8aa3b, v114
	v_mul_f32_e32 v253, 0xbfb8aa3b, v115
	v_exp_f32_e32 v250, v250
	v_exp_f32_e32 v251, v251
	v_exp_f32_e32 v252, v252
	v_exp_f32_e32 v253, v253
	v_add_f32_e32 v250, 1.0, v250
	v_add_f32_e32 v251, 1.0, v251
	v_add_f32_e32 v252, 1.0, v252
	v_add_f32_e32 v253, 1.0, v253
	v_rcp_f32_e32 v250, v250
	v_rcp_f32_e32 v251, v251
	v_rcp_f32_e32 v252, v252
	v_rcp_f32_e32 v253, v253
	v_mul_f32_e32 v112, v112, v250
	v_mul_f32_e32 v113, v113, v251
	v_mul_f32_e32 v114, v114, v252
	v_mul_f32_e32 v115, v115, v253
	v_cvt_pk_bf16_f32 v124, v124, v125
	v_cvt_pk_bf16_f32 v125, v126, v127
	v_cvt_pk_bf16_f32 v126, v120, v121
	v_cvt_pk_bf16_f32 v127, v122, v123
	v_cvt_pk_bf16_f32 v116, v116, v117
	v_cvt_pk_bf16_f32 v117, v118, v119
	v_cvt_pk_bf16_f32 v118, v112, v113
	v_cvt_pk_bf16_f32 v119, v114, v115
	v_permlane16_swap_b32_e32 v124, v126
	v_permlane16_swap_b32_e32 v125, v127
	v_permlane16_swap_b32_e32 v116, v118
	v_permlane16_swap_b32_e32 v117, v119
	global_store_dwordx4 v242, v[124:127], s[98:99]
	global_store_dwordx4 v242, v[116:119], s[98:99] offset:64
	s_add_u32 s98, s98, s7
	s_addc_u32 s99, s99, 0
	v_mul_f32_e32 v246, 0xbfb8aa3b, v108
	v_mul_f32_e32 v247, 0xbfb8aa3b, v109
	v_mul_f32_e32 v248, 0xbfb8aa3b, v110
	v_mul_f32_e32 v249, 0xbfb8aa3b, v111
	v_exp_f32_e32 v246, v246
	v_exp_f32_e32 v247, v247
	v_exp_f32_e32 v248, v248
	v_exp_f32_e32 v249, v249
	v_add_f32_e32 v246, 1.0, v246
	v_add_f32_e32 v247, 1.0, v247
	v_add_f32_e32 v248, 1.0, v248
	v_add_f32_e32 v249, 1.0, v249
	v_rcp_f32_e32 v246, v246
	v_rcp_f32_e32 v247, v247
	v_rcp_f32_e32 v248, v248
	v_rcp_f32_e32 v249, v249
	v_mul_f32_e32 v108, v108, v246
	v_mul_f32_e32 v109, v109, v247
	v_mul_f32_e32 v110, v110, v248
	v_mul_f32_e32 v111, v111, v249
	v_mul_f32_e32 v250, 0xbfb8aa3b, v104
	v_mul_f32_e32 v251, 0xbfb8aa3b, v105
	v_mul_f32_e32 v252, 0xbfb8aa3b, v106
	v_mul_f32_e32 v253, 0xbfb8aa3b, v107
	v_exp_f32_e32 v250, v250
	v_exp_f32_e32 v251, v251
	v_exp_f32_e32 v252, v252
	v_exp_f32_e32 v253, v253
	v_add_f32_e32 v250, 1.0, v250
	v_add_f32_e32 v251, 1.0, v251
	v_add_f32_e32 v252, 1.0, v252
	v_add_f32_e32 v253, 1.0, v253
	v_rcp_f32_e32 v250, v250
	v_rcp_f32_e32 v251, v251
	v_rcp_f32_e32 v252, v252
	v_rcp_f32_e32 v253, v253
	v_mul_f32_e32 v104, v104, v250
	v_mul_f32_e32 v105, v105, v251
	v_mul_f32_e32 v106, v106, v252
	v_mul_f32_e32 v107, v107, v253
	v_mul_f32_e32 v246, 0xbfb8aa3b, v100
	v_mul_f32_e32 v247, 0xbfb8aa3b, v101
	v_mul_f32_e32 v248, 0xbfb8aa3b, v102
	v_mul_f32_e32 v249, 0xbfb8aa3b, v103
	v_exp_f32_e32 v246, v246
	v_exp_f32_e32 v247, v247
	v_exp_f32_e32 v248, v248
	v_exp_f32_e32 v249, v249
	v_add_f32_e32 v246, 1.0, v246
	v_add_f32_e32 v247, 1.0, v247
	v_add_f32_e32 v248, 1.0, v248
	v_add_f32_e32 v249, 1.0, v249
	v_rcp_f32_e32 v246, v246
	v_rcp_f32_e32 v247, v247
	v_rcp_f32_e32 v248, v248
	v_rcp_f32_e32 v249, v249
	v_mul_f32_e32 v100, v100, v246
	v_mul_f32_e32 v101, v101, v247
	v_mul_f32_e32 v102, v102, v248
	v_mul_f32_e32 v103, v103, v249
	v_mul_f32_e32 v250, 0xbfb8aa3b, v96
	v_mul_f32_e32 v251, 0xbfb8aa3b, v97
	v_mul_f32_e32 v252, 0xbfb8aa3b, v98
	v_mul_f32_e32 v253, 0xbfb8aa3b, v99
	v_exp_f32_e32 v250, v250
	v_exp_f32_e32 v251, v251
	v_exp_f32_e32 v252, v252
	v_exp_f32_e32 v253, v253
	v_add_f32_e32 v250, 1.0, v250
	v_add_f32_e32 v251, 1.0, v251
	v_add_f32_e32 v252, 1.0, v252
	v_add_f32_e32 v253, 1.0, v253
	v_rcp_f32_e32 v250, v250
	v_rcp_f32_e32 v251, v251
	v_rcp_f32_e32 v252, v252
	v_rcp_f32_e32 v253, v253
	v_mul_f32_e32 v96, v96, v250
	v_mul_f32_e32 v97, v97, v251
	v_mul_f32_e32 v98, v98, v252
	v_mul_f32_e32 v99, v99, v253
	v_cvt_pk_bf16_f32 v108, v108, v109
	v_cvt_pk_bf16_f32 v109, v110, v111
	v_cvt_pk_bf16_f32 v110, v104, v105
	v_cvt_pk_bf16_f32 v111, v106, v107
	v_cvt_pk_bf16_f32 v100, v100, v101
	v_cvt_pk_bf16_f32 v101, v102, v103
	v_cvt_pk_bf16_f32 v102, v96, v97
	v_cvt_pk_bf16_f32 v103, v98, v99
	v_permlane16_swap_b32_e32 v108, v110
	v_permlane16_swap_b32_e32 v109, v111
	v_permlane16_swap_b32_e32 v100, v102
	v_permlane16_swap_b32_e32 v101, v103
	global_store_dwordx4 v242, v[108:111], s[98:99]
	global_store_dwordx4 v242, v[100:103], s[98:99] offset:64
	s_add_u32 s98, s98, s7
	s_addc_u32 s99, s99, 0
	v_mul_f32_e32 v246, 0xbfb8aa3b, v92
	v_mul_f32_e32 v247, 0xbfb8aa3b, v93
	v_mul_f32_e32 v248, 0xbfb8aa3b, v94
	v_mul_f32_e32 v249, 0xbfb8aa3b, v95
	v_exp_f32_e32 v246, v246
	v_exp_f32_e32 v247, v247
	v_exp_f32_e32 v248, v248
	v_exp_f32_e32 v249, v249
	v_add_f32_e32 v246, 1.0, v246
	v_add_f32_e32 v247, 1.0, v247
	v_add_f32_e32 v248, 1.0, v248
	v_add_f32_e32 v249, 1.0, v249
	v_rcp_f32_e32 v246, v246
	v_rcp_f32_e32 v247, v247
	v_rcp_f32_e32 v248, v248
	v_rcp_f32_e32 v249, v249
	v_mul_f32_e32 v92, v92, v246
	v_mul_f32_e32 v93, v93, v247
	v_mul_f32_e32 v94, v94, v248
	v_mul_f32_e32 v95, v95, v249
	v_mul_f32_e32 v250, 0xbfb8aa3b, v88
	v_mul_f32_e32 v251, 0xbfb8aa3b, v89
	v_mul_f32_e32 v252, 0xbfb8aa3b, v90
	v_mul_f32_e32 v253, 0xbfb8aa3b, v91
	v_exp_f32_e32 v250, v250
	v_exp_f32_e32 v251, v251
	v_exp_f32_e32 v252, v252
	v_exp_f32_e32 v253, v253
	v_add_f32_e32 v250, 1.0, v250
	v_add_f32_e32 v251, 1.0, v251
	v_add_f32_e32 v252, 1.0, v252
	v_add_f32_e32 v253, 1.0, v253
	v_rcp_f32_e32 v250, v250
	v_rcp_f32_e32 v251, v251
	v_rcp_f32_e32 v252, v252
	v_rcp_f32_e32 v253, v253
	v_mul_f32_e32 v88, v88, v250
	v_mul_f32_e32 v89, v89, v251
	v_mul_f32_e32 v90, v90, v252
	v_mul_f32_e32 v91, v91, v253
	v_mul_f32_e32 v246, 0xbfb8aa3b, v84
	v_mul_f32_e32 v247, 0xbfb8aa3b, v85
	v_mul_f32_e32 v248, 0xbfb8aa3b, v86
	v_mul_f32_e32 v249, 0xbfb8aa3b, v87
	v_exp_f32_e32 v246, v246
	v_exp_f32_e32 v247, v247
	v_exp_f32_e32 v248, v248
	v_exp_f32_e32 v249, v249
	v_add_f32_e32 v246, 1.0, v246
	v_add_f32_e32 v247, 1.0, v247
	v_add_f32_e32 v248, 1.0, v248
	v_add_f32_e32 v249, 1.0, v249
	v_rcp_f32_e32 v246, v246
	v_rcp_f32_e32 v247, v247
	v_rcp_f32_e32 v248, v248
	v_rcp_f32_e32 v249, v249
	v_mul_f32_e32 v84, v84, v246
	v_mul_f32_e32 v85, v85, v247
	v_mul_f32_e32 v86, v86, v248
	v_mul_f32_e32 v87, v87, v249
	v_mul_f32_e32 v250, 0xbfb8aa3b, v80
	v_mul_f32_e32 v251, 0xbfb8aa3b, v81
	v_mul_f32_e32 v252, 0xbfb8aa3b, v82
	v_mul_f32_e32 v253, 0xbfb8aa3b, v83
	v_exp_f32_e32 v250, v250
	v_exp_f32_e32 v251, v251
	v_exp_f32_e32 v252, v252
	v_exp_f32_e32 v253, v253
	v_add_f32_e32 v250, 1.0, v250
	v_add_f32_e32 v251, 1.0, v251
	v_add_f32_e32 v252, 1.0, v252
	v_add_f32_e32 v253, 1.0, v253
	v_rcp_f32_e32 v250, v250
	v_rcp_f32_e32 v251, v251
	v_rcp_f32_e32 v252, v252
	v_rcp_f32_e32 v253, v253
	v_mul_f32_e32 v80, v80, v250
	v_mul_f32_e32 v81, v81, v251
	v_mul_f32_e32 v82, v82, v252
	v_mul_f32_e32 v83, v83, v253
	v_cvt_pk_bf16_f32 v92, v92, v93
	v_cvt_pk_bf16_f32 v93, v94, v95
	v_cvt_pk_bf16_f32 v94, v88, v89
	v_cvt_pk_bf16_f32 v95, v90, v91
	v_cvt_pk_bf16_f32 v84, v84, v85
	v_cvt_pk_bf16_f32 v85, v86, v87
	v_cvt_pk_bf16_f32 v86, v80, v81
	v_cvt_pk_bf16_f32 v87, v82, v83
	v_permlane16_swap_b32_e32 v92, v94
	v_permlane16_swap_b32_e32 v93, v95
	v_permlane16_swap_b32_e32 v84, v86
	v_permlane16_swap_b32_e32 v85, v87
	global_store_dwordx4 v242, v[92:95], s[98:99]
	global_store_dwordx4 v242, v[84:87], s[98:99] offset:64
	s_add_u32 s98, s98, s7
	s_addc_u32 s99, s99, 0
	v_mul_f32_e32 v246, 0xbfb8aa3b, v76
	v_mul_f32_e32 v247, 0xbfb8aa3b, v77
	v_mul_f32_e32 v248, 0xbfb8aa3b, v78
	v_mul_f32_e32 v249, 0xbfb8aa3b, v79
	v_exp_f32_e32 v246, v246
	v_exp_f32_e32 v247, v247
	v_exp_f32_e32 v248, v248
	v_exp_f32_e32 v249, v249
	v_add_f32_e32 v246, 1.0, v246
	v_add_f32_e32 v247, 1.0, v247
	v_add_f32_e32 v248, 1.0, v248
	v_add_f32_e32 v249, 1.0, v249
	v_rcp_f32_e32 v246, v246
	v_rcp_f32_e32 v247, v247
	v_rcp_f32_e32 v248, v248
	v_rcp_f32_e32 v249, v249
	v_mul_f32_e32 v76, v76, v246
	v_mul_f32_e32 v77, v77, v247
	v_mul_f32_e32 v78, v78, v248
	v_mul_f32_e32 v79, v79, v249
	v_mul_f32_e32 v250, 0xbfb8aa3b, v72
	v_mul_f32_e32 v251, 0xbfb8aa3b, v73
	v_mul_f32_e32 v252, 0xbfb8aa3b, v74
	v_mul_f32_e32 v253, 0xbfb8aa3b, v75
	v_exp_f32_e32 v250, v250
	v_exp_f32_e32 v251, v251
	v_exp_f32_e32 v252, v252
	v_exp_f32_e32 v253, v253
	v_add_f32_e32 v250, 1.0, v250
	v_add_f32_e32 v251, 1.0, v251
	v_add_f32_e32 v252, 1.0, v252
	v_add_f32_e32 v253, 1.0, v253
	v_rcp_f32_e32 v250, v250
	v_rcp_f32_e32 v251, v251
	v_rcp_f32_e32 v252, v252
	v_rcp_f32_e32 v253, v253
	v_mul_f32_e32 v72, v72, v250
	v_mul_f32_e32 v73, v73, v251
	v_mul_f32_e32 v74, v74, v252
	v_mul_f32_e32 v75, v75, v253
	v_mul_f32_e32 v246, 0xbfb8aa3b, v68
	v_mul_f32_e32 v247, 0xbfb8aa3b, v69
	v_mul_f32_e32 v248, 0xbfb8aa3b, v70
	v_mul_f32_e32 v249, 0xbfb8aa3b, v71
	v_exp_f32_e32 v246, v246
	v_exp_f32_e32 v247, v247
	v_exp_f32_e32 v248, v248
	v_exp_f32_e32 v249, v249
	v_add_f32_e32 v246, 1.0, v246
	v_add_f32_e32 v247, 1.0, v247
	v_add_f32_e32 v248, 1.0, v248
	v_add_f32_e32 v249, 1.0, v249
	v_rcp_f32_e32 v246, v246
	v_rcp_f32_e32 v247, v247
	v_rcp_f32_e32 v248, v248
	v_rcp_f32_e32 v249, v249
	v_mul_f32_e32 v68, v68, v246
	v_mul_f32_e32 v69, v69, v247
	v_mul_f32_e32 v70, v70, v248
	v_mul_f32_e32 v71, v71, v249
	v_mul_f32_e32 v250, 0xbfb8aa3b, v64
	v_mul_f32_e32 v251, 0xbfb8aa3b, v65
	v_mul_f32_e32 v252, 0xbfb8aa3b, v66
	v_mul_f32_e32 v253, 0xbfb8aa3b, v67
	v_exp_f32_e32 v250, v250
	v_exp_f32_e32 v251, v251
	v_exp_f32_e32 v252, v252
	v_exp_f32_e32 v253, v253
	v_add_f32_e32 v250, 1.0, v250
	v_add_f32_e32 v251, 1.0, v251
	v_add_f32_e32 v252, 1.0, v252
	v_add_f32_e32 v253, 1.0, v253
	v_rcp_f32_e32 v250, v250
	v_rcp_f32_e32 v251, v251
	v_rcp_f32_e32 v252, v252
	v_rcp_f32_e32 v253, v253
	v_mul_f32_e32 v64, v64, v250
	v_mul_f32_e32 v65, v65, v251
	v_mul_f32_e32 v66, v66, v252
	v_mul_f32_e32 v67, v67, v253
	v_cvt_pk_bf16_f32 v76, v76, v77
	v_cvt_pk_bf16_f32 v77, v78, v79
	v_cvt_pk_bf16_f32 v78, v72, v73
	v_cvt_pk_bf16_f32 v79, v74, v75
	v_cvt_pk_bf16_f32 v68, v68, v69
	v_cvt_pk_bf16_f32 v69, v70, v71
	v_cvt_pk_bf16_f32 v70, v64, v65
	v_cvt_pk_bf16_f32 v71, v66, v67
	v_permlane16_swap_b32_e32 v76, v78
	v_permlane16_swap_b32_e32 v77, v79
	v_permlane16_swap_b32_e32 v68, v70
	v_permlane16_swap_b32_e32 v69, v71
	global_store_dwordx4 v242, v[76:79], s[98:99]
	global_store_dwordx4 v242, v[68:71], s[98:99] offset:64
	s_add_u32 s98, s98, s7
	s_addc_u32 s99, s99, 0
	v_mul_f32_e32 v246, 0xbfb8aa3b, v60
	v_mul_f32_e32 v247, 0xbfb8aa3b, v61
	v_mul_f32_e32 v248, 0xbfb8aa3b, v62
	v_mul_f32_e32 v249, 0xbfb8aa3b, v63
	v_exp_f32_e32 v246, v246
	v_exp_f32_e32 v247, v247
	v_exp_f32_e32 v248, v248
	v_exp_f32_e32 v249, v249
	v_add_f32_e32 v246, 1.0, v246
	v_add_f32_e32 v247, 1.0, v247
	v_add_f32_e32 v248, 1.0, v248
	v_add_f32_e32 v249, 1.0, v249
	v_rcp_f32_e32 v246, v246
	v_rcp_f32_e32 v247, v247
	v_rcp_f32_e32 v248, v248
	v_rcp_f32_e32 v249, v249
	v_mul_f32_e32 v60, v60, v246
	v_mul_f32_e32 v61, v61, v247
	v_mul_f32_e32 v62, v62, v248
	v_mul_f32_e32 v63, v63, v249
	v_mul_f32_e32 v250, 0xbfb8aa3b, v56
	v_mul_f32_e32 v251, 0xbfb8aa3b, v57
	v_mul_f32_e32 v252, 0xbfb8aa3b, v58
	v_mul_f32_e32 v253, 0xbfb8aa3b, v59
	v_exp_f32_e32 v250, v250
	v_exp_f32_e32 v251, v251
	v_exp_f32_e32 v252, v252
	v_exp_f32_e32 v253, v253
	v_add_f32_e32 v250, 1.0, v250
	v_add_f32_e32 v251, 1.0, v251
	v_add_f32_e32 v252, 1.0, v252
	v_add_f32_e32 v253, 1.0, v253
	v_rcp_f32_e32 v250, v250
	v_rcp_f32_e32 v251, v251
	v_rcp_f32_e32 v252, v252
	v_rcp_f32_e32 v253, v253
	v_mul_f32_e32 v56, v56, v250
	v_mul_f32_e32 v57, v57, v251
	v_mul_f32_e32 v58, v58, v252
	v_mul_f32_e32 v59, v59, v253
	v_mul_f32_e32 v246, 0xbfb8aa3b, v52
	v_mul_f32_e32 v247, 0xbfb8aa3b, v53
	v_mul_f32_e32 v248, 0xbfb8aa3b, v54
	v_mul_f32_e32 v249, 0xbfb8aa3b, v55
	v_exp_f32_e32 v246, v246
	v_exp_f32_e32 v247, v247
	v_exp_f32_e32 v248, v248
	v_exp_f32_e32 v249, v249
	v_add_f32_e32 v246, 1.0, v246
	v_add_f32_e32 v247, 1.0, v247
	v_add_f32_e32 v248, 1.0, v248
	v_add_f32_e32 v249, 1.0, v249
	v_rcp_f32_e32 v246, v246
	v_rcp_f32_e32 v247, v247
	v_rcp_f32_e32 v248, v248
	v_rcp_f32_e32 v249, v249
	v_mul_f32_e32 v52, v52, v246
	v_mul_f32_e32 v53, v53, v247
	v_mul_f32_e32 v54, v54, v248
	v_mul_f32_e32 v55, v55, v249
	v_mul_f32_e32 v250, 0xbfb8aa3b, v48
	v_mul_f32_e32 v251, 0xbfb8aa3b, v49
	v_mul_f32_e32 v252, 0xbfb8aa3b, v50
	v_mul_f32_e32 v253, 0xbfb8aa3b, v51
	v_exp_f32_e32 v250, v250
	v_exp_f32_e32 v251, v251
	v_exp_f32_e32 v252, v252
	v_exp_f32_e32 v253, v253
	v_add_f32_e32 v250, 1.0, v250
	v_add_f32_e32 v251, 1.0, v251
	v_add_f32_e32 v252, 1.0, v252
	v_add_f32_e32 v253, 1.0, v253
	v_rcp_f32_e32 v250, v250
	v_rcp_f32_e32 v251, v251
	v_rcp_f32_e32 v252, v252
	v_rcp_f32_e32 v253, v253
	v_mul_f32_e32 v48, v48, v250
	v_mul_f32_e32 v49, v49, v251
	v_mul_f32_e32 v50, v50, v252
	v_mul_f32_e32 v51, v51, v253
	v_cvt_pk_bf16_f32 v60, v60, v61
	v_cvt_pk_bf16_f32 v61, v62, v63
	v_cvt_pk_bf16_f32 v62, v56, v57
	v_cvt_pk_bf16_f32 v63, v58, v59
	v_cvt_pk_bf16_f32 v52, v52, v53
	v_cvt_pk_bf16_f32 v53, v54, v55
	v_cvt_pk_bf16_f32 v54, v48, v49
	v_cvt_pk_bf16_f32 v55, v50, v51
	v_permlane16_swap_b32_e32 v60, v62
	v_permlane16_swap_b32_e32 v61, v63
	v_permlane16_swap_b32_e32 v52, v54
	v_permlane16_swap_b32_e32 v53, v55
	global_store_dwordx4 v242, v[60:63], s[98:99]
	global_store_dwordx4 v242, v[52:55], s[98:99] offset:64
	s_add_u32 s98, s98, s7
	s_addc_u32 s99, s99, 0
	v_mul_f32_e32 v246, 0xbfb8aa3b, v44
	v_mul_f32_e32 v247, 0xbfb8aa3b, v45
	v_mul_f32_e32 v248, 0xbfb8aa3b, v46
	v_mul_f32_e32 v249, 0xbfb8aa3b, v47
	v_exp_f32_e32 v246, v246
	v_exp_f32_e32 v247, v247
	v_exp_f32_e32 v248, v248
	v_exp_f32_e32 v249, v249
	v_add_f32_e32 v246, 1.0, v246
	v_add_f32_e32 v247, 1.0, v247
	v_add_f32_e32 v248, 1.0, v248
	v_add_f32_e32 v249, 1.0, v249
	v_rcp_f32_e32 v246, v246
	v_rcp_f32_e32 v247, v247
	v_rcp_f32_e32 v248, v248
	v_rcp_f32_e32 v249, v249
	v_mul_f32_e32 v44, v44, v246
	v_mul_f32_e32 v45, v45, v247
	v_mul_f32_e32 v46, v46, v248
	v_mul_f32_e32 v47, v47, v249
	v_mul_f32_e32 v250, 0xbfb8aa3b, v40
	v_mul_f32_e32 v251, 0xbfb8aa3b, v41
	v_mul_f32_e32 v252, 0xbfb8aa3b, v42
	v_mul_f32_e32 v253, 0xbfb8aa3b, v43
	v_exp_f32_e32 v250, v250
	v_exp_f32_e32 v251, v251
	v_exp_f32_e32 v252, v252
	v_exp_f32_e32 v253, v253
	v_add_f32_e32 v250, 1.0, v250
	v_add_f32_e32 v251, 1.0, v251
	v_add_f32_e32 v252, 1.0, v252
	v_add_f32_e32 v253, 1.0, v253
	v_rcp_f32_e32 v250, v250
	v_rcp_f32_e32 v251, v251
	v_rcp_f32_e32 v252, v252
	v_rcp_f32_e32 v253, v253
	v_mul_f32_e32 v40, v40, v250
	v_mul_f32_e32 v41, v41, v251
	v_mul_f32_e32 v42, v42, v252
	v_mul_f32_e32 v43, v43, v253
	v_mul_f32_e32 v246, 0xbfb8aa3b, v36
	v_mul_f32_e32 v247, 0xbfb8aa3b, v37
	v_mul_f32_e32 v248, 0xbfb8aa3b, v38
	v_mul_f32_e32 v249, 0xbfb8aa3b, v39
	v_exp_f32_e32 v246, v246
	v_exp_f32_e32 v247, v247
	v_exp_f32_e32 v248, v248
	v_exp_f32_e32 v249, v249
	v_add_f32_e32 v246, 1.0, v246
	v_add_f32_e32 v247, 1.0, v247
	v_add_f32_e32 v248, 1.0, v248
	v_add_f32_e32 v249, 1.0, v249
	v_rcp_f32_e32 v246, v246
	v_rcp_f32_e32 v247, v247
	v_rcp_f32_e32 v248, v248
	v_rcp_f32_e32 v249, v249
	v_mul_f32_e32 v36, v36, v246
	v_mul_f32_e32 v37, v37, v247
	v_mul_f32_e32 v38, v38, v248
	v_mul_f32_e32 v39, v39, v249
	v_mul_f32_e32 v250, 0xbfb8aa3b, v32
	v_mul_f32_e32 v251, 0xbfb8aa3b, v33
	v_mul_f32_e32 v252, 0xbfb8aa3b, v34
	v_mul_f32_e32 v253, 0xbfb8aa3b, v35
	v_exp_f32_e32 v250, v250
	v_exp_f32_e32 v251, v251
	v_exp_f32_e32 v252, v252
	v_exp_f32_e32 v253, v253
	v_add_f32_e32 v250, 1.0, v250
	v_add_f32_e32 v251, 1.0, v251
	v_add_f32_e32 v252, 1.0, v252
	v_add_f32_e32 v253, 1.0, v253
	v_rcp_f32_e32 v250, v250
	v_rcp_f32_e32 v251, v251
	v_rcp_f32_e32 v252, v252
	v_rcp_f32_e32 v253, v253
	v_mul_f32_e32 v32, v32, v250
	v_mul_f32_e32 v33, v33, v251
	v_mul_f32_e32 v34, v34, v252
	v_mul_f32_e32 v35, v35, v253
	v_cvt_pk_bf16_f32 v44, v44, v45
	v_cvt_pk_bf16_f32 v45, v46, v47
	v_cvt_pk_bf16_f32 v46, v40, v41
	v_cvt_pk_bf16_f32 v47, v42, v43
	v_cvt_pk_bf16_f32 v36, v36, v37
	v_cvt_pk_bf16_f32 v37, v38, v39
	v_cvt_pk_bf16_f32 v38, v32, v33
	v_cvt_pk_bf16_f32 v39, v34, v35
	v_permlane16_swap_b32_e32 v44, v46
	v_permlane16_swap_b32_e32 v45, v47
	v_permlane16_swap_b32_e32 v36, v38
	v_permlane16_swap_b32_e32 v37, v39
	global_store_dwordx4 v242, v[44:47], s[98:99]
	global_store_dwordx4 v242, v[36:39], s[98:99] offset:64
	s_add_u32 s98, s98, s7
	s_addc_u32 s99, s99, 0
	v_mul_f32_e32 v246, 0xbfb8aa3b, v28
	v_mul_f32_e32 v247, 0xbfb8aa3b, v29
	v_mul_f32_e32 v248, 0xbfb8aa3b, v30
	v_mul_f32_e32 v249, 0xbfb8aa3b, v31
	v_exp_f32_e32 v246, v246
	v_exp_f32_e32 v247, v247
	v_exp_f32_e32 v248, v248
	v_exp_f32_e32 v249, v249
	v_add_f32_e32 v246, 1.0, v246
	v_add_f32_e32 v247, 1.0, v247
	v_add_f32_e32 v248, 1.0, v248
	v_add_f32_e32 v249, 1.0, v249
	v_rcp_f32_e32 v246, v246
	v_rcp_f32_e32 v247, v247
	v_rcp_f32_e32 v248, v248
	v_rcp_f32_e32 v249, v249
	v_mul_f32_e32 v28, v28, v246
	v_mul_f32_e32 v29, v29, v247
	v_mul_f32_e32 v30, v30, v248
	v_mul_f32_e32 v31, v31, v249
	v_mul_f32_e32 v250, 0xbfb8aa3b, v24
	v_mul_f32_e32 v251, 0xbfb8aa3b, v25
	v_mul_f32_e32 v252, 0xbfb8aa3b, v26
	v_mul_f32_e32 v253, 0xbfb8aa3b, v27
	v_exp_f32_e32 v250, v250
	v_exp_f32_e32 v251, v251
	v_exp_f32_e32 v252, v252
	v_exp_f32_e32 v253, v253
	v_add_f32_e32 v250, 1.0, v250
	v_add_f32_e32 v251, 1.0, v251
	v_add_f32_e32 v252, 1.0, v252
	v_add_f32_e32 v253, 1.0, v253
	v_rcp_f32_e32 v250, v250
	v_rcp_f32_e32 v251, v251
	v_rcp_f32_e32 v252, v252
	v_rcp_f32_e32 v253, v253
	v_mul_f32_e32 v24, v24, v250
	v_mul_f32_e32 v25, v25, v251
	v_mul_f32_e32 v26, v26, v252
	v_mul_f32_e32 v27, v27, v253
	v_mul_f32_e32 v246, 0xbfb8aa3b, v20
	v_mul_f32_e32 v247, 0xbfb8aa3b, v21
	v_mul_f32_e32 v248, 0xbfb8aa3b, v22
	v_mul_f32_e32 v249, 0xbfb8aa3b, v23
	v_exp_f32_e32 v246, v246
	v_exp_f32_e32 v247, v247
	v_exp_f32_e32 v248, v248
	v_exp_f32_e32 v249, v249
	v_add_f32_e32 v246, 1.0, v246
	v_add_f32_e32 v247, 1.0, v247
	v_add_f32_e32 v248, 1.0, v248
	v_add_f32_e32 v249, 1.0, v249
	v_rcp_f32_e32 v246, v246
	v_rcp_f32_e32 v247, v247
	v_rcp_f32_e32 v248, v248
	v_rcp_f32_e32 v249, v249
	v_mul_f32_e32 v20, v20, v246
	v_mul_f32_e32 v21, v21, v247
	v_mul_f32_e32 v22, v22, v248
	v_mul_f32_e32 v23, v23, v249
	v_mul_f32_e32 v250, 0xbfb8aa3b, v16
	v_mul_f32_e32 v251, 0xbfb8aa3b, v17
	v_mul_f32_e32 v252, 0xbfb8aa3b, v18
	v_mul_f32_e32 v253, 0xbfb8aa3b, v19
	v_exp_f32_e32 v250, v250
	v_exp_f32_e32 v251, v251
	v_exp_f32_e32 v252, v252
	v_exp_f32_e32 v253, v253
	v_add_f32_e32 v250, 1.0, v250
	v_add_f32_e32 v251, 1.0, v251
	v_add_f32_e32 v252, 1.0, v252
	v_add_f32_e32 v253, 1.0, v253
	v_rcp_f32_e32 v250, v250
	v_rcp_f32_e32 v251, v251
	v_rcp_f32_e32 v252, v252
	v_rcp_f32_e32 v253, v253
	v_mul_f32_e32 v16, v16, v250
	v_mul_f32_e32 v17, v17, v251
	v_mul_f32_e32 v18, v18, v252
	v_mul_f32_e32 v19, v19, v253
	v_cvt_pk_bf16_f32 v28, v28, v29
	v_cvt_pk_bf16_f32 v29, v30, v31
	v_cvt_pk_bf16_f32 v30, v24, v25
	v_cvt_pk_bf16_f32 v31, v26, v27
	v_cvt_pk_bf16_f32 v20, v20, v21
	v_cvt_pk_bf16_f32 v21, v22, v23
	v_cvt_pk_bf16_f32 v22, v16, v17
	v_cvt_pk_bf16_f32 v23, v18, v19
	v_permlane16_swap_b32_e32 v28, v30
	v_permlane16_swap_b32_e32 v29, v31
	v_permlane16_swap_b32_e32 v20, v22
	v_permlane16_swap_b32_e32 v21, v23
	global_store_dwordx4 v242, v[28:31], s[98:99]
	global_store_dwordx4 v242, v[20:23], s[98:99] offset:64
	s_add_u32 s98, s98, s7
	s_addc_u32 s99, s99, 0
	v_mul_f32_e32 v246, 0xbfb8aa3b, v12
	v_mul_f32_e32 v247, 0xbfb8aa3b, v13
	v_mul_f32_e32 v248, 0xbfb8aa3b, v14
	v_mul_f32_e32 v249, 0xbfb8aa3b, v15
	v_exp_f32_e32 v246, v246
	v_exp_f32_e32 v247, v247
	v_exp_f32_e32 v248, v248
	v_exp_f32_e32 v249, v249
	v_add_f32_e32 v246, 1.0, v246
	v_add_f32_e32 v247, 1.0, v247
	v_add_f32_e32 v248, 1.0, v248
	v_add_f32_e32 v249, 1.0, v249
	v_rcp_f32_e32 v246, v246
	v_rcp_f32_e32 v247, v247
	v_rcp_f32_e32 v248, v248
	v_rcp_f32_e32 v249, v249
	v_mul_f32_e32 v12, v12, v246
	v_mul_f32_e32 v13, v13, v247
	v_mul_f32_e32 v14, v14, v248
	v_mul_f32_e32 v15, v15, v249
	v_mul_f32_e32 v250, 0xbfb8aa3b, v8
	v_mul_f32_e32 v251, 0xbfb8aa3b, v9
	v_mul_f32_e32 v252, 0xbfb8aa3b, v10
	v_mul_f32_e32 v253, 0xbfb8aa3b, v11
	v_exp_f32_e32 v250, v250
	v_exp_f32_e32 v251, v251
	v_exp_f32_e32 v252, v252
	v_exp_f32_e32 v253, v253
	v_add_f32_e32 v250, 1.0, v250
	v_add_f32_e32 v251, 1.0, v251
	v_add_f32_e32 v252, 1.0, v252
	v_add_f32_e32 v253, 1.0, v253
	v_rcp_f32_e32 v250, v250
	v_rcp_f32_e32 v251, v251
	v_rcp_f32_e32 v252, v252
	v_rcp_f32_e32 v253, v253
	v_mul_f32_e32 v8, v8, v250
	v_mul_f32_e32 v9, v9, v251
	v_mul_f32_e32 v10, v10, v252
	v_mul_f32_e32 v11, v11, v253
	v_mul_f32_e32 v246, 0xbfb8aa3b, v4
	v_mul_f32_e32 v247, 0xbfb8aa3b, v5
	v_mul_f32_e32 v248, 0xbfb8aa3b, v6
	v_mul_f32_e32 v249, 0xbfb8aa3b, v7
	v_exp_f32_e32 v246, v246
	v_exp_f32_e32 v247, v247
	v_exp_f32_e32 v248, v248
	v_exp_f32_e32 v249, v249
	v_add_f32_e32 v246, 1.0, v246
	v_add_f32_e32 v247, 1.0, v247
	v_add_f32_e32 v248, 1.0, v248
	v_add_f32_e32 v249, 1.0, v249
	v_rcp_f32_e32 v246, v246
	v_rcp_f32_e32 v247, v247
	v_rcp_f32_e32 v248, v248
	v_rcp_f32_e32 v249, v249
	v_mul_f32_e32 v4, v4, v246
	v_mul_f32_e32 v5, v5, v247
	v_mul_f32_e32 v6, v6, v248
	v_mul_f32_e32 v7, v7, v249
	v_mul_f32_e32 v250, 0xbfb8aa3b, v0
	v_mul_f32_e32 v251, 0xbfb8aa3b, v1
	v_mul_f32_e32 v252, 0xbfb8aa3b, v2
	v_mul_f32_e32 v253, 0xbfb8aa3b, v3
	v_exp_f32_e32 v250, v250
	v_exp_f32_e32 v251, v251
	v_exp_f32_e32 v252, v252
	v_exp_f32_e32 v253, v253
	v_add_f32_e32 v250, 1.0, v250
	v_add_f32_e32 v251, 1.0, v251
	v_add_f32_e32 v252, 1.0, v252
	v_add_f32_e32 v253, 1.0, v253
	v_rcp_f32_e32 v250, v250
	v_rcp_f32_e32 v251, v251
	v_rcp_f32_e32 v252, v252
	v_rcp_f32_e32 v253, v253
	v_mul_f32_e32 v0, v0, v250
	v_mul_f32_e32 v1, v1, v251
	v_mul_f32_e32 v2, v2, v252
	v_mul_f32_e32 v3, v3, v253
	v_cvt_pk_bf16_f32 v12, v12, v13
	v_cvt_pk_bf16_f32 v13, v14, v15
	v_cvt_pk_bf16_f32 v14, v8, v9
	v_cvt_pk_bf16_f32 v15, v10, v11
	v_cvt_pk_bf16_f32 v4, v4, v5
	v_cvt_pk_bf16_f32 v5, v6, v7
	v_cvt_pk_bf16_f32 v6, v0, v1
	v_cvt_pk_bf16_f32 v7, v2, v3
	v_permlane16_swap_b32_e32 v12, v14
	v_permlane16_swap_b32_e32 v13, v15
	v_permlane16_swap_b32_e32 v4, v6
	v_permlane16_swap_b32_e32 v5, v7
	global_store_dwordx4 v242, v[12:15], s[98:99]
	global_store_dwordx4 v242, v[4:7], s[98:99] offset:64
	s_branch .LBB0_61

.LBB0_1228:
	s_cmp_gt_i32 s70, 13
	s_cselect_b64 s[0:1], -1, 0
	s_cmp_lt_i32 s71, 14
	s_cselect_b64 s[2:3], -1, 0
	s_or_b64 s[0:1], s[0:1], s[2:3]
	s_and_b64 vcc, exec, s[0:1]
	s_cbranch_vccnz .LBB0_1450
	v_readlane_b32 s6, v241, 0
	s_and_b32 s33, s6, 7
	s_lshl_b32 s1, s33, 2
	s_sub_i32 s1, 0x10c, s1
	s_and_b32 s0, s78, 7
	s_lshr_b32 s4, s6, 3
	s_and_b32 s5, s1, 0x1e0
	s_cmp_eq_u32 s0, 0
	s_cselect_b64 s[0:1], -1, 0
	s_and_b64 s[2:3], s[0:1], exec
	s_cselect_b32 s54, s4, s6
	s_cselect_b32 s55, s5, 0x780
	s_cmp_ge_i32 s54, s55
	s_mov_b32 s11, 0
	s_cbranch_scc1 .LBB0_1435
	s_add_u32 s56, s68, 0x13000000
	v_lshrrev_b32_e32 v3, 4, v178
	v_bfe_u32 v0, v178, 4, 2
	s_waitcnt lgkmcnt(0)
	v_and_b32_e32 v2, 7, v178
	s_addc_u32 s57, s69, 0
	v_bitop3_b32 v4, v3, v2, 3 bitop3:0x6c
	v_bitop3_b32 v2, v0, v2, 4 bitop3:0x36
	v_lshlrev_b32_e32 v0, 7, v178
	s_add_u32 s58, s94, 0x12000000
	v_and_b32_e32 v5, 0x1c00, v0
	s_addc_u32 s59, s95, 0
	v_lshl_or_b32 v0, v4, 3, v5
	v_bfe_u32 v4, v178, 1, 3
	s_add_u32 s60, s68, 0x12000000
	v_bitop3_b32 v3, v3, v4, 3 bitop3:0x6c
	s_addc_u32 s61, s69, 0
	s_ashr_i32 s4, s78, 3
	v_and_b32_e32 v1, 0xc0, v178
	v_lshl_or_b32 v2, v2, 3, v5
	s_waitcnt vmcnt(0)
	v_mov_b32_e32 v129, 0
	v_lshlrev_b32_e32 v151, 4, v3
	v_lshrrev_b32_e32 v3, 2, v178
	v_and_b32_e32 v150, 15, v178
	s_and_b64 s[2:3], s[0:1], exec
	v_and_or_b32 v153, v3, 12, v1
	v_lshlrev_b32_e32 v130, 1, v0
	v_mov_b32_e32 v131, v129
	v_lshlrev_b32_e32 v134, 1, v2
	v_mov_b32_e32 v135, v129
	v_cndmask_b32_e64 v1, 0, 1, s[0:1]
	s_cselect_b32 s62, s4, s78
	v_xor_b32_e32 v152, 64, v151
	v_lshl_or_b32 v154, v180, 7, v150
	v_lshl_add_u64 v[132:133], s[68:69], 0, v[130:131]
	v_lshl_add_u64 v[136:137], s[68:69], 0, v[134:135]
	s_mov_b64 s[8:9], 0
	v_cmp_ne_u32_e64 s[0:1], 1, v1
	s_mov_b64 s[12:13], 0x4000
	s_mov_b64 s[14:15], 0x8000
	s_mov_b64 s[16:17], 0xc000
	s_mov_b64 s[18:19], 0x80
	s_mov_b64 s[20:21], 0x12000080
	s_mov_b64 s[22:23], 0x4080
	s_mov_b64 s[24:25], 0x12004080
	s_mov_b64 s[26:27], 0x8080
	s_mov_b64 s[28:29], 0x12008080
	s_mov_b64 s[30:31], 0xc080
	s_mov_b64 s[34:35], 0x1200c080
	s_movk_i32 s63, 0xf3ff
	s_movk_i32 s64, 0x3dc
	s_movk_i32 s65, 0x3ec
	s_movk_i32 s66, 0x3fc
	v_lshlrev_b32_e32 v138, 1, v0
	v_lshlrev_b32_e32 v140, 1, v2
	s_branch .LBB0_1232
.LBB0_1232:
	s_and_b64 vcc, exec, s[0:1]
	s_mov_b32 s2, s54
	s_cbranch_vccnz .LBB0_1234
	s_ashr_i32 s2, s54, 2
	s_and_b32 s2, s2, -8
	s_or_b32 s2, s2, s33
	s_mul_hi_i32 s3, s2, 0x66666667
	s_lshr_b32 s4, s3, 31
	s_ashr_i32 s3, s3, 1
	s_add_i32 s3, s3, s4
	s_mul_i32 s4, s3, -5
	s_add_i32 s4, s4, s2
	s_lshl_b32 s2, s3, 3
	s_bfe_u32 s3, s54, 0x30002
	s_or_b32 s2, s2, s3
	s_lshl_b32 s3, s4, 2
	s_and_b32 s4, s54, 3
	s_mul_i32 s2, s2, 20
	s_or_b32 s3, s3, s4
	s_add_i32 s2, s3, s2

.LBB0_1246:
	v_readfirstlane_b32 s100, v178
	s_nop 0
	s_lshr_b32 s100, s100, 6
	s_lshr_b32 s101, s100, 2
	s_and_b32 s100, s100, 3
	s_lshl_b32 s101, s101, 7
	s_add_i32 s101, s101, s67
	s_lshl_b32 s100, s100, 6
	s_lshr_b32 s4, s38, 10
	s_and_b32 s3, s38, 0x3ff
	s_add_i32 s3, s3, s100
	s_lshl_b32 s3, s3, 1
	s_mul_i32 s5, s4, 0x3000000
	s_add_u32 s3, s3, s5
	s_lshl_b32 s5, s101, 11
	s_add_u32 s3, s3, s5
	s_add_u32 s98, s68, s3
	s_addc_u32 s99, s69, 0
	s_mov_b32 s7, 0x8000
	s_mov_b32 s2, 11
	v_and_b32_e32 v242, 15, v178
	v_bfe_u32 v243, v178, 4, 1
	v_lshlrev_b32_e32 v242, s2, v242
	v_lshl_add_u32 v242, v243, 5, v242
	v_bfe_u32 v243, v178, 5, 1
	s_nop 0
	v_lshl_add_u32 v242, v243, 4, v242
	s_cmp_eq_u32 s4, 3
	s_cbranch_scc1 .Lepi13_store
	s_cmp_eq_u32 s4, 0
	s_cbranch_scc1 .Lepi13_silu
	s_cmp_eq_u32 s4, 4
	s_cbranch_scc1 .Lepi13_silu
	s_add_i32 s3, s38, s100
	s_lshl_b32 s3, s3, 2
	s_add_u32 s4, s68, s3
	s_addc_u32 s5, s69, 0
	s_add_u32 s4, s4, 0x14103000
	s_addc_u32 s5, s5, 0
	v_bfe_u32 v243, v178, 4, 2
	v_lshlrev_b32_e32 v243, 4, v243
	global_load_dwordx4 v[156:159], v243, s[4:5]
	global_load_dwordx4 v[160:163], v243, s[4:5] offset:64
	global_load_dwordx4 v[172:175], v243, s[4:5] offset:128
	global_load_dwordx4 v[188:191], v243, s[4:5] offset:192
	s_waitcnt vmcnt(0)
	v_mul_f32_e32 v146, 0xbfb8aa3b, v124
	v_mul_f32_e32 v147, 0xbfb8aa3b, v125
	v_mul_f32_e32 v148, 0xbfb8aa3b, v126
	v_mul_f32_e32 v149, 0xbfb8aa3b, v127
	v_exp_f32_e32 v146, v146
	v_exp_f32_e32 v147, v147
	v_exp_f32_e32 v148, v148
	v_exp_f32_e32 v149, v149
	v_sub_f32_e32 v142, 1.0, v156
	v_sub_f32_e32 v143, 1.0, v157
	v_sub_f32_e32 v144, 1.0, v158
	v_sub_f32_e32 v145, 1.0, v159
	v_add_f32_e32 v146, 1.0, v146
	v_add_f32_e32 v147, 1.0, v147
	v_add_f32_e32 v148, 1.0, v148
	v_add_f32_e32 v149, 1.0, v149
	v_rcp_f32_e32 v146, v146
	v_rcp_f32_e32 v147, v147
	v_rcp_f32_e32 v148, v148
	v_rcp_f32_e32 v149, v149
	v_mul_f32_e32 v142, v142, v146
	v_mul_f32_e32 v143, v143, v147
	v_mul_f32_e32 v144, v144, v148
	v_mul_f32_e32 v145, v145, v149
	v_add_f32_e32 v142, v156, v142
	v_add_f32_e32 v143, v157, v143
	v_add_f32_e32 v144, v158, v144
	v_add_f32_e32 v145, v159, v145
	v_log_f32_e32 v124, v142
	v_log_f32_e32 v125, v143
	v_log_f32_e32 v126, v144
	v_log_f32_e32 v127, v145
	v_mul_f32_e32 v146, 0xbfb8aa3b, v120
	v_mul_f32_e32 v147, 0xbfb8aa3b, v121
	v_mul_f32_e32 v148, 0xbfb8aa3b, v122
	v_mul_f32_e32 v149, 0xbfb8aa3b, v123
	v_exp_f32_e32 v146, v146
	v_exp_f32_e32 v147, v147
	v_exp_f32_e32 v148, v148
	v_exp_f32_e32 v149, v149
	v_sub_f32_e32 v142, 1.0, v160
	v_sub_f32_e32 v143, 1.0, v161
	v_sub_f32_e32 v144, 1.0, v162
	v_sub_f32_e32 v145, 1.0, v163
	v_add_f32_e32 v146, 1.0, v146
	v_add_f32_e32 v147, 1.0, v147
	v_add_f32_e32 v148, 1.0, v148
	v_add_f32_e32 v149, 1.0, v149
	v_rcp_f32_e32 v146, v146
	v_rcp_f32_e32 v147, v147
	v_rcp_f32_e32 v148, v148
	v_rcp_f32_e32 v149, v149
	v_mul_f32_e32 v142, v142, v146
	v_mul_f32_e32 v143, v143, v147
	v_mul_f32_e32 v144, v144, v148
	v_mul_f32_e32 v145, v145, v149
	v_add_f32_e32 v142, v160, v142
	v_add_f32_e32 v143, v161, v143
	v_add_f32_e32 v144, v162, v144
	v_add_f32_e32 v145, v163, v145
	v_log_f32_e32 v120, v142
	v_log_f32_e32 v121, v143
	v_log_f32_e32 v122, v144
	v_log_f32_e32 v123, v145
	v_mul_f32_e32 v146, 0xbfb8aa3b, v116
	v_mul_f32_e32 v147, 0xbfb8aa3b, v117
	v_mul_f32_e32 v148, 0xbfb8aa3b, v118
	v_mul_f32_e32 v149, 0xbfb8aa3b, v119
	v_exp_f32_e32 v146, v146
	v_exp_f32_e32 v147, v147
	v_exp_f32_e32 v148, v148
	v_exp_f32_e32 v149, v149
	v_sub_f32_e32 v142, 1.0, v172
	v_sub_f32_e32 v143, 1.0, v173
	v_sub_f32_e32 v144, 1.0, v174
	v_sub_f32_e32 v145, 1.0, v175
	v_add_f32_e32 v146, 1.0, v146
	v_add_f32_e32 v147, 1.0, v147
	v_add_f32_e32 v148, 1.0, v148
	v_add_f32_e32 v149, 1.0, v149
	v_rcp_f32_e32 v146, v146
	v_rcp_f32_e32 v147, v147
	v_rcp_f32_e32 v148, v148
	v_rcp_f32_e32 v149, v149
	v_mul_f32_e32 v142, v142, v146
	v_mul_f32_e32 v143, v143, v147
	v_mul_f32_e32 v144, v144, v148
	v_mul_f32_e32 v145, v145, v149
	v_add_f32_e32 v142, v172, v142
	v_add_f32_e32 v143, v173, v143
	v_add_f32_e32 v144, v174, v144
	v_add_f32_e32 v145, v175, v145
	v_log_f32_e32 v116, v142
	v_log_f32_e32 v117, v143
	v_log_f32_e32 v118, v144
	v_log_f32_e32 v119, v145
	v_mul_f32_e32 v146, 0xbfb8aa3b, v112
	v_mul_f32_e32 v147, 0xbfb8aa3b, v113
	v_mul_f32_e32 v148, 0xbfb8aa3b, v114
	v_mul_f32_e32 v149, 0xbfb8aa3b, v115
	v_exp_f32_e32 v146, v146
	v_exp_f32_e32 v147, v147
	v_exp_f32_e32 v148, v148
	v_exp_f32_e32 v149, v149
	v_sub_f32_e32 v142, 1.0, v188
	v_sub_f32_e32 v143, 1.0, v189
	v_sub_f32_e32 v144, 1.0, v190
	v_sub_f32_e32 v145, 1.0, v191
	v_add_f32_e32 v146, 1.0, v146
	v_add_f32_e32 v147, 1.0, v147
	v_add_f32_e32 v148, 1.0, v148
	v_add_f32_e32 v149, 1.0, v149
	v_rcp_f32_e32 v146, v146
	v_rcp_f32_e32 v147, v147
	v_rcp_f32_e32 v148, v148
	v_rcp_f32_e32 v149, v149
	v_mul_f32_e32 v142, v142, v146
	v_mul_f32_e32 v143, v143, v147
	v_mul_f32_e32 v144, v144, v148
	v_mul_f32_e32 v145, v145, v149
	v_add_f32_e32 v142, v188, v142
	v_add_f32_e32 v143, v189, v143
	v_add_f32_e32 v144, v190, v144
	v_add_f32_e32 v145, v191, v145
	v_log_f32_e32 v112, v142
	v_log_f32_e32 v113, v143
	v_log_f32_e32 v114, v144
	v_log_f32_e32 v115, v145
	v_cvt_pk_bf16_f32 v124, v124, v125
	v_cvt_pk_bf16_f32 v125, v126, v127
	v_cvt_pk_bf16_f32 v126, v120, v121
	v_cvt_pk_bf16_f32 v127, v122, v123
	v_cvt_pk_bf16_f32 v116, v116, v117
	v_cvt_pk_bf16_f32 v117, v118, v119
	v_cvt_pk_bf16_f32 v118, v112, v113
	v_cvt_pk_bf16_f32 v119, v114, v115
	v_permlane16_swap_b32_e32 v124, v126
	v_permlane16_swap_b32_e32 v125, v127
	v_permlane16_swap_b32_e32 v116, v118
	v_permlane16_swap_b32_e32 v117, v119
	global_store_dwordx4 v242, v[124:127], s[98:99]
	global_store_dwordx4 v242, v[116:119], s[98:99] offset:64
	s_add_u32 s98, s98, s7
	s_addc_u32 s99, s99, 0
	v_mul_f32_e32 v146, 0xbfb8aa3b, v108
	v_mul_f32_e32 v147, 0xbfb8aa3b, v109
	v_mul_f32_e32 v148, 0xbfb8aa3b, v110
	v_mul_f32_e32 v149, 0xbfb8aa3b, v111
	v_exp_f32_e32 v146, v146
	v_exp_f32_e32 v147, v147
	v_exp_f32_e32 v148, v148
	v_exp_f32_e32 v149, v149
	v_sub_f32_e32 v142, 1.0, v156
	v_sub_f32_e32 v143, 1.0, v157
	v_sub_f32_e32 v144, 1.0, v158
	v_sub_f32_e32 v145, 1.0, v159
	v_add_f32_e32 v146, 1.0, v146
	v_add_f32_e32 v147, 1.0, v147
	v_add_f32_e32 v148, 1.0, v148
	v_add_f32_e32 v149, 1.0, v149
	v_rcp_f32_e32 v146, v146
	v_rcp_f32_e32 v147, v147
	v_rcp_f32_e32 v148, v148
	v_rcp_f32_e32 v149, v149
	v_mul_f32_e32 v142, v142, v146
	v_mul_f32_e32 v143, v143, v147
	v_mul_f32_e32 v144, v144, v148
	v_mul_f32_e32 v145, v145, v149
	v_add_f32_e32 v142, v156, v142
	v_add_f32_e32 v143, v157, v143
	v_add_f32_e32 v144, v158, v144
	v_add_f32_e32 v145, v159, v145
	v_log_f32_e32 v108, v142
	v_log_f32_e32 v109, v143
	v_log_f32_e32 v110, v144
	v_log_f32_e32 v111, v145
	v_mul_f32_e32 v146, 0xbfb8aa3b, v104
	v_mul_f32_e32 v147, 0xbfb8aa3b, v105
	v_mul_f32_e32 v148, 0xbfb8aa3b, v106
	v_mul_f32_e32 v149, 0xbfb8aa3b, v107
	v_exp_f32_e32 v146, v146
	v_exp_f32_e32 v147, v147
	v_exp_f32_e32 v148, v148
	v_exp_f32_e32 v149, v149
	v_sub_f32_e32 v142, 1.0, v160
	v_sub_f32_e32 v143, 1.0, v161
	v_sub_f32_e32 v144, 1.0, v162
	v_sub_f32_e32 v145, 1.0, v163
	v_add_f32_e32 v146, 1.0, v146
	v_add_f32_e32 v147, 1.0, v147
	v_add_f32_e32 v148, 1.0, v148
	v_add_f32_e32 v149, 1.0, v149
	v_rcp_f32_e32 v146, v146
	v_rcp_f32_e32 v147, v147
	v_rcp_f32_e32 v148, v148
	v_rcp_f32_e32 v149, v149
	v_mul_f32_e32 v142, v142, v146
	v_mul_f32_e32 v143, v143, v147
	v_mul_f32_e32 v144, v144, v148
	v_mul_f32_e32 v145, v145, v149
	v_add_f32_e32 v142, v160, v142
	v_add_f32_e32 v143, v161, v143
	v_add_f32_e32 v144, v162, v144
	v_add_f32_e32 v145, v163, v145
	v_log_f32_e32 v104, v142
	v_log_f32_e32 v105, v143
	v_log_f32_e32 v106, v144
	v_log_f32_e32 v107, v145
	v_mul_f32_e32 v146, 0xbfb8aa3b, v100
	v_mul_f32_e32 v147, 0xbfb8aa3b, v101
	v_mul_f32_e32 v148, 0xbfb8aa3b, v102
	v_mul_f32_e32 v149, 0xbfb8aa3b, v103
	v_exp_f32_e32 v146, v146
	v_exp_f32_e32 v147, v147
	v_exp_f32_e32 v148, v148
	v_exp_f32_e32 v149, v149
	v_sub_f32_e32 v142, 1.0, v172
	v_sub_f32_e32 v143, 1.0, v173
	v_sub_f32_e32 v144, 1.0, v174
	v_sub_f32_e32 v145, 1.0, v175
	v_add_f32_e32 v146, 1.0, v146
	v_add_f32_e32 v147, 1.0, v147
	v_add_f32_e32 v148, 1.0, v148
	v_add_f32_e32 v149, 1.0, v149
	v_rcp_f32_e32 v146, v146
	v_rcp_f32_e32 v147, v147
	v_rcp_f32_e32 v148, v148
	v_rcp_f32_e32 v149, v149
	v_mul_f32_e32 v142, v142, v146
	v_mul_f32_e32 v143, v143, v147
	v_mul_f32_e32 v144, v144, v148
	v_mul_f32_e32 v145, v145, v149
	v_add_f32_e32 v142, v172, v142
	v_add_f32_e32 v143, v173, v143
	v_add_f32_e32 v144, v174, v144
	v_add_f32_e32 v145, v175, v145
	v_log_f32_e32 v100, v142
	v_log_f32_e32 v101, v143
	v_log_f32_e32 v102, v144
	v_log_f32_e32 v103, v145
	v_mul_f32_e32 v146, 0xbfb8aa3b, v96
	v_mul_f32_e32 v147, 0xbfb8aa3b, v97
	v_mul_f32_e32 v148, 0xbfb8aa3b, v98
	v_mul_f32_e32 v149, 0xbfb8aa3b, v99
	v_exp_f32_e32 v146, v146
	v_exp_f32_e32 v147, v147
	v_exp_f32_e32 v148, v148
	v_exp_f32_e32 v149, v149
	v_sub_f32_e32 v142, 1.0, v188
	v_sub_f32_e32 v143, 1.0, v189
	v_sub_f32_e32 v144, 1.0, v190
	v_sub_f32_e32 v145, 1.0, v191
	v_add_f32_e32 v146, 1.0, v146
	v_add_f32_e32 v147, 1.0, v147
	v_add_f32_e32 v148, 1.0, v148
	v_add_f32_e32 v149, 1.0, v149
	v_rcp_f32_e32 v146, v146
	v_rcp_f32_e32 v147, v147
	v_rcp_f32_e32 v148, v148
	v_rcp_f32_e32 v149, v149
	v_mul_f32_e32 v142, v142, v146
	v_mul_f32_e32 v143, v143, v147
	v_mul_f32_e32 v144, v144, v148
	v_mul_f32_e32 v145, v145, v149
	v_add_f32_e32 v142, v188, v142
	v_add_f32_e32 v143, v189, v143
	v_add_f32_e32 v144, v190, v144
	v_add_f32_e32 v145, v191, v145
	v_log_f32_e32 v96, v142
	v_log_f32_e32 v97, v143
	v_log_f32_e32 v98, v144
	v_log_f32_e32 v99, v145
	v_cvt_pk_bf16_f32 v108, v108, v109
	v_cvt_pk_bf16_f32 v109, v110, v111
	v_cvt_pk_bf16_f32 v110, v104, v105
	v_cvt_pk_bf16_f32 v111, v106, v107
	v_cvt_pk_bf16_f32 v100, v100, v101
	v_cvt_pk_bf16_f32 v101, v102, v103
	v_cvt_pk_bf16_f32 v102, v96, v97
	v_cvt_pk_bf16_f32 v103, v98, v99
	v_permlane16_swap_b32_e32 v108, v110
	v_permlane16_swap_b32_e32 v109, v111
	v_permlane16_swap_b32_e32 v100, v102
	v_permlane16_swap_b32_e32 v101, v103
	global_store_dwordx4 v242, v[108:111], s[98:99]
	global_store_dwordx4 v242, v[100:103], s[98:99] offset:64
	s_add_u32 s98, s98, s7
	s_addc_u32 s99, s99, 0
	v_mul_f32_e32 v146, 0xbfb8aa3b, v92
	v_mul_f32_e32 v147, 0xbfb8aa3b, v93
	v_mul_f32_e32 v148, 0xbfb8aa3b, v94
	v_mul_f32_e32 v149, 0xbfb8aa3b, v95
	v_exp_f32_e32 v146, v146
	v_exp_f32_e32 v147, v147
	v_exp_f32_e32 v148, v148
	v_exp_f32_e32 v149, v149
	v_sub_f32_e32 v142, 1.0, v156
	v_sub_f32_e32 v143, 1.0, v157
	v_sub_f32_e32 v144, 1.0, v158
	v_sub_f32_e32 v145, 1.0, v159
	v_add_f32_e32 v146, 1.0, v146
	v_add_f32_e32 v147, 1.0, v147
	v_add_f32_e32 v148, 1.0, v148
	v_add_f32_e32 v149, 1.0, v149
	v_rcp_f32_e32 v146, v146
	v_rcp_f32_e32 v147, v147
	v_rcp_f32_e32 v148, v148
	v_rcp_f32_e32 v149, v149
	v_mul_f32_e32 v142, v142, v146
	v_mul_f32_e32 v143, v143, v147
	v_mul_f32_e32 v144, v144, v148
	v_mul_f32_e32 v145, v145, v149
	v_add_f32_e32 v142, v156, v142
	v_add_f32_e32 v143, v157, v143
	v_add_f32_e32 v144, v158, v144
	v_add_f32_e32 v145, v159, v145
	v_log_f32_e32 v92, v142
	v_log_f32_e32 v93, v143
	v_log_f32_e32 v94, v144
	v_log_f32_e32 v95, v145
	v_mul_f32_e32 v146, 0xbfb8aa3b, v88
	v_mul_f32_e32 v147, 0xbfb8aa3b, v89
	v_mul_f32_e32 v148, 0xbfb8aa3b, v90
	v_mul_f32_e32 v149, 0xbfb8aa3b, v91
	v_exp_f32_e32 v146, v146
	v_exp_f32_e32 v147, v147
	v_exp_f32_e32 v148, v148
	v_exp_f32_e32 v149, v149
	v_sub_f32_e32 v142, 1.0, v160
	v_sub_f32_e32 v143, 1.0, v161
	v_sub_f32_e32 v144, 1.0, v162
	v_sub_f32_e32 v145, 1.0, v163
	v_add_f32_e32 v146, 1.0, v146
	v_add_f32_e32 v147, 1.0, v147
	v_add_f32_e32 v148, 1.0, v148
	v_add_f32_e32 v149, 1.0, v149
	v_rcp_f32_e32 v146, v146
	v_rcp_f32_e32 v147, v147
	v_rcp_f32_e32 v148, v148
	v_rcp_f32_e32 v149, v149
	v_mul_f32_e32 v142, v142, v146
	v_mul_f32_e32 v143, v143, v147
	v_mul_f32_e32 v144, v144, v148
	v_mul_f32_e32 v145, v145, v149
	v_add_f32_e32 v142, v160, v142
	v_add_f32_e32 v143, v161, v143
	v_add_f32_e32 v144, v162, v144
	v_add_f32_e32 v145, v163, v145
	v_log_f32_e32 v88, v142
	v_log_f32_e32 v89, v143
	v_log_f32_e32 v90, v144
	v_log_f32_e32 v91, v145
	v_mul_f32_e32 v146, 0xbfb8aa3b, v84
	v_mul_f32_e32 v147, 0xbfb8aa3b, v85
	v_mul_f32_e32 v148, 0xbfb8aa3b, v86
	v_mul_f32_e32 v149, 0xbfb8aa3b, v87
	v_exp_f32_e32 v146, v146
	v_exp_f32_e32 v147, v147
	v_exp_f32_e32 v148, v148
	v_exp_f32_e32 v149, v149
	v_sub_f32_e32 v142, 1.0, v172
	v_sub_f32_e32 v143, 1.0, v173
	v_sub_f32_e32 v144, 1.0, v174
	v_sub_f32_e32 v145, 1.0, v175
	v_add_f32_e32 v146, 1.0, v146
	v_add_f32_e32 v147, 1.0, v147
	v_add_f32_e32 v148, 1.0, v148
	v_add_f32_e32 v149, 1.0, v149
	v_rcp_f32_e32 v146, v146
	v_rcp_f32_e32 v147, v147
	v_rcp_f32_e32 v148, v148
	v_rcp_f32_e32 v149, v149
	v_mul_f32_e32 v142, v142, v146
	v_mul_f32_e32 v143, v143, v147
	v_mul_f32_e32 v144, v144, v148
	v_mul_f32_e32 v145, v145, v149
	v_add_f32_e32 v142, v172, v142
	v_add_f32_e32 v143, v173, v143
	v_add_f32_e32 v144, v174, v144
	v_add_f32_e32 v145, v175, v145
	v_log_f32_e32 v84, v142
	v_log_f32_e32 v85, v143
	v_log_f32_e32 v86, v144
	v_log_f32_e32 v87, v145
	v_mul_f32_e32 v146, 0xbfb8aa3b, v80
	v_mul_f32_e32 v147, 0xbfb8aa3b, v81
	v_mul_f32_e32 v148, 0xbfb8aa3b, v82
	v_mul_f32_e32 v149, 0xbfb8aa3b, v83
	v_exp_f32_e32 v146, v146
	v_exp_f32_e32 v147, v147
	v_exp_f32_e32 v148, v148
	v_exp_f32_e32 v149, v149
	v_sub_f32_e32 v142, 1.0, v188
	v_sub_f32_e32 v143, 1.0, v189
	v_sub_f32_e32 v144, 1.0, v190
	v_sub_f32_e32 v145, 1.0, v191
	v_add_f32_e32 v146, 1.0, v146
	v_add_f32_e32 v147, 1.0, v147
	v_add_f32_e32 v148, 1.0, v148
	v_add_f32_e32 v149, 1.0, v149
	v_rcp_f32_e32 v146, v146
	v_rcp_f32_e32 v147, v147
	v_rcp_f32_e32 v148, v148
	v_rcp_f32_e32 v149, v149
	v_mul_f32_e32 v142, v142, v146
	v_mul_f32_e32 v143, v143, v147
	v_mul_f32_e32 v144, v144, v148
	v_mul_f32_e32 v145, v145, v149
	v_add_f32_e32 v142, v188, v142
	v_add_f32_e32 v143, v189, v143
	v_add_f32_e32 v144, v190, v144
	v_add_f32_e32 v145, v191, v145
	v_log_f32_e32 v80, v142
	v_log_f32_e32 v81, v143
	v_log_f32_e32 v82, v144
	v_log_f32_e32 v83, v145
	v_cvt_pk_bf16_f32 v92, v92, v93
	v_cvt_pk_bf16_f32 v93, v94, v95
	v_cvt_pk_bf16_f32 v94, v88, v89
	v_cvt_pk_bf16_f32 v95, v90, v91
	v_cvt_pk_bf16_f32 v84, v84, v85
	v_cvt_pk_bf16_f32 v85, v86, v87
	v_cvt_pk_bf16_f32 v86, v80, v81
	v_cvt_pk_bf16_f32 v87, v82, v83
	v_permlane16_swap_b32_e32 v92, v94
	v_permlane16_swap_b32_e32 v93, v95
	v_permlane16_swap_b32_e32 v84, v86
	v_permlane16_swap_b32_e32 v85, v87
	global_store_dwordx4 v242, v[92:95], s[98:99]
	global_store_dwordx4 v242, v[84:87], s[98:99] offset:64
	s_add_u32 s98, s98, s7
	s_addc_u32 s99, s99, 0
	v_mul_f32_e32 v146, 0xbfb8aa3b, v76
	v_mul_f32_e32 v147, 0xbfb8aa3b, v77
	v_mul_f32_e32 v148, 0xbfb8aa3b, v78
	v_mul_f32_e32 v149, 0xbfb8aa3b, v79
	v_exp_f32_e32 v146, v146
	v_exp_f32_e32 v147, v147
	v_exp_f32_e32 v148, v148
	v_exp_f32_e32 v149, v149
	v_sub_f32_e32 v142, 1.0, v156
	v_sub_f32_e32 v143, 1.0, v157
	v_sub_f32_e32 v144, 1.0, v158
	v_sub_f32_e32 v145, 1.0, v159
	v_add_f32_e32 v146, 1.0, v146
	v_add_f32_e32 v147, 1.0, v147
	v_add_f32_e32 v148, 1.0, v148
	v_add_f32_e32 v149, 1.0, v149
	v_rcp_f32_e32 v146, v146
	v_rcp_f32_e32 v147, v147
	v_rcp_f32_e32 v148, v148
	v_rcp_f32_e32 v149, v149
	v_mul_f32_e32 v142, v142, v146
	v_mul_f32_e32 v143, v143, v147
	v_mul_f32_e32 v144, v144, v148
	v_mul_f32_e32 v145, v145, v149
	v_add_f32_e32 v142, v156, v142
	v_add_f32_e32 v143, v157, v143
	v_add_f32_e32 v144, v158, v144
	v_add_f32_e32 v145, v159, v145
	v_log_f32_e32 v76, v142
	v_log_f32_e32 v77, v143
	v_log_f32_e32 v78, v144
	v_log_f32_e32 v79, v145
	v_mul_f32_e32 v146, 0xbfb8aa3b, v72
	v_mul_f32_e32 v147, 0xbfb8aa3b, v73
	v_mul_f32_e32 v148, 0xbfb8aa3b, v74
	v_mul_f32_e32 v149, 0xbfb8aa3b, v75
	v_exp_f32_e32 v146, v146
	v_exp_f32_e32 v147, v147
	v_exp_f32_e32 v148, v148
	v_exp_f32_e32 v149, v149
	v_sub_f32_e32 v142, 1.0, v160
	v_sub_f32_e32 v143, 1.0, v161
	v_sub_f32_e32 v144, 1.0, v162
	v_sub_f32_e32 v145, 1.0, v163
	v_add_f32_e32 v146, 1.0, v146
	v_add_f32_e32 v147, 1.0, v147
	v_add_f32_e32 v148, 1.0, v148
	v_add_f32_e32 v149, 1.0, v149
	v_rcp_f32_e32 v146, v146
	v_rcp_f32_e32 v147, v147
	v_rcp_f32_e32 v148, v148
	v_rcp_f32_e32 v149, v149
	v_mul_f32_e32 v142, v142, v146
	v_mul_f32_e32 v143, v143, v147
	v_mul_f32_e32 v144, v144, v148
	v_mul_f32_e32 v145, v145, v149
	v_add_f32_e32 v142, v160, v142
	v_add_f32_e32 v143, v161, v143
	v_add_f32_e32 v144, v162, v144
	v_add_f32_e32 v145, v163, v145
	v_log_f32_e32 v72, v142
	v_log_f32_e32 v73, v143
	v_log_f32_e32 v74, v144
	v_log_f32_e32 v75, v145
	v_mul_f32_e32 v146, 0xbfb8aa3b, v68
	v_mul_f32_e32 v147, 0xbfb8aa3b, v69
	v_mul_f32_e32 v148, 0xbfb8aa3b, v70
	v_mul_f32_e32 v149, 0xbfb8aa3b, v71
	v_exp_f32_e32 v146, v146
	v_exp_f32_e32 v147, v147
	v_exp_f32_e32 v148, v148
	v_exp_f32_e32 v149, v149
	v_sub_f32_e32 v142, 1.0, v172
	v_sub_f32_e32 v143, 1.0, v173
	v_sub_f32_e32 v144, 1.0, v174
	v_sub_f32_e32 v145, 1.0, v175
	v_add_f32_e32 v146, 1.0, v146
	v_add_f32_e32 v147, 1.0, v147
	v_add_f32_e32 v148, 1.0, v148
	v_add_f32_e32 v149, 1.0, v149
	v_rcp_f32_e32 v146, v146
	v_rcp_f32_e32 v147, v147
	v_rcp_f32_e32 v148, v148
	v_rcp_f32_e32 v149, v149
	v_mul_f32_e32 v142, v142, v146
	v_mul_f32_e32 v143, v143, v147
	v_mul_f32_e32 v144, v144, v148
	v_mul_f32_e32 v145, v145, v149
	v_add_f32_e32 v142, v172, v142
	v_add_f32_e32 v143, v173, v143
	v_add_f32_e32 v144, v174, v144
	v_add_f32_e32 v145, v175, v145
	v_log_f32_e32 v68, v142
	v_log_f32_e32 v69, v143
	v_log_f32_e32 v70, v144
	v_log_f32_e32 v71, v145
	v_mul_f32_e32 v146, 0xbfb8aa3b, v64
	v_mul_f32_e32 v147, 0xbfb8aa3b, v65
	v_mul_f32_e32 v148, 0xbfb8aa3b, v66
	v_mul_f32_e32 v149, 0xbfb8aa3b, v67
	v_exp_f32_e32 v146, v146
	v_exp_f32_e32 v147, v147
	v_exp_f32_e32 v148, v148
	v_exp_f32_e32 v149, v149
	v_sub_f32_e32 v142, 1.0, v188
	v_sub_f32_e32 v143, 1.0, v189
	v_sub_f32_e32 v144, 1.0, v190
	v_sub_f32_e32 v145, 1.0, v191
	v_add_f32_e32 v146, 1.0, v146
	v_add_f32_e32 v147, 1.0, v147
	v_add_f32_e32 v148, 1.0, v148
	v_add_f32_e32 v149, 1.0, v149
	v_rcp_f32_e32 v146, v146
	v_rcp_f32_e32 v147, v147
	v_rcp_f32_e32 v148, v148
	v_rcp_f32_e32 v149, v149
	v_mul_f32_e32 v142, v142, v146
	v_mul_f32_e32 v143, v143, v147
	v_mul_f32_e32 v144, v144, v148
	v_mul_f32_e32 v145, v145, v149
	v_add_f32_e32 v142, v188, v142
	v_add_f32_e32 v143, v189, v143
	v_add_f32_e32 v144, v190, v144
	v_add_f32_e32 v145, v191, v145
	v_log_f32_e32 v64, v142
	v_log_f32_e32 v65, v143
	v_log_f32_e32 v66, v144
	v_log_f32_e32 v67, v145
	v_cvt_pk_bf16_f32 v76, v76, v77
	v_cvt_pk_bf16_f32 v77, v78, v79
	v_cvt_pk_bf16_f32 v78, v72, v73
	v_cvt_pk_bf16_f32 v79, v74, v75
	v_cvt_pk_bf16_f32 v68, v68, v69
	v_cvt_pk_bf16_f32 v69, v70, v71
	v_cvt_pk_bf16_f32 v70, v64, v65
	v_cvt_pk_bf16_f32 v71, v66, v67
	v_permlane16_swap_b32_e32 v76, v78
	v_permlane16_swap_b32_e32 v77, v79
	v_permlane16_swap_b32_e32 v68, v70
	v_permlane16_swap_b32_e32 v69, v71
	global_store_dwordx4 v242, v[76:79], s[98:99]
	global_store_dwordx4 v242, v[68:71], s[98:99] offset:64
	s_add_u32 s98, s98, s7
	s_addc_u32 s99, s99, 0
	v_mul_f32_e32 v146, 0xbfb8aa3b, v60
	v_mul_f32_e32 v147, 0xbfb8aa3b, v61
	v_mul_f32_e32 v148, 0xbfb8aa3b, v62
	v_mul_f32_e32 v149, 0xbfb8aa3b, v63
	v_exp_f32_e32 v146, v146
	v_exp_f32_e32 v147, v147
	v_exp_f32_e32 v148, v148
	v_exp_f32_e32 v149, v149
	v_sub_f32_e32 v142, 1.0, v156
	v_sub_f32_e32 v143, 1.0, v157
	v_sub_f32_e32 v144, 1.0, v158
	v_sub_f32_e32 v145, 1.0, v159
	v_add_f32_e32 v146, 1.0, v146
	v_add_f32_e32 v147, 1.0, v147
	v_add_f32_e32 v148, 1.0, v148
	v_add_f32_e32 v149, 1.0, v149
	v_rcp_f32_e32 v146, v146
	v_rcp_f32_e32 v147, v147
	v_rcp_f32_e32 v148, v148
	v_rcp_f32_e32 v149, v149
	v_mul_f32_e32 v142, v142, v146
	v_mul_f32_e32 v143, v143, v147
	v_mul_f32_e32 v144, v144, v148
	v_mul_f32_e32 v145, v145, v149
	v_add_f32_e32 v142, v156, v142
	v_add_f32_e32 v143, v157, v143
	v_add_f32_e32 v144, v158, v144
	v_add_f32_e32 v145, v159, v145
	v_log_f32_e32 v60, v142
	v_log_f32_e32 v61, v143
	v_log_f32_e32 v62, v144
	v_log_f32_e32 v63, v145
	v_mul_f32_e32 v146, 0xbfb8aa3b, v56
	v_mul_f32_e32 v147, 0xbfb8aa3b, v57
	v_mul_f32_e32 v148, 0xbfb8aa3b, v58
	v_mul_f32_e32 v149, 0xbfb8aa3b, v59
	v_exp_f32_e32 v146, v146
	v_exp_f32_e32 v147, v147
	v_exp_f32_e32 v148, v148
	v_exp_f32_e32 v149, v149
	v_sub_f32_e32 v142, 1.0, v160
	v_sub_f32_e32 v143, 1.0, v161
	v_sub_f32_e32 v144, 1.0, v162
	v_sub_f32_e32 v145, 1.0, v163
	v_add_f32_e32 v146, 1.0, v146
	v_add_f32_e32 v147, 1.0, v147
	v_add_f32_e32 v148, 1.0, v148
	v_add_f32_e32 v149, 1.0, v149
	v_rcp_f32_e32 v146, v146
	v_rcp_f32_e32 v147, v147
	v_rcp_f32_e32 v148, v148
	v_rcp_f32_e32 v149, v149
	v_mul_f32_e32 v142, v142, v146
	v_mul_f32_e32 v143, v143, v147
	v_mul_f32_e32 v144, v144, v148
	v_mul_f32_e32 v145, v145, v149
	v_add_f32_e32 v142, v160, v142
	v_add_f32_e32 v143, v161, v143
	v_add_f32_e32 v144, v162, v144
	v_add_f32_e32 v145, v163, v145
	v_log_f32_e32 v56, v142
	v_log_f32_e32 v57, v143
	v_log_f32_e32 v58, v144
	v_log_f32_e32 v59, v145
	v_mul_f32_e32 v146, 0xbfb8aa3b, v52
	v_mul_f32_e32 v147, 0xbfb8aa3b, v53
	v_mul_f32_e32 v148, 0xbfb8aa3b, v54
	v_mul_f32_e32 v149, 0xbfb8aa3b, v55
	v_exp_f32_e32 v146, v146
	v_exp_f32_e32 v147, v147
	v_exp_f32_e32 v148, v148
	v_exp_f32_e32 v149, v149
	v_sub_f32_e32 v142, 1.0, v172
	v_sub_f32_e32 v143, 1.0, v173
	v_sub_f32_e32 v144, 1.0, v174
	v_sub_f32_e32 v145, 1.0, v175
	v_add_f32_e32 v146, 1.0, v146
	v_add_f32_e32 v147, 1.0, v147
	v_add_f32_e32 v148, 1.0, v148
	v_add_f32_e32 v149, 1.0, v149
	v_rcp_f32_e32 v146, v146
	v_rcp_f32_e32 v147, v147
	v_rcp_f32_e32 v148, v148
	v_rcp_f32_e32 v149, v149
	v_mul_f32_e32 v142, v142, v146
	v_mul_f32_e32 v143, v143, v147
	v_mul_f32_e32 v144, v144, v148
	v_mul_f32_e32 v145, v145, v149
	v_add_f32_e32 v142, v172, v142
	v_add_f32_e32 v143, v173, v143
	v_add_f32_e32 v144, v174, v144
	v_add_f32_e32 v145, v175, v145
	v_log_f32_e32 v52, v142
	v_log_f32_e32 v53, v143
	v_log_f32_e32 v54, v144
	v_log_f32_e32 v55, v145
	v_mul_f32_e32 v146, 0xbfb8aa3b, v48
	v_mul_f32_e32 v147, 0xbfb8aa3b, v49
	v_mul_f32_e32 v148, 0xbfb8aa3b, v50
	v_mul_f32_e32 v149, 0xbfb8aa3b, v51
	v_exp_f32_e32 v146, v146
	v_exp_f32_e32 v147, v147
	v_exp_f32_e32 v148, v148
	v_exp_f32_e32 v149, v149
	v_sub_f32_e32 v142, 1.0, v188
	v_sub_f32_e32 v143, 1.0, v189
	v_sub_f32_e32 v144, 1.0, v190
	v_sub_f32_e32 v145, 1.0, v191
	v_add_f32_e32 v146, 1.0, v146
	v_add_f32_e32 v147, 1.0, v147
	v_add_f32_e32 v148, 1.0, v148
	v_add_f32_e32 v149, 1.0, v149
	v_rcp_f32_e32 v146, v146
	v_rcp_f32_e32 v147, v147
	v_rcp_f32_e32 v148, v148
	v_rcp_f32_e32 v149, v149
	v_mul_f32_e32 v142, v142, v146
	v_mul_f32_e32 v143, v143, v147
	v_mul_f32_e32 v144, v144, v148
	v_mul_f32_e32 v145, v145, v149
	v_add_f32_e32 v142, v188, v142
	v_add_f32_e32 v143, v189, v143
	v_add_f32_e32 v144, v190, v144
	v_add_f32_e32 v145, v191, v145
	v_log_f32_e32 v48, v142
	v_log_f32_e32 v49, v143
	v_log_f32_e32 v50, v144
	v_log_f32_e32 v51, v145
	v_cvt_pk_bf16_f32 v60, v60, v61
	v_cvt_pk_bf16_f32 v61, v62, v63
	v_cvt_pk_bf16_f32 v62, v56, v57
	v_cvt_pk_bf16_f32 v63, v58, v59
	v_cvt_pk_bf16_f32 v52, v52, v53
	v_cvt_pk_bf16_f32 v53, v54, v55
	v_cvt_pk_bf16_f32 v54, v48, v49
	v_cvt_pk_bf16_f32 v55, v50, v51
	v_permlane16_swap_b32_e32 v60, v62
	v_permlane16_swap_b32_e32 v61, v63
	v_permlane16_swap_b32_e32 v52, v54
	v_permlane16_swap_b32_e32 v53, v55
	global_store_dwordx4 v242, v[60:63], s[98:99]
	global_store_dwordx4 v242, v[52:55], s[98:99] offset:64
	s_add_u32 s98, s98, s7
	s_addc_u32 s99, s99, 0
	v_mul_f32_e32 v146, 0xbfb8aa3b, v44
	v_mul_f32_e32 v147, 0xbfb8aa3b, v45
	v_mul_f32_e32 v148, 0xbfb8aa3b, v46
	v_mul_f32_e32 v149, 0xbfb8aa3b, v47
	v_exp_f32_e32 v146, v146
	v_exp_f32_e32 v147, v147
	v_exp_f32_e32 v148, v148
	v_exp_f32_e32 v149, v149
	v_sub_f32_e32 v142, 1.0, v156
	v_sub_f32_e32 v143, 1.0, v157
	v_sub_f32_e32 v144, 1.0, v158
	v_sub_f32_e32 v145, 1.0, v159
	v_add_f32_e32 v146, 1.0, v146
	v_add_f32_e32 v147, 1.0, v147
	v_add_f32_e32 v148, 1.0, v148
	v_add_f32_e32 v149, 1.0, v149
	v_rcp_f32_e32 v146, v146
	v_rcp_f32_e32 v147, v147
	v_rcp_f32_e32 v148, v148
	v_rcp_f32_e32 v149, v149
	v_mul_f32_e32 v142, v142, v146
	v_mul_f32_e32 v143, v143, v147
	v_mul_f32_e32 v144, v144, v148
	v_mul_f32_e32 v145, v145, v149
	v_add_f32_e32 v142, v156, v142
	v_add_f32_e32 v143, v157, v143
	v_add_f32_e32 v144, v158, v144
	v_add_f32_e32 v145, v159, v145
	v_log_f32_e32 v44, v142
	v_log_f32_e32 v45, v143
	v_log_f32_e32 v46, v144
	v_log_f32_e32 v47, v145
	v_mul_f32_e32 v146, 0xbfb8aa3b, v40
	v_mul_f32_e32 v147, 0xbfb8aa3b, v41
	v_mul_f32_e32 v148, 0xbfb8aa3b, v42
	v_mul_f32_e32 v149, 0xbfb8aa3b, v43
	v_exp_f32_e32 v146, v146
	v_exp_f32_e32 v147, v147
	v_exp_f32_e32 v148, v148
	v_exp_f32_e32 v149, v149
	v_sub_f32_e32 v142, 1.0, v160
	v_sub_f32_e32 v143, 1.0, v161
	v_sub_f32_e32 v144, 1.0, v162
	v_sub_f32_e32 v145, 1.0, v163
	v_add_f32_e32 v146, 1.0, v146
	v_add_f32_e32 v147, 1.0, v147
	v_add_f32_e32 v148, 1.0, v148
	v_add_f32_e32 v149, 1.0, v149
	v_rcp_f32_e32 v146, v146
	v_rcp_f32_e32 v147, v147
	v_rcp_f32_e32 v148, v148
	v_rcp_f32_e32 v149, v149
	v_mul_f32_e32 v142, v142, v146
	v_mul_f32_e32 v143, v143, v147
	v_mul_f32_e32 v144, v144, v148
	v_mul_f32_e32 v145, v145, v149
	v_add_f32_e32 v142, v160, v142
	v_add_f32_e32 v143, v161, v143
	v_add_f32_e32 v144, v162, v144
	v_add_f32_e32 v145, v163, v145
	v_log_f32_e32 v40, v142
	v_log_f32_e32 v41, v143
	v_log_f32_e32 v42, v144
	v_log_f32_e32 v43, v145
	v_mul_f32_e32 v146, 0xbfb8aa3b, v36
	v_mul_f32_e32 v147, 0xbfb8aa3b, v37
	v_mul_f32_e32 v148, 0xbfb8aa3b, v38
	v_mul_f32_e32 v149, 0xbfb8aa3b, v39
	v_exp_f32_e32 v146, v146
	v_exp_f32_e32 v147, v147
	v_exp_f32_e32 v148, v148
	v_exp_f32_e32 v149, v149
	v_sub_f32_e32 v142, 1.0, v172
	v_sub_f32_e32 v143, 1.0, v173
	v_sub_f32_e32 v144, 1.0, v174
	v_sub_f32_e32 v145, 1.0, v175
	v_add_f32_e32 v146, 1.0, v146
	v_add_f32_e32 v147, 1.0, v147
	v_add_f32_e32 v148, 1.0, v148
	v_add_f32_e32 v149, 1.0, v149
	v_rcp_f32_e32 v146, v146
	v_rcp_f32_e32 v147, v147
	v_rcp_f32_e32 v148, v148
	v_rcp_f32_e32 v149, v149
	v_mul_f32_e32 v142, v142, v146
	v_mul_f32_e32 v143, v143, v147
	v_mul_f32_e32 v144, v144, v148
	v_mul_f32_e32 v145, v145, v149
	v_add_f32_e32 v142, v172, v142
	v_add_f32_e32 v143, v173, v143
	v_add_f32_e32 v144, v174, v144
	v_add_f32_e32 v145, v175, v145
	v_log_f32_e32 v36, v142
	v_log_f32_e32 v37, v143
	v_log_f32_e32 v38, v144
	v_log_f32_e32 v39, v145
	v_mul_f32_e32 v146, 0xbfb8aa3b, v32
	v_mul_f32_e32 v147, 0xbfb8aa3b, v33
	v_mul_f32_e32 v148, 0xbfb8aa3b, v34
	v_mul_f32_e32 v149, 0xbfb8aa3b, v35
	v_exp_f32_e32 v146, v146
	v_exp_f32_e32 v147, v147
	v_exp_f32_e32 v148, v148
	v_exp_f32_e32 v149, v149
	v_sub_f32_e32 v142, 1.0, v188
	v_sub_f32_e32 v143, 1.0, v189
	v_sub_f32_e32 v144, 1.0, v190
	v_sub_f32_e32 v145, 1.0, v191
	v_add_f32_e32 v146, 1.0, v146
	v_add_f32_e32 v147, 1.0, v147
	v_add_f32_e32 v148, 1.0, v148
	v_add_f32_e32 v149, 1.0, v149
	v_rcp_f32_e32 v146, v146
	v_rcp_f32_e32 v147, v147
	v_rcp_f32_e32 v148, v148
	v_rcp_f32_e32 v149, v149
	v_mul_f32_e32 v142, v142, v146
	v_mul_f32_e32 v143, v143, v147
	v_mul_f32_e32 v144, v144, v148
	v_mul_f32_e32 v145, v145, v149
	v_add_f32_e32 v142, v188, v142
	v_add_f32_e32 v143, v189, v143
	v_add_f32_e32 v144, v190, v144
	v_add_f32_e32 v145, v191, v145
	v_log_f32_e32 v32, v142
	v_log_f32_e32 v33, v143
	v_log_f32_e32 v34, v144
	v_log_f32_e32 v35, v145
	v_cvt_pk_bf16_f32 v44, v44, v45
	v_cvt_pk_bf16_f32 v45, v46, v47
	v_cvt_pk_bf16_f32 v46, v40, v41
	v_cvt_pk_bf16_f32 v47, v42, v43
	v_cvt_pk_bf16_f32 v36, v36, v37
	v_cvt_pk_bf16_f32 v37, v38, v39
	v_cvt_pk_bf16_f32 v38, v32, v33
	v_cvt_pk_bf16_f32 v39, v34, v35
	v_permlane16_swap_b32_e32 v44, v46
	v_permlane16_swap_b32_e32 v45, v47
	v_permlane16_swap_b32_e32 v36, v38
	v_permlane16_swap_b32_e32 v37, v39
	global_store_dwordx4 v242, v[44:47], s[98:99]
	global_store_dwordx4 v242, v[36:39], s[98:99] offset:64
	s_add_u32 s98, s98, s7
	s_addc_u32 s99, s99, 0
	v_mul_f32_e32 v146, 0xbfb8aa3b, v28
	v_mul_f32_e32 v147, 0xbfb8aa3b, v29
	v_mul_f32_e32 v148, 0xbfb8aa3b, v30
	v_mul_f32_e32 v149, 0xbfb8aa3b, v31
	v_exp_f32_e32 v146, v146
	v_exp_f32_e32 v147, v147
	v_exp_f32_e32 v148, v148
	v_exp_f32_e32 v149, v149
	v_sub_f32_e32 v142, 1.0, v156
	v_sub_f32_e32 v143, 1.0, v157
	v_sub_f32_e32 v144, 1.0, v158
	v_sub_f32_e32 v145, 1.0, v159
	v_add_f32_e32 v146, 1.0, v146
	v_add_f32_e32 v147, 1.0, v147
	v_add_f32_e32 v148, 1.0, v148
	v_add_f32_e32 v149, 1.0, v149
	v_rcp_f32_e32 v146, v146
	v_rcp_f32_e32 v147, v147
	v_rcp_f32_e32 v148, v148
	v_rcp_f32_e32 v149, v149
	v_mul_f32_e32 v142, v142, v146
	v_mul_f32_e32 v143, v143, v147
	v_mul_f32_e32 v144, v144, v148
	v_mul_f32_e32 v145, v145, v149
	v_add_f32_e32 v142, v156, v142
	v_add_f32_e32 v143, v157, v143
	v_add_f32_e32 v144, v158, v144
	v_add_f32_e32 v145, v159, v145
	v_log_f32_e32 v28, v142
	v_log_f32_e32 v29, v143
	v_log_f32_e32 v30, v144
	v_log_f32_e32 v31, v145
	v_mul_f32_e32 v146, 0xbfb8aa3b, v24
	v_mul_f32_e32 v147, 0xbfb8aa3b, v25
	v_mul_f32_e32 v148, 0xbfb8aa3b, v26
	v_mul_f32_e32 v149, 0xbfb8aa3b, v27
	v_exp_f32_e32 v146, v146
	v_exp_f32_e32 v147, v147
	v_exp_f32_e32 v148, v148
	v_exp_f32_e32 v149, v149
	v_sub_f32_e32 v142, 1.0, v160
	v_sub_f32_e32 v143, 1.0, v161
	v_sub_f32_e32 v144, 1.0, v162
	v_sub_f32_e32 v145, 1.0, v163
	v_add_f32_e32 v146, 1.0, v146
	v_add_f32_e32 v147, 1.0, v147
	v_add_f32_e32 v148, 1.0, v148
	v_add_f32_e32 v149, 1.0, v149
	v_rcp_f32_e32 v146, v146
	v_rcp_f32_e32 v147, v147
	v_rcp_f32_e32 v148, v148
	v_rcp_f32_e32 v149, v149
	v_mul_f32_e32 v142, v142, v146
	v_mul_f32_e32 v143, v143, v147
	v_mul_f32_e32 v144, v144, v148
	v_mul_f32_e32 v145, v145, v149
	v_add_f32_e32 v142, v160, v142
	v_add_f32_e32 v143, v161, v143
	v_add_f32_e32 v144, v162, v144
	v_add_f32_e32 v145, v163, v145
	v_log_f32_e32 v24, v142
	v_log_f32_e32 v25, v143
	v_log_f32_e32 v26, v144
	v_log_f32_e32 v27, v145
	v_mul_f32_e32 v146, 0xbfb8aa3b, v20
	v_mul_f32_e32 v147, 0xbfb8aa3b, v21
	v_mul_f32_e32 v148, 0xbfb8aa3b, v22
	v_mul_f32_e32 v149, 0xbfb8aa3b, v23
	v_exp_f32_e32 v146, v146
	v_exp_f32_e32 v147, v147
	v_exp_f32_e32 v148, v148
	v_exp_f32_e32 v149, v149
	v_sub_f32_e32 v142, 1.0, v172
	v_sub_f32_e32 v143, 1.0, v173
	v_sub_f32_e32 v144, 1.0, v174
	v_sub_f32_e32 v145, 1.0, v175
	v_add_f32_e32 v146, 1.0, v146
	v_add_f32_e32 v147, 1.0, v147
	v_add_f32_e32 v148, 1.0, v148
	v_add_f32_e32 v149, 1.0, v149
	v_rcp_f32_e32 v146, v146
	v_rcp_f32_e32 v147, v147
	v_rcp_f32_e32 v148, v148
	v_rcp_f32_e32 v149, v149
	v_mul_f32_e32 v142, v142, v146
	v_mul_f32_e32 v143, v143, v147
	v_mul_f32_e32 v144, v144, v148
	v_mul_f32_e32 v145, v145, v149
	v_add_f32_e32 v142, v172, v142
	v_add_f32_e32 v143, v173, v143
	v_add_f32_e32 v144, v174, v144
	v_add_f32_e32 v145, v175, v145
	v_log_f32_e32 v20, v142
	v_log_f32_e32 v21, v143
	v_log_f32_e32 v22, v144
	v_log_f32_e32 v23, v145
	v_mul_f32_e32 v146, 0xbfb8aa3b, v16
	v_mul_f32_e32 v147, 0xbfb8aa3b, v17
	v_mul_f32_e32 v148, 0xbfb8aa3b, v18
	v_mul_f32_e32 v149, 0xbfb8aa3b, v19
	v_exp_f32_e32 v146, v146
	v_exp_f32_e32 v147, v147
	v_exp_f32_e32 v148, v148
	v_exp_f32_e32 v149, v149
	v_sub_f32_e32 v142, 1.0, v188
	v_sub_f32_e32 v143, 1.0, v189
	v_sub_f32_e32 v144, 1.0, v190
	v_sub_f32_e32 v145, 1.0, v191
	v_add_f32_e32 v146, 1.0, v146
	v_add_f32_e32 v147, 1.0, v147
	v_add_f32_e32 v148, 1.0, v148
	v_add_f32_e32 v149, 1.0, v149
	v_rcp_f32_e32 v146, v146
	v_rcp_f32_e32 v147, v147
	v_rcp_f32_e32 v148, v148
	v_rcp_f32_e32 v149, v149
	v_mul_f32_e32 v142, v142, v146
	v_mul_f32_e32 v143, v143, v147
	v_mul_f32_e32 v144, v144, v148
	v_mul_f32_e32 v145, v145, v149
	v_add_f32_e32 v142, v188, v142
	v_add_f32_e32 v143, v189, v143
	v_add_f32_e32 v144, v190, v144
	v_add_f32_e32 v145, v191, v145
	v_log_f32_e32 v16, v142
	v_log_f32_e32 v17, v143
	v_log_f32_e32 v18, v144
	v_log_f32_e32 v19, v145
	v_cvt_pk_bf16_f32 v28, v28, v29
	v_cvt_pk_bf16_f32 v29, v30, v31
	v_cvt_pk_bf16_f32 v30, v24, v25
	v_cvt_pk_bf16_f32 v31, v26, v27
	v_cvt_pk_bf16_f32 v20, v20, v21
	v_cvt_pk_bf16_f32 v21, v22, v23
	v_cvt_pk_bf16_f32 v22, v16, v17
	v_cvt_pk_bf16_f32 v23, v18, v19
	v_permlane16_swap_b32_e32 v28, v30
	v_permlane16_swap_b32_e32 v29, v31
	v_permlane16_swap_b32_e32 v20, v22
	v_permlane16_swap_b32_e32 v21, v23
	global_store_dwordx4 v242, v[28:31], s[98:99]
	global_store_dwordx4 v242, v[20:23], s[98:99] offset:64
	s_add_u32 s98, s98, s7
	s_addc_u32 s99, s99, 0
	v_mul_f32_e32 v146, 0xbfb8aa3b, v12
	v_mul_f32_e32 v147, 0xbfb8aa3b, v13
	v_mul_f32_e32 v148, 0xbfb8aa3b, v14
	v_mul_f32_e32 v149, 0xbfb8aa3b, v15
	v_exp_f32_e32 v146, v146
	v_exp_f32_e32 v147, v147
	v_exp_f32_e32 v148, v148
	v_exp_f32_e32 v149, v149
	v_sub_f32_e32 v142, 1.0, v156
	v_sub_f32_e32 v143, 1.0, v157
	v_sub_f32_e32 v144, 1.0, v158
	v_sub_f32_e32 v145, 1.0, v159
	v_add_f32_e32 v146, 1.0, v146
	v_add_f32_e32 v147, 1.0, v147
	v_add_f32_e32 v148, 1.0, v148
	v_add_f32_e32 v149, 1.0, v149
	v_rcp_f32_e32 v146, v146
	v_rcp_f32_e32 v147, v147
	v_rcp_f32_e32 v148, v148
	v_rcp_f32_e32 v149, v149
	v_mul_f32_e32 v142, v142, v146
	v_mul_f32_e32 v143, v143, v147
	v_mul_f32_e32 v144, v144, v148
	v_mul_f32_e32 v145, v145, v149
	v_add_f32_e32 v142, v156, v142
	v_add_f32_e32 v143, v157, v143
	v_add_f32_e32 v144, v158, v144
	v_add_f32_e32 v145, v159, v145
	v_log_f32_e32 v12, v142
	v_log_f32_e32 v13, v143
	v_log_f32_e32 v14, v144
	v_log_f32_e32 v15, v145
	v_mul_f32_e32 v146, 0xbfb8aa3b, v8
	v_mul_f32_e32 v147, 0xbfb8aa3b, v9
	v_mul_f32_e32 v148, 0xbfb8aa3b, v10
	v_mul_f32_e32 v149, 0xbfb8aa3b, v11
	v_exp_f32_e32 v146, v146
	v_exp_f32_e32 v147, v147
	v_exp_f32_e32 v148, v148
	v_exp_f32_e32 v149, v149
	v_sub_f32_e32 v142, 1.0, v160
	v_sub_f32_e32 v143, 1.0, v161
	v_sub_f32_e32 v144, 1.0, v162
	v_sub_f32_e32 v145, 1.0, v163
	v_add_f32_e32 v146, 1.0, v146
	v_add_f32_e32 v147, 1.0, v147
	v_add_f32_e32 v148, 1.0, v148
	v_add_f32_e32 v149, 1.0, v149
	v_rcp_f32_e32 v146, v146
	v_rcp_f32_e32 v147, v147
	v_rcp_f32_e32 v148, v148
	v_rcp_f32_e32 v149, v149
	v_mul_f32_e32 v142, v142, v146
	v_mul_f32_e32 v143, v143, v147
	v_mul_f32_e32 v144, v144, v148
	v_mul_f32_e32 v145, v145, v149
	v_add_f32_e32 v142, v160, v142
	v_add_f32_e32 v143, v161, v143
	v_add_f32_e32 v144, v162, v144
	v_add_f32_e32 v145, v163, v145
	v_log_f32_e32 v8, v142
	v_log_f32_e32 v9, v143
	v_log_f32_e32 v10, v144
	v_log_f32_e32 v11, v145
	v_mul_f32_e32 v146, 0xbfb8aa3b, v4
	v_mul_f32_e32 v147, 0xbfb8aa3b, v5
	v_mul_f32_e32 v148, 0xbfb8aa3b, v6
	v_mul_f32_e32 v149, 0xbfb8aa3b, v7
	v_exp_f32_e32 v146, v146
	v_exp_f32_e32 v147, v147
	v_exp_f32_e32 v148, v148
	v_exp_f32_e32 v149, v149
	v_sub_f32_e32 v142, 1.0, v172
	v_sub_f32_e32 v143, 1.0, v173
	v_sub_f32_e32 v144, 1.0, v174
	v_sub_f32_e32 v145, 1.0, v175
	v_add_f32_e32 v146, 1.0, v146
	v_add_f32_e32 v147, 1.0, v147
	v_add_f32_e32 v148, 1.0, v148
	v_add_f32_e32 v149, 1.0, v149
	v_rcp_f32_e32 v146, v146
	v_rcp_f32_e32 v147, v147
	v_rcp_f32_e32 v148, v148
	v_rcp_f32_e32 v149, v149
	v_mul_f32_e32 v142, v142, v146
	v_mul_f32_e32 v143, v143, v147
	v_mul_f32_e32 v144, v144, v148
	v_mul_f32_e32 v145, v145, v149
	v_add_f32_e32 v142, v172, v142
	v_add_f32_e32 v143, v173, v143
	v_add_f32_e32 v144, v174, v144
	v_add_f32_e32 v145, v175, v145
	v_log_f32_e32 v4, v142
	v_log_f32_e32 v5, v143
	v_log_f32_e32 v6, v144
	v_log_f32_e32 v7, v145
	v_mul_f32_e32 v146, 0xbfb8aa3b, v0
	v_mul_f32_e32 v147, 0xbfb8aa3b, v1
	v_mul_f32_e32 v148, 0xbfb8aa3b, v2
	v_mul_f32_e32 v149, 0xbfb8aa3b, v3
	v_exp_f32_e32 v146, v146
	v_exp_f32_e32 v147, v147
	v_exp_f32_e32 v148, v148
	v_exp_f32_e32 v149, v149
	v_sub_f32_e32 v142, 1.0, v188
	v_sub_f32_e32 v143, 1.0, v189
	v_sub_f32_e32 v144, 1.0, v190
	v_sub_f32_e32 v145, 1.0, v191
	v_add_f32_e32 v146, 1.0, v146
	v_add_f32_e32 v147, 1.0, v147
	v_add_f32_e32 v148, 1.0, v148
	v_add_f32_e32 v149, 1.0, v149
	v_rcp_f32_e32 v146, v146
	v_rcp_f32_e32 v147, v147
	v_rcp_f32_e32 v148, v148
	v_rcp_f32_e32 v149, v149
	v_mul_f32_e32 v142, v142, v146
	v_mul_f32_e32 v143, v143, v147
	v_mul_f32_e32 v144, v144, v148
	v_mul_f32_e32 v145, v145, v149
	v_add_f32_e32 v142, v188, v142
	v_add_f32_e32 v143, v189, v143
	v_add_f32_e32 v144, v190, v144
	v_add_f32_e32 v145, v191, v145
	v_log_f32_e32 v0, v142
	v_log_f32_e32 v1, v143
	v_log_f32_e32 v2, v144
	v_log_f32_e32 v3, v145
	v_cvt_pk_bf16_f32 v12, v12, v13
	v_cvt_pk_bf16_f32 v13, v14, v15
	v_cvt_pk_bf16_f32 v14, v8, v9
	v_cvt_pk_bf16_f32 v15, v10, v11
	v_cvt_pk_bf16_f32 v4, v4, v5
	v_cvt_pk_bf16_f32 v5, v6, v7
	v_cvt_pk_bf16_f32 v6, v0, v1
	v_cvt_pk_bf16_f32 v7, v2, v3
	v_permlane16_swap_b32_e32 v12, v14
	v_permlane16_swap_b32_e32 v13, v15
	v_permlane16_swap_b32_e32 v4, v6
	v_permlane16_swap_b32_e32 v5, v7
	global_store_dwordx4 v242, v[12:15], s[98:99]
	global_store_dwordx4 v242, v[4:7], s[98:99] offset:64
	s_mov_b64 s[8:9], -1
	s_and_b64 vcc, exec, s[36:37]
	s_cbranch_vccnz .LBB0_1435
	s_branch .LBB0_1232
.Lepi13_silu:
	v_mul_f32_e32 v146, 0xbfb8aa3b, v124
	v_mul_f32_e32 v147, 0xbfb8aa3b, v125
	v_mul_f32_e32 v148, 0xbfb8aa3b, v126
	v_mul_f32_e32 v149, 0xbfb8aa3b, v127
	v_exp_f32_e32 v146, v146
	v_exp_f32_e32 v147, v147
	v_exp_f32_e32 v148, v148
	v_exp_f32_e32 v149, v149
	v_add_f32_e32 v146, 1.0, v146
	v_add_f32_e32 v147, 1.0, v147
	v_add_f32_e32 v148, 1.0, v148
	v_add_f32_e32 v149, 1.0, v149
	v_rcp_f32_e32 v146, v146
	v_rcp_f32_e32 v147, v147
	v_rcp_f32_e32 v148, v148
	v_rcp_f32_e32 v149, v149
	v_mul_f32_e32 v124, v124, v146
	v_mul_f32_e32 v125, v125, v147
	v_mul_f32_e32 v126, v126, v148
	v_mul_f32_e32 v127, v127, v149
	v_mul_f32_e32 v142, 0xbfb8aa3b, v120
	v_mul_f32_e32 v143, 0xbfb8aa3b, v121
	v_mul_f32_e32 v144, 0xbfb8aa3b, v122
	v_mul_f32_e32 v145, 0xbfb8aa3b, v123
	v_exp_f32_e32 v142, v142
	v_exp_f32_e32 v143, v143
	v_exp_f32_e32 v144, v144
	v_exp_f32_e32 v145, v145
	v_add_f32_e32 v142, 1.0, v142
	v_add_f32_e32 v143, 1.0, v143
	v_add_f32_e32 v144, 1.0, v144
	v_add_f32_e32 v145, 1.0, v145
	v_rcp_f32_e32 v142, v142
	v_rcp_f32_e32 v143, v143
	v_rcp_f32_e32 v144, v144
	v_rcp_f32_e32 v145, v145
	v_mul_f32_e32 v120, v120, v142
	v_mul_f32_e32 v121, v121, v143
	v_mul_f32_e32 v122, v122, v144
	v_mul_f32_e32 v123, v123, v145
	v_mul_f32_e32 v146, 0xbfb8aa3b, v116
	v_mul_f32_e32 v147, 0xbfb8aa3b, v117
	v_mul_f32_e32 v148, 0xbfb8aa3b, v118
	v_mul_f32_e32 v149, 0xbfb8aa3b, v119
	v_exp_f32_e32 v146, v146
	v_exp_f32_e32 v147, v147
	v_exp_f32_e32 v148, v148
	v_exp_f32_e32 v149, v149
	v_add_f32_e32 v146, 1.0, v146
	v_add_f32_e32 v147, 1.0, v147
	v_add_f32_e32 v148, 1.0, v148
	v_add_f32_e32 v149, 1.0, v149
	v_rcp_f32_e32 v146, v146
	v_rcp_f32_e32 v147, v147
	v_rcp_f32_e32 v148, v148
	v_rcp_f32_e32 v149, v149
	v_mul_f32_e32 v116, v116, v146
	v_mul_f32_e32 v117, v117, v147
	v_mul_f32_e32 v118, v118, v148
	v_mul_f32_e32 v119, v119, v149
	v_mul_f32_e32 v142, 0xbfb8aa3b, v112
	v_mul_f32_e32 v143, 0xbfb8aa3b, v113
	v_mul_f32_e32 v144, 0xbfb8aa3b, v114
	v_mul_f32_e32 v145, 0xbfb8aa3b, v115
	v_exp_f32_e32 v142, v142
	v_exp_f32_e32 v143, v143
	v_exp_f32_e32 v144, v144
	v_exp_f32_e32 v145, v145
	v_add_f32_e32 v142, 1.0, v142
	v_add_f32_e32 v143, 1.0, v143
	v_add_f32_e32 v144, 1.0, v144
	v_add_f32_e32 v145, 1.0, v145
	v_rcp_f32_e32 v142, v142
	v_rcp_f32_e32 v143, v143
	v_rcp_f32_e32 v144, v144
	v_rcp_f32_e32 v145, v145
	v_mul_f32_e32 v112, v112, v142
	v_mul_f32_e32 v113, v113, v143
	v_mul_f32_e32 v114, v114, v144
	v_mul_f32_e32 v115, v115, v145
	v_cvt_pk_bf16_f32 v124, v124, v125
	v_cvt_pk_bf16_f32 v125, v126, v127
	v_cvt_pk_bf16_f32 v126, v120, v121
	v_cvt_pk_bf16_f32 v127, v122, v123
	v_cvt_pk_bf16_f32 v116, v116, v117
	v_cvt_pk_bf16_f32 v117, v118, v119
	v_cvt_pk_bf16_f32 v118, v112, v113
	v_cvt_pk_bf16_f32 v119, v114, v115
	v_permlane16_swap_b32_e32 v124, v126
	v_permlane16_swap_b32_e32 v125, v127
	v_permlane16_swap_b32_e32 v116, v118
	v_permlane16_swap_b32_e32 v117, v119
	global_store_dwordx4 v242, v[124:127], s[98:99]
	global_store_dwordx4 v242, v[116:119], s[98:99] offset:64
	s_add_u32 s98, s98, s7
	s_addc_u32 s99, s99, 0
	v_mul_f32_e32 v146, 0xbfb8aa3b, v108
	v_mul_f32_e32 v147, 0xbfb8aa3b, v109
	v_mul_f32_e32 v148, 0xbfb8aa3b, v110
	v_mul_f32_e32 v149, 0xbfb8aa3b, v111
	v_exp_f32_e32 v146, v146
	v_exp_f32_e32 v147, v147
	v_exp_f32_e32 v148, v148
	v_exp_f32_e32 v149, v149
	v_add_f32_e32 v146, 1.0, v146
	v_add_f32_e32 v147, 1.0, v147
	v_add_f32_e32 v148, 1.0, v148
	v_add_f32_e32 v149, 1.0, v149
	v_rcp_f32_e32 v146, v146
	v_rcp_f32_e32 v147, v147
	v_rcp_f32_e32 v148, v148
	v_rcp_f32_e32 v149, v149
	v_mul_f32_e32 v108, v108, v146
	v_mul_f32_e32 v109, v109, v147
	v_mul_f32_e32 v110, v110, v148
	v_mul_f32_e32 v111, v111, v149
	v_mul_f32_e32 v142, 0xbfb8aa3b, v104
	v_mul_f32_e32 v143, 0xbfb8aa3b, v105
	v_mul_f32_e32 v144, 0xbfb8aa3b, v106
	v_mul_f32_e32 v145, 0xbfb8aa3b, v107
	v_exp_f32_e32 v142, v142
	v_exp_f32_e32 v143, v143
	v_exp_f32_e32 v144, v144
	v_exp_f32_e32 v145, v145
	v_add_f32_e32 v142, 1.0, v142
	v_add_f32_e32 v143, 1.0, v143
	v_add_f32_e32 v144, 1.0, v144
	v_add_f32_e32 v145, 1.0, v145
	v_rcp_f32_e32 v142, v142
	v_rcp_f32_e32 v143, v143
	v_rcp_f32_e32 v144, v144
	v_rcp_f32_e32 v145, v145
	v_mul_f32_e32 v104, v104, v142
	v_mul_f32_e32 v105, v105, v143
	v_mul_f32_e32 v106, v106, v144
	v_mul_f32_e32 v107, v107, v145
	v_mul_f32_e32 v146, 0xbfb8aa3b, v100
	v_mul_f32_e32 v147, 0xbfb8aa3b, v101
	v_mul_f32_e32 v148, 0xbfb8aa3b, v102
	v_mul_f32_e32 v149, 0xbfb8aa3b, v103
	v_exp_f32_e32 v146, v146
	v_exp_f32_e32 v147, v147
	v_exp_f32_e32 v148, v148
	v_exp_f32_e32 v149, v149
	v_add_f32_e32 v146, 1.0, v146
	v_add_f32_e32 v147, 1.0, v147
	v_add_f32_e32 v148, 1.0, v148
	v_add_f32_e32 v149, 1.0, v149
	v_rcp_f32_e32 v146, v146
	v_rcp_f32_e32 v147, v147
	v_rcp_f32_e32 v148, v148
	v_rcp_f32_e32 v149, v149
	v_mul_f32_e32 v100, v100, v146
	v_mul_f32_e32 v101, v101, v147
	v_mul_f32_e32 v102, v102, v148
	v_mul_f32_e32 v103, v103, v149
	v_mul_f32_e32 v142, 0xbfb8aa3b, v96
	v_mul_f32_e32 v143, 0xbfb8aa3b, v97
	v_mul_f32_e32 v144, 0xbfb8aa3b, v98
	v_mul_f32_e32 v145, 0xbfb8aa3b, v99
	v_exp_f32_e32 v142, v142
	v_exp_f32_e32 v143, v143
	v_exp_f32_e32 v144, v144
	v_exp_f32_e32 v145, v145
	v_add_f32_e32 v142, 1.0, v142
	v_add_f32_e32 v143, 1.0, v143
	v_add_f32_e32 v144, 1.0, v144
	v_add_f32_e32 v145, 1.0, v145
	v_rcp_f32_e32 v142, v142
	v_rcp_f32_e32 v143, v143
	v_rcp_f32_e32 v144, v144
	v_rcp_f32_e32 v145, v145
	v_mul_f32_e32 v96, v96, v142
	v_mul_f32_e32 v97, v97, v143
	v_mul_f32_e32 v98, v98, v144
	v_mul_f32_e32 v99, v99, v145
	v_cvt_pk_bf16_f32 v108, v108, v109
	v_cvt_pk_bf16_f32 v109, v110, v111
	v_cvt_pk_bf16_f32 v110, v104, v105
	v_cvt_pk_bf16_f32 v111, v106, v107
	v_cvt_pk_bf16_f32 v100, v100, v101
	v_cvt_pk_bf16_f32 v101, v102, v103
	v_cvt_pk_bf16_f32 v102, v96, v97
	v_cvt_pk_bf16_f32 v103, v98, v99
	v_permlane16_swap_b32_e32 v108, v110
	v_permlane16_swap_b32_e32 v109, v111
	v_permlane16_swap_b32_e32 v100, v102
	v_permlane16_swap_b32_e32 v101, v103
	global_store_dwordx4 v242, v[108:111], s[98:99]
	global_store_dwordx4 v242, v[100:103], s[98:99] offset:64
	s_add_u32 s98, s98, s7
	s_addc_u32 s99, s99, 0
	v_mul_f32_e32 v146, 0xbfb8aa3b, v92
	v_mul_f32_e32 v147, 0xbfb8aa3b, v93
	v_mul_f32_e32 v148, 0xbfb8aa3b, v94
	v_mul_f32_e32 v149, 0xbfb8aa3b, v95
	v_exp_f32_e32 v146, v146
	v_exp_f32_e32 v147, v147
	v_exp_f32_e32 v148, v148
	v_exp_f32_e32 v149, v149
	v_add_f32_e32 v146, 1.0, v146
	v_add_f32_e32 v147, 1.0, v147
	v_add_f32_e32 v148, 1.0, v148
	v_add_f32_e32 v149, 1.0, v149
	v_rcp_f32_e32 v146, v146
	v_rcp_f32_e32 v147, v147
	v_rcp_f32_e32 v148, v148
	v_rcp_f32_e32 v149, v149
	v_mul_f32_e32 v92, v92, v146
	v_mul_f32_e32 v93, v93, v147
	v_mul_f32_e32 v94, v94, v148
	v_mul_f32_e32 v95, v95, v149
	v_mul_f32_e32 v142, 0xbfb8aa3b, v88
	v_mul_f32_e32 v143, 0xbfb8aa3b, v89
	v_mul_f32_e32 v144, 0xbfb8aa3b, v90
	v_mul_f32_e32 v145, 0xbfb8aa3b, v91
	v_exp_f32_e32 v142, v142
	v_exp_f32_e32 v143, v143
	v_exp_f32_e32 v144, v144
	v_exp_f32_e32 v145, v145
	v_add_f32_e32 v142, 1.0, v142
	v_add_f32_e32 v143, 1.0, v143
	v_add_f32_e32 v144, 1.0, v144
	v_add_f32_e32 v145, 1.0, v145
	v_rcp_f32_e32 v142, v142
	v_rcp_f32_e32 v143, v143
	v_rcp_f32_e32 v144, v144
	v_rcp_f32_e32 v145, v145
	v_mul_f32_e32 v88, v88, v142
	v_mul_f32_e32 v89, v89, v143
	v_mul_f32_e32 v90, v90, v144
	v_mul_f32_e32 v91, v91, v145
	v_mul_f32_e32 v146, 0xbfb8aa3b, v84
	v_mul_f32_e32 v147, 0xbfb8aa3b, v85
	v_mul_f32_e32 v148, 0xbfb8aa3b, v86
	v_mul_f32_e32 v149, 0xbfb8aa3b, v87
	v_exp_f32_e32 v146, v146
	v_exp_f32_e32 v147, v147
	v_exp_f32_e32 v148, v148
	v_exp_f32_e32 v149, v149
	v_add_f32_e32 v146, 1.0, v146
	v_add_f32_e32 v147, 1.0, v147
	v_add_f32_e32 v148, 1.0, v148
	v_add_f32_e32 v149, 1.0, v149
	v_rcp_f32_e32 v146, v146
	v_rcp_f32_e32 v147, v147
	v_rcp_f32_e32 v148, v148
	v_rcp_f32_e32 v149, v149
	v_mul_f32_e32 v84, v84, v146
	v_mul_f32_e32 v85, v85, v147
	v_mul_f32_e32 v86, v86, v148
	v_mul_f32_e32 v87, v87, v149
	v_mul_f32_e32 v142, 0xbfb8aa3b, v80
	v_mul_f32_e32 v143, 0xbfb8aa3b, v81
	v_mul_f32_e32 v144, 0xbfb8aa3b, v82
	v_mul_f32_e32 v145, 0xbfb8aa3b, v83
	v_exp_f32_e32 v142, v142
	v_exp_f32_e32 v143, v143
	v_exp_f32_e32 v144, v144
	v_exp_f32_e32 v145, v145
	v_add_f32_e32 v142, 1.0, v142
	v_add_f32_e32 v143, 1.0, v143
	v_add_f32_e32 v144, 1.0, v144
	v_add_f32_e32 v145, 1.0, v145
	v_rcp_f32_e32 v142, v142
	v_rcp_f32_e32 v143, v143
	v_rcp_f32_e32 v144, v144
	v_rcp_f32_e32 v145, v145
	v_mul_f32_e32 v80, v80, v142
	v_mul_f32_e32 v81, v81, v143
	v_mul_f32_e32 v82, v82, v144
	v_mul_f32_e32 v83, v83, v145
	v_cvt_pk_bf16_f32 v92, v92, v93
	v_cvt_pk_bf16_f32 v93, v94, v95
	v_cvt_pk_bf16_f32 v94, v88, v89
	v_cvt_pk_bf16_f32 v95, v90, v91
	v_cvt_pk_bf16_f32 v84, v84, v85
	v_cvt_pk_bf16_f32 v85, v86, v87
	v_cvt_pk_bf16_f32 v86, v80, v81
	v_cvt_pk_bf16_f32 v87, v82, v83
	v_permlane16_swap_b32_e32 v92, v94
	v_permlane16_swap_b32_e32 v93, v95
	v_permlane16_swap_b32_e32 v84, v86
	v_permlane16_swap_b32_e32 v85, v87
	global_store_dwordx4 v242, v[92:95], s[98:99]
	global_store_dwordx4 v242, v[84:87], s[98:99] offset:64
	s_add_u32 s98, s98, s7
	s_addc_u32 s99, s99, 0
	v_mul_f32_e32 v146, 0xbfb8aa3b, v76
	v_mul_f32_e32 v147, 0xbfb8aa3b, v77
	v_mul_f32_e32 v148, 0xbfb8aa3b, v78
	v_mul_f32_e32 v149, 0xbfb8aa3b, v79
	v_exp_f32_e32 v146, v146
	v_exp_f32_e32 v147, v147
	v_exp_f32_e32 v148, v148
	v_exp_f32_e32 v149, v149
	v_add_f32_e32 v146, 1.0, v146
	v_add_f32_e32 v147, 1.0, v147
	v_add_f32_e32 v148, 1.0, v148
	v_add_f32_e32 v149, 1.0, v149
	v_rcp_f32_e32 v146, v146
	v_rcp_f32_e32 v147, v147
	v_rcp_f32_e32 v148, v148
	v_rcp_f32_e32 v149, v149
	v_mul_f32_e32 v76, v76, v146
	v_mul_f32_e32 v77, v77, v147
	v_mul_f32_e32 v78, v78, v148
	v_mul_f32_e32 v79, v79, v149
	v_mul_f32_e32 v142, 0xbfb8aa3b, v72
	v_mul_f32_e32 v143, 0xbfb8aa3b, v73
	v_mul_f32_e32 v144, 0xbfb8aa3b, v74
	v_mul_f32_e32 v145, 0xbfb8aa3b, v75
	v_exp_f32_e32 v142, v142
	v_exp_f32_e32 v143, v143
	v_exp_f32_e32 v144, v144
	v_exp_f32_e32 v145, v145
	v_add_f32_e32 v142, 1.0, v142
	v_add_f32_e32 v143, 1.0, v143
	v_add_f32_e32 v144, 1.0, v144
	v_add_f32_e32 v145, 1.0, v145
	v_rcp_f32_e32 v142, v142
	v_rcp_f32_e32 v143, v143
	v_rcp_f32_e32 v144, v144
	v_rcp_f32_e32 v145, v145
	v_mul_f32_e32 v72, v72, v142
	v_mul_f32_e32 v73, v73, v143
	v_mul_f32_e32 v74, v74, v144
	v_mul_f32_e32 v75, v75, v145
	v_mul_f32_e32 v146, 0xbfb8aa3b, v68
	v_mul_f32_e32 v147, 0xbfb8aa3b, v69
	v_mul_f32_e32 v148, 0xbfb8aa3b, v70
	v_mul_f32_e32 v149, 0xbfb8aa3b, v71
	v_exp_f32_e32 v146, v146
	v_exp_f32_e32 v147, v147
	v_exp_f32_e32 v148, v148
	v_exp_f32_e32 v149, v149
	v_add_f32_e32 v146, 1.0, v146
	v_add_f32_e32 v147, 1.0, v147
	v_add_f32_e32 v148, 1.0, v148
	v_add_f32_e32 v149, 1.0, v149
	v_rcp_f32_e32 v146, v146
	v_rcp_f32_e32 v147, v147
	v_rcp_f32_e32 v148, v148
	v_rcp_f32_e32 v149, v149
	v_mul_f32_e32 v68, v68, v146
	v_mul_f32_e32 v69, v69, v147
	v_mul_f32_e32 v70, v70, v148
	v_mul_f32_e32 v71, v71, v149
	v_mul_f32_e32 v142, 0xbfb8aa3b, v64
	v_mul_f32_e32 v143, 0xbfb8aa3b, v65
	v_mul_f32_e32 v144, 0xbfb8aa3b, v66
	v_mul_f32_e32 v145, 0xbfb8aa3b, v67
	v_exp_f32_e32 v142, v142
	v_exp_f32_e32 v143, v143
	v_exp_f32_e32 v144, v144
	v_exp_f32_e32 v145, v145
	v_add_f32_e32 v142, 1.0, v142
	v_add_f32_e32 v143, 1.0, v143
	v_add_f32_e32 v144, 1.0, v144
	v_add_f32_e32 v145, 1.0, v145
	v_rcp_f32_e32 v142, v142
	v_rcp_f32_e32 v143, v143
	v_rcp_f32_e32 v144, v144
	v_rcp_f32_e32 v145, v145
	v_mul_f32_e32 v64, v64, v142
	v_mul_f32_e32 v65, v65, v143
	v_mul_f32_e32 v66, v66, v144
	v_mul_f32_e32 v67, v67, v145
	v_cvt_pk_bf16_f32 v76, v76, v77
	v_cvt_pk_bf16_f32 v77, v78, v79
	v_cvt_pk_bf16_f32 v78, v72, v73
	v_cvt_pk_bf16_f32 v79, v74, v75
	v_cvt_pk_bf16_f32 v68, v68, v69
	v_cvt_pk_bf16_f32 v69, v70, v71
	v_cvt_pk_bf16_f32 v70, v64, v65
	v_cvt_pk_bf16_f32 v71, v66, v67
	v_permlane16_swap_b32_e32 v76, v78
	v_permlane16_swap_b32_e32 v77, v79
	v_permlane16_swap_b32_e32 v68, v70
	v_permlane16_swap_b32_e32 v69, v71
	global_store_dwordx4 v242, v[76:79], s[98:99]
	global_store_dwordx4 v242, v[68:71], s[98:99] offset:64
	s_add_u32 s98, s98, s7
	s_addc_u32 s99, s99, 0
	v_mul_f32_e32 v146, 0xbfb8aa3b, v60
	v_mul_f32_e32 v147, 0xbfb8aa3b, v61
	v_mul_f32_e32 v148, 0xbfb8aa3b, v62
	v_mul_f32_e32 v149, 0xbfb8aa3b, v63
	v_exp_f32_e32 v146, v146
	v_exp_f32_e32 v147, v147
	v_exp_f32_e32 v148, v148
	v_exp_f32_e32 v149, v149
	v_add_f32_e32 v146, 1.0, v146
	v_add_f32_e32 v147, 1.0, v147
	v_add_f32_e32 v148, 1.0, v148
	v_add_f32_e32 v149, 1.0, v149
	v_rcp_f32_e32 v146, v146
	v_rcp_f32_e32 v147, v147
	v_rcp_f32_e32 v148, v148
	v_rcp_f32_e32 v149, v149
	v_mul_f32_e32 v60, v60, v146
	v_mul_f32_e32 v61, v61, v147
	v_mul_f32_e32 v62, v62, v148
	v_mul_f32_e32 v63, v63, v149
	v_mul_f32_e32 v142, 0xbfb8aa3b, v56
	v_mul_f32_e32 v143, 0xbfb8aa3b, v57
	v_mul_f32_e32 v144, 0xbfb8aa3b, v58
	v_mul_f32_e32 v145, 0xbfb8aa3b, v59
	v_exp_f32_e32 v142, v142
	v_exp_f32_e32 v143, v143
	v_exp_f32_e32 v144, v144
	v_exp_f32_e32 v145, v145
	v_add_f32_e32 v142, 1.0, v142
	v_add_f32_e32 v143, 1.0, v143
	v_add_f32_e32 v144, 1.0, v144
	v_add_f32_e32 v145, 1.0, v145
	v_rcp_f32_e32 v142, v142
	v_rcp_f32_e32 v143, v143
	v_rcp_f32_e32 v144, v144
	v_rcp_f32_e32 v145, v145
	v_mul_f32_e32 v56, v56, v142
	v_mul_f32_e32 v57, v57, v143
	v_mul_f32_e32 v58, v58, v144
	v_mul_f32_e32 v59, v59, v145
	v_mul_f32_e32 v146, 0xbfb8aa3b, v52
	v_mul_f32_e32 v147, 0xbfb8aa3b, v53
	v_mul_f32_e32 v148, 0xbfb8aa3b, v54
	v_mul_f32_e32 v149, 0xbfb8aa3b, v55
	v_exp_f32_e32 v146, v146
	v_exp_f32_e32 v147, v147
	v_exp_f32_e32 v148, v148
	v_exp_f32_e32 v149, v149
	v_add_f32_e32 v146, 1.0, v146
	v_add_f32_e32 v147, 1.0, v147
	v_add_f32_e32 v148, 1.0, v148
	v_add_f32_e32 v149, 1.0, v149
	v_rcp_f32_e32 v146, v146
	v_rcp_f32_e32 v147, v147
	v_rcp_f32_e32 v148, v148
	v_rcp_f32_e32 v149, v149
	v_mul_f32_e32 v52, v52, v146
	v_mul_f32_e32 v53, v53, v147
	v_mul_f32_e32 v54, v54, v148
	v_mul_f32_e32 v55, v55, v149
	v_mul_f32_e32 v142, 0xbfb8aa3b, v48
	v_mul_f32_e32 v143, 0xbfb8aa3b, v49
	v_mul_f32_e32 v144, 0xbfb8aa3b, v50
	v_mul_f32_e32 v145, 0xbfb8aa3b, v51
	v_exp_f32_e32 v142, v142
	v_exp_f32_e32 v143, v143
	v_exp_f32_e32 v144, v144
	v_exp_f32_e32 v145, v145
	v_add_f32_e32 v142, 1.0, v142
	v_add_f32_e32 v143, 1.0, v143
	v_add_f32_e32 v144, 1.0, v144
	v_add_f32_e32 v145, 1.0, v145
	v_rcp_f32_e32 v142, v142
	v_rcp_f32_e32 v143, v143
	v_rcp_f32_e32 v144, v144
	v_rcp_f32_e32 v145, v145
	v_mul_f32_e32 v48, v48, v142
	v_mul_f32_e32 v49, v49, v143
	v_mul_f32_e32 v50, v50, v144
	v_mul_f32_e32 v51, v51, v145
	v_cvt_pk_bf16_f32 v60, v60, v61
	v_cvt_pk_bf16_f32 v61, v62, v63
	v_cvt_pk_bf16_f32 v62, v56, v57
	v_cvt_pk_bf16_f32 v63, v58, v59
	v_cvt_pk_bf16_f32 v52, v52, v53
	v_cvt_pk_bf16_f32 v53, v54, v55
	v_cvt_pk_bf16_f32 v54, v48, v49
	v_cvt_pk_bf16_f32 v55, v50, v51
	v_permlane16_swap_b32_e32 v60, v62
	v_permlane16_swap_b32_e32 v61, v63
	v_permlane16_swap_b32_e32 v52, v54
	v_permlane16_swap_b32_e32 v53, v55
	global_store_dwordx4 v242, v[60:63], s[98:99]
	global_store_dwordx4 v242, v[52:55], s[98:99] offset:64
	s_add_u32 s98, s98, s7
	s_addc_u32 s99, s99, 0
	v_mul_f32_e32 v146, 0xbfb8aa3b, v44
	v_mul_f32_e32 v147, 0xbfb8aa3b, v45
	v_mul_f32_e32 v148, 0xbfb8aa3b, v46
	v_mul_f32_e32 v149, 0xbfb8aa3b, v47
	v_exp_f32_e32 v146, v146
	v_exp_f32_e32 v147, v147
	v_exp_f32_e32 v148, v148
	v_exp_f32_e32 v149, v149
	v_add_f32_e32 v146, 1.0, v146
	v_add_f32_e32 v147, 1.0, v147
	v_add_f32_e32 v148, 1.0, v148
	v_add_f32_e32 v149, 1.0, v149
	v_rcp_f32_e32 v146, v146
	v_rcp_f32_e32 v147, v147
	v_rcp_f32_e32 v148, v148
	v_rcp_f32_e32 v149, v149
	v_mul_f32_e32 v44, v44, v146
	v_mul_f32_e32 v45, v45, v147
	v_mul_f32_e32 v46, v46, v148
	v_mul_f32_e32 v47, v47, v149
	v_mul_f32_e32 v142, 0xbfb8aa3b, v40
	v_mul_f32_e32 v143, 0xbfb8aa3b, v41
	v_mul_f32_e32 v144, 0xbfb8aa3b, v42
	v_mul_f32_e32 v145, 0xbfb8aa3b, v43
	v_exp_f32_e32 v142, v142
	v_exp_f32_e32 v143, v143
	v_exp_f32_e32 v144, v144
	v_exp_f32_e32 v145, v145
	v_add_f32_e32 v142, 1.0, v142
	v_add_f32_e32 v143, 1.0, v143
	v_add_f32_e32 v144, 1.0, v144
	v_add_f32_e32 v145, 1.0, v145
	v_rcp_f32_e32 v142, v142
	v_rcp_f32_e32 v143, v143
	v_rcp_f32_e32 v144, v144
	v_rcp_f32_e32 v145, v145
	v_mul_f32_e32 v40, v40, v142
	v_mul_f32_e32 v41, v41, v143
	v_mul_f32_e32 v42, v42, v144
	v_mul_f32_e32 v43, v43, v145
	v_mul_f32_e32 v146, 0xbfb8aa3b, v36
	v_mul_f32_e32 v147, 0xbfb8aa3b, v37
	v_mul_f32_e32 v148, 0xbfb8aa3b, v38
	v_mul_f32_e32 v149, 0xbfb8aa3b, v39
	v_exp_f32_e32 v146, v146
	v_exp_f32_e32 v147, v147
	v_exp_f32_e32 v148, v148
	v_exp_f32_e32 v149, v149
	v_add_f32_e32 v146, 1.0, v146
	v_add_f32_e32 v147, 1.0, v147
	v_add_f32_e32 v148, 1.0, v148
	v_add_f32_e32 v149, 1.0, v149
	v_rcp_f32_e32 v146, v146
	v_rcp_f32_e32 v147, v147
	v_rcp_f32_e32 v148, v148
	v_rcp_f32_e32 v149, v149
	v_mul_f32_e32 v36, v36, v146
	v_mul_f32_e32 v37, v37, v147
	v_mul_f32_e32 v38, v38, v148
	v_mul_f32_e32 v39, v39, v149
	v_mul_f32_e32 v142, 0xbfb8aa3b, v32
	v_mul_f32_e32 v143, 0xbfb8aa3b, v33
	v_mul_f32_e32 v144, 0xbfb8aa3b, v34
	v_mul_f32_e32 v145, 0xbfb8aa3b, v35
	v_exp_f32_e32 v142, v142
	v_exp_f32_e32 v143, v143
	v_exp_f32_e32 v144, v144
	v_exp_f32_e32 v145, v145
	v_add_f32_e32 v142, 1.0, v142
	v_add_f32_e32 v143, 1.0, v143
	v_add_f32_e32 v144, 1.0, v144
	v_add_f32_e32 v145, 1.0, v145
	v_rcp_f32_e32 v142, v142
	v_rcp_f32_e32 v143, v143
	v_rcp_f32_e32 v144, v144
	v_rcp_f32_e32 v145, v145
	v_mul_f32_e32 v32, v32, v142
	v_mul_f32_e32 v33, v33, v143
	v_mul_f32_e32 v34, v34, v144
	v_mul_f32_e32 v35, v35, v145
	v_cvt_pk_bf16_f32 v44, v44, v45
	v_cvt_pk_bf16_f32 v45, v46, v47
	v_cvt_pk_bf16_f32 v46, v40, v41
	v_cvt_pk_bf16_f32 v47, v42, v43
	v_cvt_pk_bf16_f32 v36, v36, v37
	v_cvt_pk_bf16_f32 v37, v38, v39
	v_cvt_pk_bf16_f32 v38, v32, v33
	v_cvt_pk_bf16_f32 v39, v34, v35
	v_permlane16_swap_b32_e32 v44, v46
	v_permlane16_swap_b32_e32 v45, v47
	v_permlane16_swap_b32_e32 v36, v38
	v_permlane16_swap_b32_e32 v37, v39
	global_store_dwordx4 v242, v[44:47], s[98:99]
	global_store_dwordx4 v242, v[36:39], s[98:99] offset:64
	s_add_u32 s98, s98, s7
	s_addc_u32 s99, s99, 0
	v_mul_f32_e32 v146, 0xbfb8aa3b, v28
	v_mul_f32_e32 v147, 0xbfb8aa3b, v29
	v_mul_f32_e32 v148, 0xbfb8aa3b, v30
	v_mul_f32_e32 v149, 0xbfb8aa3b, v31
	v_exp_f32_e32 v146, v146
	v_exp_f32_e32 v147, v147
	v_exp_f32_e32 v148, v148
	v_exp_f32_e32 v149, v149
	v_add_f32_e32 v146, 1.0, v146
	v_add_f32_e32 v147, 1.0, v147
	v_add_f32_e32 v148, 1.0, v148
	v_add_f32_e32 v149, 1.0, v149
	v_rcp_f32_e32 v146, v146
	v_rcp_f32_e32 v147, v147
	v_rcp_f32_e32 v148, v148
	v_rcp_f32_e32 v149, v149
	v_mul_f32_e32 v28, v28, v146
	v_mul_f32_e32 v29, v29, v147
	v_mul_f32_e32 v30, v30, v148
	v_mul_f32_e32 v31, v31, v149
	v_mul_f32_e32 v142, 0xbfb8aa3b, v24
	v_mul_f32_e32 v143, 0xbfb8aa3b, v25
	v_mul_f32_e32 v144, 0xbfb8aa3b, v26
	v_mul_f32_e32 v145, 0xbfb8aa3b, v27
	v_exp_f32_e32 v142, v142
	v_exp_f32_e32 v143, v143
	v_exp_f32_e32 v144, v144
	v_exp_f32_e32 v145, v145
	v_add_f32_e32 v142, 1.0, v142
	v_add_f32_e32 v143, 1.0, v143
	v_add_f32_e32 v144, 1.0, v144
	v_add_f32_e32 v145, 1.0, v145
	v_rcp_f32_e32 v142, v142
	v_rcp_f32_e32 v143, v143
	v_rcp_f32_e32 v144, v144
	v_rcp_f32_e32 v145, v145
	v_mul_f32_e32 v24, v24, v142
	v_mul_f32_e32 v25, v25, v143
	v_mul_f32_e32 v26, v26, v144
	v_mul_f32_e32 v27, v27, v145
	v_mul_f32_e32 v146, 0xbfb8aa3b, v20
	v_mul_f32_e32 v147, 0xbfb8aa3b, v21
	v_mul_f32_e32 v148, 0xbfb8aa3b, v22
	v_mul_f32_e32 v149, 0xbfb8aa3b, v23
	v_exp_f32_e32 v146, v146
	v_exp_f32_e32 v147, v147
	v_exp_f32_e32 v148, v148
	v_exp_f32_e32 v149, v149
	v_add_f32_e32 v146, 1.0, v146
	v_add_f32_e32 v147, 1.0, v147
	v_add_f32_e32 v148, 1.0, v148
	v_add_f32_e32 v149, 1.0, v149
	v_rcp_f32_e32 v146, v146
	v_rcp_f32_e32 v147, v147
	v_rcp_f32_e32 v148, v148
	v_rcp_f32_e32 v149, v149
	v_mul_f32_e32 v20, v20, v146
	v_mul_f32_e32 v21, v21, v147
	v_mul_f32_e32 v22, v22, v148
	v_mul_f32_e32 v23, v23, v149
	v_mul_f32_e32 v142, 0xbfb8aa3b, v16
	v_mul_f32_e32 v143, 0xbfb8aa3b, v17
	v_mul_f32_e32 v144, 0xbfb8aa3b, v18
	v_mul_f32_e32 v145, 0xbfb8aa3b, v19
	v_exp_f32_e32 v142, v142
	v_exp_f32_e32 v143, v143
	v_exp_f32_e32 v144, v144
	v_exp_f32_e32 v145, v145
	v_add_f32_e32 v142, 1.0, v142
	v_add_f32_e32 v143, 1.0, v143
	v_add_f32_e32 v144, 1.0, v144
	v_add_f32_e32 v145, 1.0, v145
	v_rcp_f32_e32 v142, v142
	v_rcp_f32_e32 v143, v143
	v_rcp_f32_e32 v144, v144
	v_rcp_f32_e32 v145, v145
	v_mul_f32_e32 v16, v16, v142
	v_mul_f32_e32 v17, v17, v143
	v_mul_f32_e32 v18, v18, v144
	v_mul_f32_e32 v19, v19, v145
	v_cvt_pk_bf16_f32 v28, v28, v29
	v_cvt_pk_bf16_f32 v29, v30, v31
	v_cvt_pk_bf16_f32 v30, v24, v25
	v_cvt_pk_bf16_f32 v31, v26, v27
	v_cvt_pk_bf16_f32 v20, v20, v21
	v_cvt_pk_bf16_f32 v21, v22, v23
	v_cvt_pk_bf16_f32 v22, v16, v17
	v_cvt_pk_bf16_f32 v23, v18, v19
	v_permlane16_swap_b32_e32 v28, v30
	v_permlane16_swap_b32_e32 v29, v31
	v_permlane16_swap_b32_e32 v20, v22
	v_permlane16_swap_b32_e32 v21, v23
	global_store_dwordx4 v242, v[28:31], s[98:99]
	global_store_dwordx4 v242, v[20:23], s[98:99] offset:64
	s_add_u32 s98, s98, s7
	s_addc_u32 s99, s99, 0
	v_mul_f32_e32 v146, 0xbfb8aa3b, v12
	v_mul_f32_e32 v147, 0xbfb8aa3b, v13
	v_mul_f32_e32 v148, 0xbfb8aa3b, v14
	v_mul_f32_e32 v149, 0xbfb8aa3b, v15
	v_exp_f32_e32 v146, v146
	v_exp_f32_e32 v147, v147
	v_exp_f32_e32 v148, v148
	v_exp_f32_e32 v149, v149
	v_add_f32_e32 v146, 1.0, v146
	v_add_f32_e32 v147, 1.0, v147
	v_add_f32_e32 v148, 1.0, v148
	v_add_f32_e32 v149, 1.0, v149
	v_rcp_f32_e32 v146, v146
	v_rcp_f32_e32 v147, v147
	v_rcp_f32_e32 v148, v148
	v_rcp_f32_e32 v149, v149
	v_mul_f32_e32 v12, v12, v146
	v_mul_f32_e32 v13, v13, v147
	v_mul_f32_e32 v14, v14, v148
	v_mul_f32_e32 v15, v15, v149
	v_mul_f32_e32 v142, 0xbfb8aa3b, v8
	v_mul_f32_e32 v143, 0xbfb8aa3b, v9
	v_mul_f32_e32 v144, 0xbfb8aa3b, v10
	v_mul_f32_e32 v145, 0xbfb8aa3b, v11
	v_exp_f32_e32 v142, v142
	v_exp_f32_e32 v143, v143
	v_exp_f32_e32 v144, v144
	v_exp_f32_e32 v145, v145
	v_add_f32_e32 v142, 1.0, v142
	v_add_f32_e32 v143, 1.0, v143
	v_add_f32_e32 v144, 1.0, v144
	v_add_f32_e32 v145, 1.0, v145
	v_rcp_f32_e32 v142, v142
	v_rcp_f32_e32 v143, v143
	v_rcp_f32_e32 v144, v144
	v_rcp_f32_e32 v145, v145
	v_mul_f32_e32 v8, v8, v142
	v_mul_f32_e32 v9, v9, v143
	v_mul_f32_e32 v10, v10, v144
	v_mul_f32_e32 v11, v11, v145
	v_mul_f32_e32 v146, 0xbfb8aa3b, v4
	v_mul_f32_e32 v147, 0xbfb8aa3b, v5
	v_mul_f32_e32 v148, 0xbfb8aa3b, v6
	v_mul_f32_e32 v149, 0xbfb8aa3b, v7
	v_exp_f32_e32 v146, v146
	v_exp_f32_e32 v147, v147
	v_exp_f32_e32 v148, v148
	v_exp_f32_e32 v149, v149
	v_add_f32_e32 v146, 1.0, v146
	v_add_f32_e32 v147, 1.0, v147
	v_add_f32_e32 v148, 1.0, v148
	v_add_f32_e32 v149, 1.0, v149
	v_rcp_f32_e32 v146, v146
	v_rcp_f32_e32 v147, v147
	v_rcp_f32_e32 v148, v148
	v_rcp_f32_e32 v149, v149
	v_mul_f32_e32 v4, v4, v146
	v_mul_f32_e32 v5, v5, v147
	v_mul_f32_e32 v6, v6, v148
	v_mul_f32_e32 v7, v7, v149
	v_mul_f32_e32 v142, 0xbfb8aa3b, v0
	v_mul_f32_e32 v143, 0xbfb8aa3b, v1
	v_mul_f32_e32 v144, 0xbfb8aa3b, v2
	v_mul_f32_e32 v145, 0xbfb8aa3b, v3
	v_exp_f32_e32 v142, v142
	v_exp_f32_e32 v143, v143
	v_exp_f32_e32 v144, v144
	v_exp_f32_e32 v145, v145
	v_add_f32_e32 v142, 1.0, v142
	v_add_f32_e32 v143, 1.0, v143
	v_add_f32_e32 v144, 1.0, v144
	v_add_f32_e32 v145, 1.0, v145
	v_rcp_f32_e32 v142, v142
	v_rcp_f32_e32 v143, v143
	v_rcp_f32_e32 v144, v144
	v_rcp_f32_e32 v145, v145
	v_mul_f32_e32 v0, v0, v142
	v_mul_f32_e32 v1, v1, v143
	v_mul_f32_e32 v2, v2, v144
	v_mul_f32_e32 v3, v3, v145
	v_cvt_pk_bf16_f32 v12, v12, v13
	v_cvt_pk_bf16_f32 v13, v14, v15
	v_cvt_pk_bf16_f32 v14, v8, v9
	v_cvt_pk_bf16_f32 v15, v10, v11
	v_cvt_pk_bf16_f32 v4, v4, v5
	v_cvt_pk_bf16_f32 v5, v6, v7
	v_cvt_pk_bf16_f32 v6, v0, v1
	v_cvt_pk_bf16_f32 v7, v2, v3
	v_permlane16_swap_b32_e32 v12, v14
	v_permlane16_swap_b32_e32 v13, v15
	v_permlane16_swap_b32_e32 v4, v6
	v_permlane16_swap_b32_e32 v5, v7
	global_store_dwordx4 v242, v[12:15], s[98:99]
	global_store_dwordx4 v242, v[4:7], s[98:99] offset:64
	s_mov_b64 s[8:9], -1
	s_and_b64 vcc, exec, s[36:37]
	s_cbranch_vccnz .LBB0_1435
	s_branch .LBB0_1232
.Lepi13_store:
	v_cvt_pk_bf16_f32 v124, v124, v125
	v_cvt_pk_bf16_f32 v125, v126, v127
	v_cvt_pk_bf16_f32 v126, v120, v121
	v_cvt_pk_bf16_f32 v127, v122, v123
	v_cvt_pk_bf16_f32 v116, v116, v117
	v_cvt_pk_bf16_f32 v117, v118, v119
	v_cvt_pk_bf16_f32 v118, v112, v113
	v_cvt_pk_bf16_f32 v119, v114, v115
	v_permlane16_swap_b32_e32 v124, v126
	v_permlane16_swap_b32_e32 v125, v127
	v_permlane16_swap_b32_e32 v116, v118
	v_permlane16_swap_b32_e32 v117, v119
	global_store_dwordx4 v242, v[124:127], s[98:99]
	global_store_dwordx4 v242, v[116:119], s[98:99] offset:64
	s_add_u32 s98, s98, s7
	s_addc_u32 s99, s99, 0
	v_cvt_pk_bf16_f32 v108, v108, v109
	v_cvt_pk_bf16_f32 v109, v110, v111
	v_cvt_pk_bf16_f32 v110, v104, v105
	v_cvt_pk_bf16_f32 v111, v106, v107
	v_cvt_pk_bf16_f32 v100, v100, v101
	v_cvt_pk_bf16_f32 v101, v102, v103
	v_cvt_pk_bf16_f32 v102, v96, v97
	v_cvt_pk_bf16_f32 v103, v98, v99
	v_permlane16_swap_b32_e32 v108, v110
	v_permlane16_swap_b32_e32 v109, v111
	v_permlane16_swap_b32_e32 v100, v102
	v_permlane16_swap_b32_e32 v101, v103
	global_store_dwordx4 v242, v[108:111], s[98:99]
	global_store_dwordx4 v242, v[100:103], s[98:99] offset:64
	s_add_u32 s98, s98, s7
	s_addc_u32 s99, s99, 0
	v_cvt_pk_bf16_f32 v92, v92, v93
	v_cvt_pk_bf16_f32 v93, v94, v95
	v_cvt_pk_bf16_f32 v94, v88, v89
	v_cvt_pk_bf16_f32 v95, v90, v91
	v_cvt_pk_bf16_f32 v84, v84, v85
	v_cvt_pk_bf16_f32 v85, v86, v87
	v_cvt_pk_bf16_f32 v86, v80, v81
	v_cvt_pk_bf16_f32 v87, v82, v83
	v_permlane16_swap_b32_e32 v92, v94
	v_permlane16_swap_b32_e32 v93, v95
	v_permlane16_swap_b32_e32 v84, v86
	v_permlane16_swap_b32_e32 v85, v87
	global_store_dwordx4 v242, v[92:95], s[98:99]
	global_store_dwordx4 v242, v[84:87], s[98:99] offset:64
	s_add_u32 s98, s98, s7
	s_addc_u32 s99, s99, 0
	v_cvt_pk_bf16_f32 v76, v76, v77
	v_cvt_pk_bf16_f32 v77, v78, v79
	v_cvt_pk_bf16_f32 v78, v72, v73
	v_cvt_pk_bf16_f32 v79, v74, v75
	v_cvt_pk_bf16_f32 v68, v68, v69
	v_cvt_pk_bf16_f32 v69, v70, v71
	v_cvt_pk_bf16_f32 v70, v64, v65
	v_cvt_pk_bf16_f32 v71, v66, v67
	v_permlane16_swap_b32_e32 v76, v78
	v_permlane16_swap_b32_e32 v77, v79
	v_permlane16_swap_b32_e32 v68, v70
	v_permlane16_swap_b32_e32 v69, v71
	global_store_dwordx4 v242, v[76:79], s[98:99]
	global_store_dwordx4 v242, v[68:71], s[98:99] offset:64
	s_add_u32 s98, s98, s7
	s_addc_u32 s99, s99, 0
	v_cvt_pk_bf16_f32 v60, v60, v61
	v_cvt_pk_bf16_f32 v61, v62, v63
	v_cvt_pk_bf16_f32 v62, v56, v57
	v_cvt_pk_bf16_f32 v63, v58, v59
	v_cvt_pk_bf16_f32 v52, v52, v53
	v_cvt_pk_bf16_f32 v53, v54, v55
	v_cvt_pk_bf16_f32 v54, v48, v49
	v_cvt_pk_bf16_f32 v55, v50, v51
	v_permlane16_swap_b32_e32 v60, v62
	v_permlane16_swap_b32_e32 v61, v63
	v_permlane16_swap_b32_e32 v52, v54
	v_permlane16_swap_b32_e32 v53, v55
	global_store_dwordx4 v242, v[60:63], s[98:99]
	global_store_dwordx4 v242, v[52:55], s[98:99] offset:64
	s_add_u32 s98, s98, s7
	s_addc_u32 s99, s99, 0
	v_cvt_pk_bf16_f32 v44, v44, v45
	v_cvt_pk_bf16_f32 v45, v46, v47
	v_cvt_pk_bf16_f32 v46, v40, v41
	v_cvt_pk_bf16_f32 v47, v42, v43
	v_cvt_pk_bf16_f32 v36, v36, v37
	v_cvt_pk_bf16_f32 v37, v38, v39
	v_cvt_pk_bf16_f32 v38, v32, v33
	v_cvt_pk_bf16_f32 v39, v34, v35
	v_permlane16_swap_b32_e32 v44, v46
	v_permlane16_swap_b32_e32 v45, v47
	v_permlane16_swap_b32_e32 v36, v38
	v_permlane16_swap_b32_e32 v37, v39
	global_store_dwordx4 v242, v[44:47], s[98:99]
	global_store_dwordx4 v242, v[36:39], s[98:99] offset:64
	s_add_u32 s98, s98, s7
	s_addc_u32 s99, s99, 0
	v_cvt_pk_bf16_f32 v28, v28, v29
	v_cvt_pk_bf16_f32 v29, v30, v31
	v_cvt_pk_bf16_f32 v30, v24, v25
	v_cvt_pk_bf16_f32 v31, v26, v27
	v_cvt_pk_bf16_f32 v20, v20, v21
	v_cvt_pk_bf16_f32 v21, v22, v23
	v_cvt_pk_bf16_f32 v22, v16, v17
	v_cvt_pk_bf16_f32 v23, v18, v19
	v_permlane16_swap_b32_e32 v28, v30
	v_permlane16_swap_b32_e32 v29, v31
	v_permlane16_swap_b32_e32 v20, v22
	v_permlane16_swap_b32_e32 v21, v23
	global_store_dwordx4 v242, v[28:31], s[98:99]
	global_store_dwordx4 v242, v[20:23], s[98:99] offset:64
	s_add_u32 s98, s98, s7
	s_addc_u32 s99, s99, 0
	v_cvt_pk_bf16_f32 v12, v12, v13
	v_cvt_pk_bf16_f32 v13, v14, v15
	v_cvt_pk_bf16_f32 v14, v8, v9
	v_cvt_pk_bf16_f32 v15, v10, v11
	v_cvt_pk_bf16_f32 v4, v4, v5
	v_cvt_pk_bf16_f32 v5, v6, v7
	v_cvt_pk_bf16_f32 v6, v0, v1
	v_cvt_pk_bf16_f32 v7, v2, v3
	v_permlane16_swap_b32_e32 v12, v14
	v_permlane16_swap_b32_e32 v13, v15
	v_permlane16_swap_b32_e32 v4, v6
	v_permlane16_swap_b32_e32 v5, v7
	global_store_dwordx4 v242, v[12:15], s[98:99]
	global_store_dwordx4 v242, v[4:7], s[98:99] offset:64
	s_mov_b64 s[8:9], -1
	s_and_b64 vcc, exec, s[36:37]
	s_cbranch_vccnz .LBB0_1435
	s_branch .LBB0_1232

.LBB0_1617:
	v_readfirstlane_b32 s100, v178
	s_nop 0
	s_lshr_b32 s100, s100, 6
	s_lshr_b32 s101, s100, 2
	s_and_b32 s100, s100, 3
	s_lshl_b32 s101, s101, 7
	s_add_i32 s101, s101, s36
	s_lshl_b32 s100, s100, 6
	s_mov_b32 s7, 0x8000
	s_mov_b32 s2, 11
	v_and_b32_e32 v242, 15, v178
	v_bfe_u32 v243, v178, 4, 1
	v_lshlrev_b32_e32 v242, s2, v242
	v_lshl_add_u32 v242, v243, 5, v242
	v_bfe_u32 v243, v178, 5, 1
	s_nop 0
	v_lshl_add_u32 v242, v243, 4, v242
	s_mov_b32 s6, s54
	s_cmpk_ge_u32 s58, 0xc00
	s_cbranch_scc1 .Lepi19_gate
	s_cmpk_ge_u32 s58, 0x400
	s_cbranch_scc1 .Lepi19_k
	s_add_i32 s3, s58, s100
	s_lshl_b32 s3, s3, 1
	s_lshl_b32 s5, s101, 11
	s_add_u32 s3, s3, s5
	s_add_u32 s98, s68, s3
	s_addc_u32 s99, s69, 0
	s_cmpk_ge_u32 s36, 0x2000
	s_cbranch_scc1 .Lepi19_qrope
	v_pk_mul_f32 v[124:125], v[124:125], s[6:7] op_sel_hi:[1,0]
	v_pk_mul_f32 v[126:127], v[126:127], s[6:7] op_sel_hi:[1,0]
	v_pk_mul_f32 v[120:121], v[120:121], s[6:7] op_sel_hi:[1,0]
	v_pk_mul_f32 v[122:123], v[122:123], s[6:7] op_sel_hi:[1,0]
	v_pk_mul_f32 v[116:117], v[116:117], s[6:7] op_sel_hi:[1,0]
	v_pk_mul_f32 v[118:119], v[118:119], s[6:7] op_sel_hi:[1,0]
	v_pk_mul_f32 v[112:113], v[112:113], s[6:7] op_sel_hi:[1,0]
	v_pk_mul_f32 v[114:115], v[114:115], s[6:7] op_sel_hi:[1,0]
	v_cvt_pk_bf16_f32 v124, v124, v125
	v_cvt_pk_bf16_f32 v125, v126, v127
	v_cvt_pk_bf16_f32 v126, v120, v121
	v_cvt_pk_bf16_f32 v127, v122, v123
	v_cvt_pk_bf16_f32 v116, v116, v117
	v_cvt_pk_bf16_f32 v117, v118, v119
	v_cvt_pk_bf16_f32 v118, v112, v113
	v_cvt_pk_bf16_f32 v119, v114, v115
	v_permlane16_swap_b32_e32 v124, v126
	v_permlane16_swap_b32_e32 v125, v127
	v_permlane16_swap_b32_e32 v116, v118
	v_permlane16_swap_b32_e32 v117, v119
	global_store_dwordx4 v242, v[124:127], s[98:99]
	global_store_dwordx4 v242, v[116:119], s[98:99] offset:64
	s_add_u32 s98, s98, s7
	s_addc_u32 s99, s99, 0
	v_pk_mul_f32 v[108:109], v[108:109], s[6:7] op_sel_hi:[1,0]
	v_pk_mul_f32 v[110:111], v[110:111], s[6:7] op_sel_hi:[1,0]
	v_pk_mul_f32 v[104:105], v[104:105], s[6:7] op_sel_hi:[1,0]
	v_pk_mul_f32 v[106:107], v[106:107], s[6:7] op_sel_hi:[1,0]
	v_pk_mul_f32 v[100:101], v[100:101], s[6:7] op_sel_hi:[1,0]
	v_pk_mul_f32 v[102:103], v[102:103], s[6:7] op_sel_hi:[1,0]
	v_pk_mul_f32 v[96:97], v[96:97], s[6:7] op_sel_hi:[1,0]
	v_pk_mul_f32 v[98:99], v[98:99], s[6:7] op_sel_hi:[1,0]
	v_cvt_pk_bf16_f32 v108, v108, v109
	v_cvt_pk_bf16_f32 v109, v110, v111
	v_cvt_pk_bf16_f32 v110, v104, v105
	v_cvt_pk_bf16_f32 v111, v106, v107
	v_cvt_pk_bf16_f32 v100, v100, v101
	v_cvt_pk_bf16_f32 v101, v102, v103
	v_cvt_pk_bf16_f32 v102, v96, v97
	v_cvt_pk_bf16_f32 v103, v98, v99
	v_permlane16_swap_b32_e32 v108, v110
	v_permlane16_swap_b32_e32 v109, v111
	v_permlane16_swap_b32_e32 v100, v102
	v_permlane16_swap_b32_e32 v101, v103
	global_store_dwordx4 v242, v[108:111], s[98:99]
	global_store_dwordx4 v242, v[100:103], s[98:99] offset:64
	s_add_u32 s98, s98, s7
	s_addc_u32 s99, s99, 0
	v_pk_mul_f32 v[92:93], v[92:93], s[6:7] op_sel_hi:[1,0]
	v_pk_mul_f32 v[94:95], v[94:95], s[6:7] op_sel_hi:[1,0]
	v_pk_mul_f32 v[88:89], v[88:89], s[6:7] op_sel_hi:[1,0]
	v_pk_mul_f32 v[90:91], v[90:91], s[6:7] op_sel_hi:[1,0]
	v_pk_mul_f32 v[84:85], v[84:85], s[6:7] op_sel_hi:[1,0]
	v_pk_mul_f32 v[86:87], v[86:87], s[6:7] op_sel_hi:[1,0]
	v_pk_mul_f32 v[80:81], v[80:81], s[6:7] op_sel_hi:[1,0]
	v_pk_mul_f32 v[82:83], v[82:83], s[6:7] op_sel_hi:[1,0]
	v_cvt_pk_bf16_f32 v92, v92, v93
	v_cvt_pk_bf16_f32 v93, v94, v95
	v_cvt_pk_bf16_f32 v94, v88, v89
	v_cvt_pk_bf16_f32 v95, v90, v91
	v_cvt_pk_bf16_f32 v84, v84, v85
	v_cvt_pk_bf16_f32 v85, v86, v87
	v_cvt_pk_bf16_f32 v86, v80, v81
	v_cvt_pk_bf16_f32 v87, v82, v83
	v_permlane16_swap_b32_e32 v92, v94
	v_permlane16_swap_b32_e32 v93, v95
	v_permlane16_swap_b32_e32 v84, v86
	v_permlane16_swap_b32_e32 v85, v87
	global_store_dwordx4 v242, v[92:95], s[98:99]
	global_store_dwordx4 v242, v[84:87], s[98:99] offset:64
	s_add_u32 s98, s98, s7
	s_addc_u32 s99, s99, 0
	v_pk_mul_f32 v[76:77], v[76:77], s[6:7] op_sel_hi:[1,0]
	v_pk_mul_f32 v[78:79], v[78:79], s[6:7] op_sel_hi:[1,0]
	v_pk_mul_f32 v[72:73], v[72:73], s[6:7] op_sel_hi:[1,0]
	v_pk_mul_f32 v[74:75], v[74:75], s[6:7] op_sel_hi:[1,0]
	v_pk_mul_f32 v[68:69], v[68:69], s[6:7] op_sel_hi:[1,0]
	v_pk_mul_f32 v[70:71], v[70:71], s[6:7] op_sel_hi:[1,0]
	v_pk_mul_f32 v[64:65], v[64:65], s[6:7] op_sel_hi:[1,0]
	v_pk_mul_f32 v[66:67], v[66:67], s[6:7] op_sel_hi:[1,0]
	v_cvt_pk_bf16_f32 v76, v76, v77
	v_cvt_pk_bf16_f32 v77, v78, v79
	v_cvt_pk_bf16_f32 v78, v72, v73
	v_cvt_pk_bf16_f32 v79, v74, v75
	v_cvt_pk_bf16_f32 v68, v68, v69
	v_cvt_pk_bf16_f32 v69, v70, v71
	v_cvt_pk_bf16_f32 v70, v64, v65
	v_cvt_pk_bf16_f32 v71, v66, v67
	v_permlane16_swap_b32_e32 v76, v78
	v_permlane16_swap_b32_e32 v77, v79
	v_permlane16_swap_b32_e32 v68, v70
	v_permlane16_swap_b32_e32 v69, v71
	global_store_dwordx4 v242, v[76:79], s[98:99]
	global_store_dwordx4 v242, v[68:71], s[98:99] offset:64
	s_add_u32 s98, s98, s7
	s_addc_u32 s99, s99, 0
	v_pk_mul_f32 v[60:61], v[60:61], s[6:7] op_sel_hi:[1,0]
	v_pk_mul_f32 v[62:63], v[62:63], s[6:7] op_sel_hi:[1,0]
	v_pk_mul_f32 v[56:57], v[56:57], s[6:7] op_sel_hi:[1,0]
	v_pk_mul_f32 v[58:59], v[58:59], s[6:7] op_sel_hi:[1,0]
	v_pk_mul_f32 v[52:53], v[52:53], s[6:7] op_sel_hi:[1,0]
	v_pk_mul_f32 v[54:55], v[54:55], s[6:7] op_sel_hi:[1,0]
	v_pk_mul_f32 v[48:49], v[48:49], s[6:7] op_sel_hi:[1,0]
	v_pk_mul_f32 v[50:51], v[50:51], s[6:7] op_sel_hi:[1,0]
	v_cvt_pk_bf16_f32 v60, v60, v61
	v_cvt_pk_bf16_f32 v61, v62, v63
	v_cvt_pk_bf16_f32 v62, v56, v57
	v_cvt_pk_bf16_f32 v63, v58, v59
	v_cvt_pk_bf16_f32 v52, v52, v53
	v_cvt_pk_bf16_f32 v53, v54, v55
	v_cvt_pk_bf16_f32 v54, v48, v49
	v_cvt_pk_bf16_f32 v55, v50, v51
	v_permlane16_swap_b32_e32 v60, v62
	v_permlane16_swap_b32_e32 v61, v63
	v_permlane16_swap_b32_e32 v52, v54
	v_permlane16_swap_b32_e32 v53, v55
	global_store_dwordx4 v242, v[60:63], s[98:99]
	global_store_dwordx4 v242, v[52:55], s[98:99] offset:64
	s_add_u32 s98, s98, s7
	s_addc_u32 s99, s99, 0
	v_pk_mul_f32 v[44:45], v[44:45], s[6:7] op_sel_hi:[1,0]
	v_pk_mul_f32 v[46:47], v[46:47], s[6:7] op_sel_hi:[1,0]
	v_pk_mul_f32 v[40:41], v[40:41], s[6:7] op_sel_hi:[1,0]
	v_pk_mul_f32 v[42:43], v[42:43], s[6:7] op_sel_hi:[1,0]
	v_pk_mul_f32 v[36:37], v[36:37], s[6:7] op_sel_hi:[1,0]
	v_pk_mul_f32 v[38:39], v[38:39], s[6:7] op_sel_hi:[1,0]
	v_pk_mul_f32 v[32:33], v[32:33], s[6:7] op_sel_hi:[1,0]
	v_pk_mul_f32 v[34:35], v[34:35], s[6:7] op_sel_hi:[1,0]
	v_cvt_pk_bf16_f32 v44, v44, v45
	v_cvt_pk_bf16_f32 v45, v46, v47
	v_cvt_pk_bf16_f32 v46, v40, v41
	v_cvt_pk_bf16_f32 v47, v42, v43
	v_cvt_pk_bf16_f32 v36, v36, v37
	v_cvt_pk_bf16_f32 v37, v38, v39
	v_cvt_pk_bf16_f32 v38, v32, v33
	v_cvt_pk_bf16_f32 v39, v34, v35
	v_permlane16_swap_b32_e32 v44, v46
	v_permlane16_swap_b32_e32 v45, v47
	v_permlane16_swap_b32_e32 v36, v38
	v_permlane16_swap_b32_e32 v37, v39
	global_store_dwordx4 v242, v[44:47], s[98:99]
	global_store_dwordx4 v242, v[36:39], s[98:99] offset:64
	s_add_u32 s98, s98, s7
	s_addc_u32 s99, s99, 0
	v_pk_mul_f32 v[28:29], v[28:29], s[6:7] op_sel_hi:[1,0]
	v_pk_mul_f32 v[30:31], v[30:31], s[6:7] op_sel_hi:[1,0]
	v_pk_mul_f32 v[24:25], v[24:25], s[6:7] op_sel_hi:[1,0]
	v_pk_mul_f32 v[26:27], v[26:27], s[6:7] op_sel_hi:[1,0]
	v_pk_mul_f32 v[20:21], v[20:21], s[6:7] op_sel_hi:[1,0]
	v_pk_mul_f32 v[22:23], v[22:23], s[6:7] op_sel_hi:[1,0]
	v_pk_mul_f32 v[16:17], v[16:17], s[6:7] op_sel_hi:[1,0]
	v_pk_mul_f32 v[18:19], v[18:19], s[6:7] op_sel_hi:[1,0]
	v_cvt_pk_bf16_f32 v28, v28, v29
	v_cvt_pk_bf16_f32 v29, v30, v31
	v_cvt_pk_bf16_f32 v30, v24, v25
	v_cvt_pk_bf16_f32 v31, v26, v27
	v_cvt_pk_bf16_f32 v20, v20, v21
	v_cvt_pk_bf16_f32 v21, v22, v23
	v_cvt_pk_bf16_f32 v22, v16, v17
	v_cvt_pk_bf16_f32 v23, v18, v19
	v_permlane16_swap_b32_e32 v28, v30
	v_permlane16_swap_b32_e32 v29, v31
	v_permlane16_swap_b32_e32 v20, v22
	v_permlane16_swap_b32_e32 v21, v23
	global_store_dwordx4 v242, v[28:31], s[98:99]
	global_store_dwordx4 v242, v[20:23], s[98:99] offset:64
	s_add_u32 s98, s98, s7
	s_addc_u32 s99, s99, 0
	v_pk_mul_f32 v[12:13], v[12:13], s[6:7] op_sel_hi:[1,0]
	v_pk_mul_f32 v[14:15], v[14:15], s[6:7] op_sel_hi:[1,0]
	v_pk_mul_f32 v[8:9], v[8:9], s[6:7] op_sel_hi:[1,0]
	v_pk_mul_f32 v[10:11], v[10:11], s[6:7] op_sel_hi:[1,0]
	v_pk_mul_f32 v[4:5], v[4:5], s[6:7] op_sel_hi:[1,0]
	v_pk_mul_f32 v[6:7], v[6:7], s[6:7] op_sel_hi:[1,0]
	v_pk_mul_f32 v[0:1], v[0:1], s[6:7] op_sel_hi:[1,0]
	v_pk_mul_f32 v[2:3], v[2:3], s[6:7] op_sel_hi:[1,0]
	v_cvt_pk_bf16_f32 v12, v12, v13
	v_cvt_pk_bf16_f32 v13, v14, v15
	v_cvt_pk_bf16_f32 v14, v8, v9
	v_cvt_pk_bf16_f32 v15, v10, v11
	v_cvt_pk_bf16_f32 v4, v4, v5
	v_cvt_pk_bf16_f32 v5, v6, v7
	v_cvt_pk_bf16_f32 v6, v0, v1
	v_cvt_pk_bf16_f32 v7, v2, v3
	v_permlane16_swap_b32_e32 v12, v14
	v_permlane16_swap_b32_e32 v13, v15
	v_permlane16_swap_b32_e32 v4, v6
	v_permlane16_swap_b32_e32 v5, v7
	global_store_dwordx4 v242, v[12:15], s[98:99]
	global_store_dwordx4 v242, v[4:7], s[98:99] offset:64
	s_branch .LBB0_1600
.Lepi19_qrope:
	s_sub_i32 s3, s101, 0x2000
	s_and_b32 s3, s3, 0x7ff
	s_lshl_b32 s3, s3, 8
	s_add_u32 s2, s16, s3
	s_addc_u32 s3, s17, 0
	v_and_b32_e32 v243, 15, v178
	v_bfe_u32 v244, v178, 4, 2
	v_lshlrev_b32_e32 v243, 8, v243
	v_lshl_add_u32 v243, v244, 4, v243
	global_load_dwordx4 v[150:153], v243, s[2:3]
	global_load_dwordx4 v[196:199], v243, s[2:3] offset:64
	global_load_dwordx4 v[200:203], v243, s[2:3] offset:128
	global_load_dwordx4 v[204:207], v243, s[2:3] offset:192
	s_add_u32 s2, s2, 0x1000
	s_addc_u32 s3, s3, 0
	global_load_dwordx4 v[142:145], v243, s[2:3]
	global_load_dwordx4 v[246:249], v243, s[2:3] offset:64
	global_load_dwordx4 v[250:253], v243, s[2:3] offset:128
	s_waitcnt vmcnt(6)
	v_mul_f32_e32 v244, v125, v151
	v_mul_f32_e32 v245, v124, v151
	v_mul_f32_e32 v124, v124, v150
	v_fma_f32 v125, v125, v150, v245
	v_sub_f32_e32 v124, v124, v244
	v_mul_f32_e32 v244, v127, v153
	v_mul_f32_e32 v245, v126, v153
	v_fma_f32 v126, v126, v152, -v244
	v_fma_f32 v127, v127, v152, v245
	v_pk_mul_f32 v[124:125], v[124:125], s[6:7] op_sel_hi:[1,0]
	v_pk_mul_f32 v[126:127], v[126:127], s[6:7] op_sel_hi:[1,0]
	global_load_dwordx4 v[150:153], v243, s[2:3] offset:192
	s_waitcnt vmcnt(6)
	v_mul_f32_e32 v244, v121, v197
	v_mul_f32_e32 v245, v120, v197
	v_mul_f32_e32 v120, v120, v196
	v_fma_f32 v121, v121, v196, v245
	v_sub_f32_e32 v120, v120, v244
	v_mul_f32_e32 v244, v123, v199
	v_mul_f32_e32 v245, v122, v199
	v_fma_f32 v122, v122, v198, -v244
	v_fma_f32 v123, v123, v198, v245
	v_pk_mul_f32 v[120:121], v[120:121], s[6:7] op_sel_hi:[1,0]
	v_pk_mul_f32 v[122:123], v[122:123], s[6:7] op_sel_hi:[1,0]
	s_add_u32 s2, s2, 0x1000
	s_addc_u32 s3, s3, 0
	global_load_dwordx4 v[196:199], v243, s[2:3]
	s_waitcnt vmcnt(6)
	v_mul_f32_e32 v244, v117, v201
	v_mul_f32_e32 v245, v116, v201
	v_mul_f32_e32 v116, v116, v200
	v_fma_f32 v117, v117, v200, v245
	v_sub_f32_e32 v116, v116, v244
	v_mul_f32_e32 v244, v119, v203
	v_mul_f32_e32 v245, v118, v203
	v_fma_f32 v118, v118, v202, -v244
	v_fma_f32 v119, v119, v202, v245
	v_pk_mul_f32 v[116:117], v[116:117], s[6:7] op_sel_hi:[1,0]
	v_pk_mul_f32 v[118:119], v[118:119], s[6:7] op_sel_hi:[1,0]
	global_load_dwordx4 v[200:203], v243, s[2:3] offset:64
	s_waitcnt vmcnt(6)
	v_mul_f32_e32 v244, v113, v205
	v_mul_f32_e32 v245, v112, v205
	v_mul_f32_e32 v112, v112, v204
	v_fma_f32 v113, v113, v204, v245
	v_sub_f32_e32 v112, v112, v244
	v_mul_f32_e32 v244, v115, v207
	v_mul_f32_e32 v245, v114, v207
	v_fma_f32 v114, v114, v206, -v244
	v_fma_f32 v115, v115, v206, v245
	v_pk_mul_f32 v[112:113], v[112:113], s[6:7] op_sel_hi:[1,0]
	v_pk_mul_f32 v[114:115], v[114:115], s[6:7] op_sel_hi:[1,0]
	v_cvt_pk_bf16_f32 v124, v124, v125
	v_cvt_pk_bf16_f32 v125, v126, v127
	v_cvt_pk_bf16_f32 v126, v120, v121
	v_cvt_pk_bf16_f32 v127, v122, v123
	v_cvt_pk_bf16_f32 v116, v116, v117
	v_cvt_pk_bf16_f32 v117, v118, v119
	v_cvt_pk_bf16_f32 v118, v112, v113
	v_cvt_pk_bf16_f32 v119, v114, v115
	v_permlane16_swap_b32_e32 v124, v126
	v_permlane16_swap_b32_e32 v125, v127
	v_permlane16_swap_b32_e32 v116, v118
	v_permlane16_swap_b32_e32 v117, v119
	global_store_dwordx4 v242, v[124:127], s[98:99]
	global_store_dwordx4 v242, v[116:119], s[98:99] offset:64
	s_add_u32 s98, s98, s7
	s_addc_u32 s99, s99, 0
	global_load_dwordx4 v[204:207], v243, s[2:3] offset:128
	s_waitcnt vmcnt(8)
	v_mul_f32_e32 v244, v109, v143
	v_mul_f32_e32 v245, v108, v143
	v_mul_f32_e32 v108, v108, v142
	v_fma_f32 v109, v109, v142, v245
	v_sub_f32_e32 v108, v108, v244
	v_mul_f32_e32 v244, v111, v145
	v_mul_f32_e32 v245, v110, v145
	v_fma_f32 v110, v110, v144, -v244
	v_fma_f32 v111, v111, v144, v245
	v_pk_mul_f32 v[108:109], v[108:109], s[6:7] op_sel_hi:[1,0]
	v_pk_mul_f32 v[110:111], v[110:111], s[6:7] op_sel_hi:[1,0]
	global_load_dwordx4 v[142:145], v243, s[2:3] offset:192
	s_waitcnt vmcnt(8)
	v_mul_f32_e32 v244, v105, v247
	v_mul_f32_e32 v245, v104, v247
	v_mul_f32_e32 v104, v104, v246
	v_fma_f32 v105, v105, v246, v245
	v_sub_f32_e32 v104, v104, v244
	v_mul_f32_e32 v244, v107, v249
	v_mul_f32_e32 v245, v106, v249
	v_fma_f32 v106, v106, v248, -v244
	v_fma_f32 v107, v107, v248, v245
	v_pk_mul_f32 v[104:105], v[104:105], s[6:7] op_sel_hi:[1,0]
	v_pk_mul_f32 v[106:107], v[106:107], s[6:7] op_sel_hi:[1,0]
	s_add_u32 s2, s2, 0x1000
	s_addc_u32 s3, s3, 0
	global_load_dwordx4 v[246:249], v243, s[2:3]
	s_waitcnt vmcnt(8)
	v_mul_f32_e32 v244, v101, v251
	v_mul_f32_e32 v245, v100, v251
	v_mul_f32_e32 v100, v100, v250
	v_fma_f32 v101, v101, v250, v245
	v_sub_f32_e32 v100, v100, v244
	v_mul_f32_e32 v244, v103, v253
	v_mul_f32_e32 v245, v102, v253
	v_fma_f32 v102, v102, v252, -v244
	v_fma_f32 v103, v103, v252, v245
	v_pk_mul_f32 v[100:101], v[100:101], s[6:7] op_sel_hi:[1,0]
	v_pk_mul_f32 v[102:103], v[102:103], s[6:7] op_sel_hi:[1,0]
	global_load_dwordx4 v[250:253], v243, s[2:3] offset:64
	s_waitcnt vmcnt(8)
	v_mul_f32_e32 v244, v97, v151
	v_mul_f32_e32 v245, v96, v151
	v_mul_f32_e32 v96, v96, v150
	v_fma_f32 v97, v97, v150, v245
	v_sub_f32_e32 v96, v96, v244
	v_mul_f32_e32 v244, v99, v153
	v_mul_f32_e32 v245, v98, v153
	v_fma_f32 v98, v98, v152, -v244
	v_fma_f32 v99, v99, v152, v245
	v_pk_mul_f32 v[96:97], v[96:97], s[6:7] op_sel_hi:[1,0]
	v_pk_mul_f32 v[98:99], v[98:99], s[6:7] op_sel_hi:[1,0]
	v_cvt_pk_bf16_f32 v108, v108, v109
	v_cvt_pk_bf16_f32 v109, v110, v111
	v_cvt_pk_bf16_f32 v110, v104, v105
	v_cvt_pk_bf16_f32 v111, v106, v107
	v_cvt_pk_bf16_f32 v100, v100, v101
	v_cvt_pk_bf16_f32 v101, v102, v103
	v_cvt_pk_bf16_f32 v102, v96, v97
	v_cvt_pk_bf16_f32 v103, v98, v99
	v_permlane16_swap_b32_e32 v108, v110
	v_permlane16_swap_b32_e32 v109, v111
	v_permlane16_swap_b32_e32 v100, v102
	v_permlane16_swap_b32_e32 v101, v103
	global_store_dwordx4 v242, v[108:111], s[98:99]
	global_store_dwordx4 v242, v[100:103], s[98:99] offset:64
	s_add_u32 s98, s98, s7
	s_addc_u32 s99, s99, 0
	global_load_dwordx4 v[150:153], v243, s[2:3] offset:128
	s_waitcnt vmcnt(10)
	v_mul_f32_e32 v244, v93, v197
	v_mul_f32_e32 v245, v92, v197
	v_mul_f32_e32 v92, v92, v196
	v_fma_f32 v93, v93, v196, v245
	v_sub_f32_e32 v92, v92, v244
	v_mul_f32_e32 v244, v95, v199
	v_mul_f32_e32 v245, v94, v199
	v_fma_f32 v94, v94, v198, -v244
	v_fma_f32 v95, v95, v198, v245
	v_pk_mul_f32 v[92:93], v[92:93], s[6:7] op_sel_hi:[1,0]
	v_pk_mul_f32 v[94:95], v[94:95], s[6:7] op_sel_hi:[1,0]
	global_load_dwordx4 v[196:199], v243, s[2:3] offset:192
	s_waitcnt vmcnt(10)
	v_mul_f32_e32 v244, v89, v201
	v_mul_f32_e32 v245, v88, v201
	v_mul_f32_e32 v88, v88, v200
	v_fma_f32 v89, v89, v200, v245
	v_sub_f32_e32 v88, v88, v244
	v_mul_f32_e32 v244, v91, v203
	v_mul_f32_e32 v245, v90, v203
	v_fma_f32 v90, v90, v202, -v244
	v_fma_f32 v91, v91, v202, v245
	v_pk_mul_f32 v[88:89], v[88:89], s[6:7] op_sel_hi:[1,0]
	v_pk_mul_f32 v[90:91], v[90:91], s[6:7] op_sel_hi:[1,0]
	s_add_u32 s2, s2, 0x1000
	s_addc_u32 s3, s3, 0
	global_load_dwordx4 v[200:203], v243, s[2:3]
	s_waitcnt vmcnt(8)
	v_mul_f32_e32 v244, v85, v205
	v_mul_f32_e32 v245, v84, v205
	v_mul_f32_e32 v84, v84, v204
	v_fma_f32 v85, v85, v204, v245
	v_sub_f32_e32 v84, v84, v244
	v_mul_f32_e32 v244, v87, v207
	v_mul_f32_e32 v245, v86, v207
	v_fma_f32 v86, v86, v206, -v244
	v_fma_f32 v87, v87, v206, v245
	v_pk_mul_f32 v[84:85], v[84:85], s[6:7] op_sel_hi:[1,0]
	v_pk_mul_f32 v[86:87], v[86:87], s[6:7] op_sel_hi:[1,0]
	global_load_dwordx4 v[204:207], v243, s[2:3] offset:64
	s_waitcnt vmcnt(8)
	v_mul_f32_e32 v244, v81, v143
	v_mul_f32_e32 v245, v80, v143
	v_mul_f32_e32 v80, v80, v142
	v_fma_f32 v81, v81, v142, v245
	v_sub_f32_e32 v80, v80, v244
	v_mul_f32_e32 v244, v83, v145
	v_mul_f32_e32 v245, v82, v145
	v_fma_f32 v82, v82, v144, -v244
	v_fma_f32 v83, v83, v144, v245
	v_pk_mul_f32 v[80:81], v[80:81], s[6:7] op_sel_hi:[1,0]
	v_pk_mul_f32 v[82:83], v[82:83], s[6:7] op_sel_hi:[1,0]
	v_cvt_pk_bf16_f32 v92, v92, v93
	v_cvt_pk_bf16_f32 v93, v94, v95
	v_cvt_pk_bf16_f32 v94, v88, v89
	v_cvt_pk_bf16_f32 v95, v90, v91
	v_cvt_pk_bf16_f32 v84, v84, v85
	v_cvt_pk_bf16_f32 v85, v86, v87
	v_cvt_pk_bf16_f32 v86, v80, v81
	v_cvt_pk_bf16_f32 v87, v82, v83
	v_permlane16_swap_b32_e32 v92, v94
	v_permlane16_swap_b32_e32 v93, v95
	v_permlane16_swap_b32_e32 v84, v86
	v_permlane16_swap_b32_e32 v85, v87
	global_store_dwordx4 v242, v[92:95], s[98:99]
	global_store_dwordx4 v242, v[84:87], s[98:99] offset:64
	s_add_u32 s98, s98, s7
	s_addc_u32 s99, s99, 0
	global_load_dwordx4 v[142:145], v243, s[2:3] offset:128
	s_waitcnt vmcnt(10)
	v_mul_f32_e32 v244, v77, v247
	v_mul_f32_e32 v245, v76, v247
	v_mul_f32_e32 v76, v76, v246
	v_fma_f32 v77, v77, v246, v245
	v_sub_f32_e32 v76, v76, v244
	v_mul_f32_e32 v244, v79, v249
	v_mul_f32_e32 v245, v78, v249
	v_fma_f32 v78, v78, v248, -v244
	v_fma_f32 v79, v79, v248, v245
	v_pk_mul_f32 v[76:77], v[76:77], s[6:7] op_sel_hi:[1,0]
	v_pk_mul_f32 v[78:79], v[78:79], s[6:7] op_sel_hi:[1,0]
	global_load_dwordx4 v[246:249], v243, s[2:3] offset:192
	s_waitcnt vmcnt(10)
	v_mul_f32_e32 v244, v73, v251
	v_mul_f32_e32 v245, v72, v251
	v_mul_f32_e32 v72, v72, v250
	v_fma_f32 v73, v73, v250, v245
	v_sub_f32_e32 v72, v72, v244
	v_mul_f32_e32 v244, v75, v253
	v_mul_f32_e32 v245, v74, v253
	v_fma_f32 v74, v74, v252, -v244
	v_fma_f32 v75, v75, v252, v245
	v_pk_mul_f32 v[72:73], v[72:73], s[6:7] op_sel_hi:[1,0]
	v_pk_mul_f32 v[74:75], v[74:75], s[6:7] op_sel_hi:[1,0]
	s_add_u32 s2, s2, 0x1000
	s_addc_u32 s3, s3, 0
	global_load_dwordx4 v[250:253], v243, s[2:3]
	s_waitcnt vmcnt(8)
	v_mul_f32_e32 v244, v69, v151
	v_mul_f32_e32 v245, v68, v151
	v_mul_f32_e32 v68, v68, v150
	v_fma_f32 v69, v69, v150, v245
	v_sub_f32_e32 v68, v68, v244
	v_mul_f32_e32 v244, v71, v153
	v_mul_f32_e32 v245, v70, v153
	v_fma_f32 v70, v70, v152, -v244
	v_fma_f32 v71, v71, v152, v245
	v_pk_mul_f32 v[68:69], v[68:69], s[6:7] op_sel_hi:[1,0]
	v_pk_mul_f32 v[70:71], v[70:71], s[6:7] op_sel_hi:[1,0]
	global_load_dwordx4 v[150:153], v243, s[2:3] offset:64
	s_waitcnt vmcnt(8)
	v_mul_f32_e32 v244, v65, v197
	v_mul_f32_e32 v245, v64, v197
	v_mul_f32_e32 v64, v64, v196
	v_fma_f32 v65, v65, v196, v245
	v_sub_f32_e32 v64, v64, v244
	v_mul_f32_e32 v244, v67, v199
	v_mul_f32_e32 v245, v66, v199
	v_fma_f32 v66, v66, v198, -v244
	v_fma_f32 v67, v67, v198, v245
	v_pk_mul_f32 v[64:65], v[64:65], s[6:7] op_sel_hi:[1,0]
	v_pk_mul_f32 v[66:67], v[66:67], s[6:7] op_sel_hi:[1,0]
	v_cvt_pk_bf16_f32 v76, v76, v77
	v_cvt_pk_bf16_f32 v77, v78, v79
	v_cvt_pk_bf16_f32 v78, v72, v73
	v_cvt_pk_bf16_f32 v79, v74, v75
	v_cvt_pk_bf16_f32 v68, v68, v69
	v_cvt_pk_bf16_f32 v69, v70, v71
	v_cvt_pk_bf16_f32 v70, v64, v65
	v_cvt_pk_bf16_f32 v71, v66, v67
	v_permlane16_swap_b32_e32 v76, v78
	v_permlane16_swap_b32_e32 v77, v79
	v_permlane16_swap_b32_e32 v68, v70
	v_permlane16_swap_b32_e32 v69, v71
	global_store_dwordx4 v242, v[76:79], s[98:99]
	global_store_dwordx4 v242, v[68:71], s[98:99] offset:64
	s_add_u32 s98, s98, s7
	s_addc_u32 s99, s99, 0
	global_load_dwordx4 v[196:199], v243, s[2:3] offset:128
	s_waitcnt vmcnt(10)
	v_mul_f32_e32 v244, v61, v201
	v_mul_f32_e32 v245, v60, v201
	v_mul_f32_e32 v60, v60, v200
	v_fma_f32 v61, v61, v200, v245
	v_sub_f32_e32 v60, v60, v244
	v_mul_f32_e32 v244, v63, v203
	v_mul_f32_e32 v245, v62, v203
	v_fma_f32 v62, v62, v202, -v244
	v_fma_f32 v63, v63, v202, v245
	v_pk_mul_f32 v[60:61], v[60:61], s[6:7] op_sel_hi:[1,0]
	v_pk_mul_f32 v[62:63], v[62:63], s[6:7] op_sel_hi:[1,0]
	global_load_dwordx4 v[200:203], v243, s[2:3] offset:192
	s_waitcnt vmcnt(10)
	v_mul_f32_e32 v244, v57, v205
	v_mul_f32_e32 v245, v56, v205
	v_mul_f32_e32 v56, v56, v204
	v_fma_f32 v57, v57, v204, v245
	v_sub_f32_e32 v56, v56, v244
	v_mul_f32_e32 v244, v59, v207
	v_mul_f32_e32 v245, v58, v207
	v_fma_f32 v58, v58, v206, -v244
	v_fma_f32 v59, v59, v206, v245
	v_pk_mul_f32 v[56:57], v[56:57], s[6:7] op_sel_hi:[1,0]
	v_pk_mul_f32 v[58:59], v[58:59], s[6:7] op_sel_hi:[1,0]
	s_add_u32 s2, s2, 0x1000
	s_addc_u32 s3, s3, 0
	global_load_dwordx4 v[204:207], v243, s[2:3]
	s_waitcnt vmcnt(8)
	v_mul_f32_e32 v244, v53, v143
	v_mul_f32_e32 v245, v52, v143
	v_mul_f32_e32 v52, v52, v142
	v_fma_f32 v53, v53, v142, v245
	v_sub_f32_e32 v52, v52, v244
	v_mul_f32_e32 v244, v55, v145
	v_mul_f32_e32 v245, v54, v145
	v_fma_f32 v54, v54, v144, -v244
	v_fma_f32 v55, v55, v144, v245
	v_pk_mul_f32 v[52:53], v[52:53], s[6:7] op_sel_hi:[1,0]
	v_pk_mul_f32 v[54:55], v[54:55], s[6:7] op_sel_hi:[1,0]
	global_load_dwordx4 v[142:145], v243, s[2:3] offset:64
	s_waitcnt vmcnt(8)
	v_mul_f32_e32 v244, v49, v247
	v_mul_f32_e32 v245, v48, v247
	v_mul_f32_e32 v48, v48, v246
	v_fma_f32 v49, v49, v246, v245
	v_sub_f32_e32 v48, v48, v244
	v_mul_f32_e32 v244, v51, v249
	v_mul_f32_e32 v245, v50, v249
	v_fma_f32 v50, v50, v248, -v244
	v_fma_f32 v51, v51, v248, v245
	v_pk_mul_f32 v[48:49], v[48:49], s[6:7] op_sel_hi:[1,0]
	v_pk_mul_f32 v[50:51], v[50:51], s[6:7] op_sel_hi:[1,0]
	v_cvt_pk_bf16_f32 v60, v60, v61
	v_cvt_pk_bf16_f32 v61, v62, v63
	v_cvt_pk_bf16_f32 v62, v56, v57
	v_cvt_pk_bf16_f32 v63, v58, v59
	v_cvt_pk_bf16_f32 v52, v52, v53
	v_cvt_pk_bf16_f32 v53, v54, v55
	v_cvt_pk_bf16_f32 v54, v48, v49
	v_cvt_pk_bf16_f32 v55, v50, v51
	v_permlane16_swap_b32_e32 v60, v62
	v_permlane16_swap_b32_e32 v61, v63
	v_permlane16_swap_b32_e32 v52, v54
	v_permlane16_swap_b32_e32 v53, v55
	global_store_dwordx4 v242, v[60:63], s[98:99]
	global_store_dwordx4 v242, v[52:55], s[98:99] offset:64
	s_add_u32 s98, s98, s7
	s_addc_u32 s99, s99, 0
	global_load_dwordx4 v[246:249], v243, s[2:3] offset:128
	s_waitcnt vmcnt(10)
	v_mul_f32_e32 v244, v45, v251
	v_mul_f32_e32 v245, v44, v251
	v_mul_f32_e32 v44, v44, v250
	v_fma_f32 v45, v45, v250, v245
	v_sub_f32_e32 v44, v44, v244
	v_mul_f32_e32 v244, v47, v253
	v_mul_f32_e32 v245, v46, v253
	v_fma_f32 v46, v46, v252, -v244
	v_fma_f32 v47, v47, v252, v245
	v_pk_mul_f32 v[44:45], v[44:45], s[6:7] op_sel_hi:[1,0]
	v_pk_mul_f32 v[46:47], v[46:47], s[6:7] op_sel_hi:[1,0]
	global_load_dwordx4 v[250:253], v243, s[2:3] offset:192
	s_waitcnt vmcnt(10)
	v_mul_f32_e32 v244, v41, v151
	v_mul_f32_e32 v245, v40, v151
	v_mul_f32_e32 v40, v40, v150
	v_fma_f32 v41, v41, v150, v245
	v_sub_f32_e32 v40, v40, v244
	v_mul_f32_e32 v244, v43, v153
	v_mul_f32_e32 v245, v42, v153
	v_fma_f32 v42, v42, v152, -v244
	v_fma_f32 v43, v43, v152, v245
	v_pk_mul_f32 v[40:41], v[40:41], s[6:7] op_sel_hi:[1,0]
	v_pk_mul_f32 v[42:43], v[42:43], s[6:7] op_sel_hi:[1,0]
	s_add_u32 s2, s2, 0x1000
	s_addc_u32 s3, s3, 0
	global_load_dwordx4 v[150:153], v243, s[2:3]
	s_waitcnt vmcnt(8)
	v_mul_f32_e32 v244, v37, v197
	v_mul_f32_e32 v245, v36, v197
	v_mul_f32_e32 v36, v36, v196
	v_fma_f32 v37, v37, v196, v245
	v_sub_f32_e32 v36, v36, v244
	v_mul_f32_e32 v244, v39, v199
	v_mul_f32_e32 v245, v38, v199
	v_fma_f32 v38, v38, v198, -v244
	v_fma_f32 v39, v39, v198, v245
	v_pk_mul_f32 v[36:37], v[36:37], s[6:7] op_sel_hi:[1,0]
	v_pk_mul_f32 v[38:39], v[38:39], s[6:7] op_sel_hi:[1,0]
	global_load_dwordx4 v[196:199], v243, s[2:3] offset:64
	s_waitcnt vmcnt(8)
	v_mul_f32_e32 v244, v33, v201
	v_mul_f32_e32 v245, v32, v201
	v_mul_f32_e32 v32, v32, v200
	v_fma_f32 v33, v33, v200, v245
	v_sub_f32_e32 v32, v32, v244
	v_mul_f32_e32 v244, v35, v203
	v_mul_f32_e32 v245, v34, v203
	v_fma_f32 v34, v34, v202, -v244
	v_fma_f32 v35, v35, v202, v245
	v_pk_mul_f32 v[32:33], v[32:33], s[6:7] op_sel_hi:[1,0]
	v_pk_mul_f32 v[34:35], v[34:35], s[6:7] op_sel_hi:[1,0]
	v_cvt_pk_bf16_f32 v44, v44, v45
	v_cvt_pk_bf16_f32 v45, v46, v47
	v_cvt_pk_bf16_f32 v46, v40, v41
	v_cvt_pk_bf16_f32 v47, v42, v43
	v_cvt_pk_bf16_f32 v36, v36, v37
	v_cvt_pk_bf16_f32 v37, v38, v39
	v_cvt_pk_bf16_f32 v38, v32, v33
	v_cvt_pk_bf16_f32 v39, v34, v35
	v_permlane16_swap_b32_e32 v44, v46
	v_permlane16_swap_b32_e32 v45, v47
	v_permlane16_swap_b32_e32 v36, v38
	v_permlane16_swap_b32_e32 v37, v39
	global_store_dwordx4 v242, v[44:47], s[98:99]
	global_store_dwordx4 v242, v[36:39], s[98:99] offset:64
	s_add_u32 s98, s98, s7
	s_addc_u32 s99, s99, 0
	global_load_dwordx4 v[200:203], v243, s[2:3] offset:128
	s_waitcnt vmcnt(10)
	v_mul_f32_e32 v244, v29, v205
	v_mul_f32_e32 v245, v28, v205
	v_mul_f32_e32 v28, v28, v204
	v_fma_f32 v29, v29, v204, v245
	v_sub_f32_e32 v28, v28, v244
	v_mul_f32_e32 v244, v31, v207
	v_mul_f32_e32 v245, v30, v207
	v_fma_f32 v30, v30, v206, -v244
	v_fma_f32 v31, v31, v206, v245
	v_pk_mul_f32 v[28:29], v[28:29], s[6:7] op_sel_hi:[1,0]
	v_pk_mul_f32 v[30:31], v[30:31], s[6:7] op_sel_hi:[1,0]
	global_load_dwordx4 v[204:207], v243, s[2:3] offset:192
	s_waitcnt vmcnt(10)
	v_mul_f32_e32 v244, v25, v143
	v_mul_f32_e32 v245, v24, v143
	v_mul_f32_e32 v24, v24, v142
	v_fma_f32 v25, v25, v142, v245
	v_sub_f32_e32 v24, v24, v244
	v_mul_f32_e32 v244, v27, v145
	v_mul_f32_e32 v245, v26, v145
	v_fma_f32 v26, v26, v144, -v244
	v_fma_f32 v27, v27, v144, v245
	v_pk_mul_f32 v[24:25], v[24:25], s[6:7] op_sel_hi:[1,0]
	v_pk_mul_f32 v[26:27], v[26:27], s[6:7] op_sel_hi:[1,0]
	s_waitcnt vmcnt(7)
	v_mul_f32_e32 v244, v21, v247
	v_mul_f32_e32 v245, v20, v247
	v_mul_f32_e32 v20, v20, v246
	v_fma_f32 v21, v21, v246, v245
	v_sub_f32_e32 v20, v20, v244
	v_mul_f32_e32 v244, v23, v249
	v_mul_f32_e32 v245, v22, v249
	v_fma_f32 v22, v22, v248, -v244
	v_fma_f32 v23, v23, v248, v245
	v_pk_mul_f32 v[20:21], v[20:21], s[6:7] op_sel_hi:[1,0]
	v_pk_mul_f32 v[22:23], v[22:23], s[6:7] op_sel_hi:[1,0]
	s_waitcnt vmcnt(6)
	v_mul_f32_e32 v244, v17, v251
	v_mul_f32_e32 v245, v16, v251
	v_mul_f32_e32 v16, v16, v250
	v_fma_f32 v17, v17, v250, v245
	v_sub_f32_e32 v16, v16, v244
	v_mul_f32_e32 v244, v19, v253
	v_mul_f32_e32 v245, v18, v253
	v_fma_f32 v18, v18, v252, -v244
	v_fma_f32 v19, v19, v252, v245
	v_pk_mul_f32 v[16:17], v[16:17], s[6:7] op_sel_hi:[1,0]
	v_pk_mul_f32 v[18:19], v[18:19], s[6:7] op_sel_hi:[1,0]
	v_cvt_pk_bf16_f32 v28, v28, v29
	v_cvt_pk_bf16_f32 v29, v30, v31
	v_cvt_pk_bf16_f32 v30, v24, v25
	v_cvt_pk_bf16_f32 v31, v26, v27
	v_cvt_pk_bf16_f32 v20, v20, v21
	v_cvt_pk_bf16_f32 v21, v22, v23
	v_cvt_pk_bf16_f32 v22, v16, v17
	v_cvt_pk_bf16_f32 v23, v18, v19
	v_permlane16_swap_b32_e32 v28, v30
	v_permlane16_swap_b32_e32 v29, v31
	v_permlane16_swap_b32_e32 v20, v22
	v_permlane16_swap_b32_e32 v21, v23
	global_store_dwordx4 v242, v[28:31], s[98:99]
	global_store_dwordx4 v242, v[20:23], s[98:99] offset:64
	s_add_u32 s98, s98, s7
	s_addc_u32 s99, s99, 0
	s_waitcnt vmcnt(7)
	v_mul_f32_e32 v244, v13, v151
	v_mul_f32_e32 v245, v12, v151
	v_mul_f32_e32 v12, v12, v150
	v_fma_f32 v13, v13, v150, v245
	v_sub_f32_e32 v12, v12, v244
	v_mul_f32_e32 v244, v15, v153
	v_mul_f32_e32 v245, v14, v153
	v_fma_f32 v14, v14, v152, -v244
	v_fma_f32 v15, v15, v152, v245
	v_pk_mul_f32 v[12:13], v[12:13], s[6:7] op_sel_hi:[1,0]
	v_pk_mul_f32 v[14:15], v[14:15], s[6:7] op_sel_hi:[1,0]
	s_waitcnt vmcnt(6)
	v_mul_f32_e32 v244, v9, v197
	v_mul_f32_e32 v245, v8, v197
	v_mul_f32_e32 v8, v8, v196
	v_fma_f32 v9, v9, v196, v245
	v_sub_f32_e32 v8, v8, v244
	v_mul_f32_e32 v244, v11, v199
	v_mul_f32_e32 v245, v10, v199
	v_fma_f32 v10, v10, v198, -v244
	v_fma_f32 v11, v11, v198, v245
	v_pk_mul_f32 v[8:9], v[8:9], s[6:7] op_sel_hi:[1,0]
	v_pk_mul_f32 v[10:11], v[10:11], s[6:7] op_sel_hi:[1,0]
	s_waitcnt vmcnt(3)
	v_mul_f32_e32 v244, v5, v201
	v_mul_f32_e32 v245, v4, v201
	v_mul_f32_e32 v4, v4, v200
	v_fma_f32 v5, v5, v200, v245
	v_sub_f32_e32 v4, v4, v244
	v_mul_f32_e32 v244, v7, v203
	v_mul_f32_e32 v245, v6, v203
	v_fma_f32 v6, v6, v202, -v244
	v_fma_f32 v7, v7, v202, v245
	v_pk_mul_f32 v[4:5], v[4:5], s[6:7] op_sel_hi:[1,0]
	v_pk_mul_f32 v[6:7], v[6:7], s[6:7] op_sel_hi:[1,0]
	s_waitcnt vmcnt(2)
	v_mul_f32_e32 v244, v1, v205
	v_mul_f32_e32 v245, v0, v205
	v_mul_f32_e32 v0, v0, v204
	v_fma_f32 v1, v1, v204, v245
	v_sub_f32_e32 v0, v0, v244
	v_mul_f32_e32 v244, v3, v207
	v_mul_f32_e32 v245, v2, v207
	v_fma_f32 v2, v2, v206, -v244
	v_fma_f32 v3, v3, v206, v245
	v_pk_mul_f32 v[0:1], v[0:1], s[6:7] op_sel_hi:[1,0]
	v_pk_mul_f32 v[2:3], v[2:3], s[6:7] op_sel_hi:[1,0]
	v_cvt_pk_bf16_f32 v12, v12, v13
	v_cvt_pk_bf16_f32 v13, v14, v15
	v_cvt_pk_bf16_f32 v14, v8, v9
	v_cvt_pk_bf16_f32 v15, v10, v11
	v_cvt_pk_bf16_f32 v4, v4, v5
	v_cvt_pk_bf16_f32 v5, v6, v7
	v_cvt_pk_bf16_f32 v6, v0, v1
	v_cvt_pk_bf16_f32 v7, v2, v3
	v_permlane16_swap_b32_e32 v12, v14
	v_permlane16_swap_b32_e32 v13, v15
	v_permlane16_swap_b32_e32 v4, v6
	v_permlane16_swap_b32_e32 v5, v7
	global_store_dwordx4 v242, v[12:15], s[98:99]
	global_store_dwordx4 v242, v[4:7], s[98:99] offset:64
	s_branch .LBB0_1600
.Lepi19_k:
	s_cmpk_ge_u32 s36, 0x2000
	s_cbranch_scc1 .Lepi19_krope
	s_lshr_b32 s4, s36, 8
	s_lshl_b32 s4, s4, 1
	s_add_i32 s4, s4, 1
	s_lshl_b32 s4, s4, 8
	s_sub_i32 s5, s101, s36
	s_add_i32 s4, s4, s5
	s_lshl_b32 s4, s4, 12
	s_sub_i32 s5, s58, 0x400
	s_add_i32 s5, s5, s100
	s_lshl_b32 vcc_lo, s5, 2
	s_add_u32 s4, s4, vcc_lo
	s_add_u32 s2, s18, s4
	s_addc_u32 s3, s19, 0
	s_lshl_b32 s5, s5, 1
	s_lshl_b32 vcc_lo, s101, 11
	s_add_u32 s5, s5, vcc_lo
	s_add_u32 s98, s20, s5
	s_addc_u32 s99, s21, 0
	v_and_b32_e32 v243, 15, v178
	v_bfe_u32 v244, v178, 4, 2
	v_lshlrev_b32_e32 v243, 12, v243
	v_lshl_add_u32 v243, v244, 4, v243
	global_store_dwordx4 v243, v[124:127], s[2:3]
	global_store_dwordx4 v243, v[120:123], s[2:3] offset:64
	global_store_dwordx4 v243, v[116:119], s[2:3] offset:128
	global_store_dwordx4 v243, v[112:115], s[2:3] offset:192
	s_add_u32 s2, s2, 0x10000
	s_addc_u32 s3, s3, 0
	v_cvt_pk_bf16_f32 v124, v124, v125
	v_cvt_pk_bf16_f32 v125, v126, v127
	v_cvt_pk_bf16_f32 v126, v120, v121
	v_cvt_pk_bf16_f32 v127, v122, v123
	v_cvt_pk_bf16_f32 v116, v116, v117
	v_cvt_pk_bf16_f32 v117, v118, v119
	v_cvt_pk_bf16_f32 v118, v112, v113
	v_cvt_pk_bf16_f32 v119, v114, v115
	v_permlane16_swap_b32_e32 v124, v126
	v_permlane16_swap_b32_e32 v125, v127
	v_permlane16_swap_b32_e32 v116, v118
	v_permlane16_swap_b32_e32 v117, v119
	global_store_dwordx4 v242, v[124:127], s[98:99]
	global_store_dwordx4 v242, v[116:119], s[98:99] offset:64
	s_add_u32 s98, s98, s7
	s_addc_u32 s99, s99, 0
	global_store_dwordx4 v243, v[108:111], s[2:3]
	global_store_dwordx4 v243, v[104:107], s[2:3] offset:64
	global_store_dwordx4 v243, v[100:103], s[2:3] offset:128
	global_store_dwordx4 v243, v[96:99], s[2:3] offset:192
	s_add_u32 s2, s2, 0x10000
	s_addc_u32 s3, s3, 0
	v_cvt_pk_bf16_f32 v108, v108, v109
	v_cvt_pk_bf16_f32 v109, v110, v111
	v_cvt_pk_bf16_f32 v110, v104, v105
	v_cvt_pk_bf16_f32 v111, v106, v107
	v_cvt_pk_bf16_f32 v100, v100, v101
	v_cvt_pk_bf16_f32 v101, v102, v103
	v_cvt_pk_bf16_f32 v102, v96, v97
	v_cvt_pk_bf16_f32 v103, v98, v99
	v_permlane16_swap_b32_e32 v108, v110
	v_permlane16_swap_b32_e32 v109, v111
	v_permlane16_swap_b32_e32 v100, v102
	v_permlane16_swap_b32_e32 v101, v103
	global_store_dwordx4 v242, v[108:111], s[98:99]
	global_store_dwordx4 v242, v[100:103], s[98:99] offset:64
	s_add_u32 s98, s98, s7
	s_addc_u32 s99, s99, 0
	global_store_dwordx4 v243, v[92:95], s[2:3]
	global_store_dwordx4 v243, v[88:91], s[2:3] offset:64
	global_store_dwordx4 v243, v[84:87], s[2:3] offset:128
	global_store_dwordx4 v243, v[80:83], s[2:3] offset:192
	s_add_u32 s2, s2, 0x10000
	s_addc_u32 s3, s3, 0
	v_cvt_pk_bf16_f32 v92, v92, v93
	v_cvt_pk_bf16_f32 v93, v94, v95
	v_cvt_pk_bf16_f32 v94, v88, v89
	v_cvt_pk_bf16_f32 v95, v90, v91
	v_cvt_pk_bf16_f32 v84, v84, v85
	v_cvt_pk_bf16_f32 v85, v86, v87
	v_cvt_pk_bf16_f32 v86, v80, v81
	v_cvt_pk_bf16_f32 v87, v82, v83
	v_permlane16_swap_b32_e32 v92, v94
	v_permlane16_swap_b32_e32 v93, v95
	v_permlane16_swap_b32_e32 v84, v86
	v_permlane16_swap_b32_e32 v85, v87
	global_store_dwordx4 v242, v[92:95], s[98:99]
	global_store_dwordx4 v242, v[84:87], s[98:99] offset:64
	s_add_u32 s98, s98, s7
	s_addc_u32 s99, s99, 0
	global_store_dwordx4 v243, v[76:79], s[2:3]
	global_store_dwordx4 v243, v[72:75], s[2:3] offset:64
	global_store_dwordx4 v243, v[68:71], s[2:3] offset:128
	global_store_dwordx4 v243, v[64:67], s[2:3] offset:192
	s_add_u32 s2, s2, 0x10000
	s_addc_u32 s3, s3, 0
	v_cvt_pk_bf16_f32 v76, v76, v77
	v_cvt_pk_bf16_f32 v77, v78, v79
	v_cvt_pk_bf16_f32 v78, v72, v73
	v_cvt_pk_bf16_f32 v79, v74, v75
	v_cvt_pk_bf16_f32 v68, v68, v69
	v_cvt_pk_bf16_f32 v69, v70, v71
	v_cvt_pk_bf16_f32 v70, v64, v65
	v_cvt_pk_bf16_f32 v71, v66, v67
	v_permlane16_swap_b32_e32 v76, v78
	v_permlane16_swap_b32_e32 v77, v79
	v_permlane16_swap_b32_e32 v68, v70
	v_permlane16_swap_b32_e32 v69, v71
	global_store_dwordx4 v242, v[76:79], s[98:99]
	global_store_dwordx4 v242, v[68:71], s[98:99] offset:64
	s_add_u32 s98, s98, s7
	s_addc_u32 s99, s99, 0
	global_store_dwordx4 v243, v[60:63], s[2:3]
	global_store_dwordx4 v243, v[56:59], s[2:3] offset:64
	global_store_dwordx4 v243, v[52:55], s[2:3] offset:128
	global_store_dwordx4 v243, v[48:51], s[2:3] offset:192
	s_add_u32 s2, s2, 0x10000
	s_addc_u32 s3, s3, 0
	v_cvt_pk_bf16_f32 v60, v60, v61
	v_cvt_pk_bf16_f32 v61, v62, v63
	v_cvt_pk_bf16_f32 v62, v56, v57
	v_cvt_pk_bf16_f32 v63, v58, v59
	v_cvt_pk_bf16_f32 v52, v52, v53
	v_cvt_pk_bf16_f32 v53, v54, v55
	v_cvt_pk_bf16_f32 v54, v48, v49
	v_cvt_pk_bf16_f32 v55, v50, v51
	v_permlane16_swap_b32_e32 v60, v62
	v_permlane16_swap_b32_e32 v61, v63
	v_permlane16_swap_b32_e32 v52, v54
	v_permlane16_swap_b32_e32 v53, v55
	global_store_dwordx4 v242, v[60:63], s[98:99]
	global_store_dwordx4 v242, v[52:55], s[98:99] offset:64
	s_add_u32 s98, s98, s7
	s_addc_u32 s99, s99, 0
	global_store_dwordx4 v243, v[44:47], s[2:3]
	global_store_dwordx4 v243, v[40:43], s[2:3] offset:64
	global_store_dwordx4 v243, v[36:39], s[2:3] offset:128
	global_store_dwordx4 v243, v[32:35], s[2:3] offset:192
	s_add_u32 s2, s2, 0x10000
	s_addc_u32 s3, s3, 0
	v_cvt_pk_bf16_f32 v44, v44, v45
	v_cvt_pk_bf16_f32 v45, v46, v47
	v_cvt_pk_bf16_f32 v46, v40, v41
	v_cvt_pk_bf16_f32 v47, v42, v43
	v_cvt_pk_bf16_f32 v36, v36, v37
	v_cvt_pk_bf16_f32 v37, v38, v39
	v_cvt_pk_bf16_f32 v38, v32, v33
	v_cvt_pk_bf16_f32 v39, v34, v35
	v_permlane16_swap_b32_e32 v44, v46
	v_permlane16_swap_b32_e32 v45, v47
	v_permlane16_swap_b32_e32 v36, v38
	v_permlane16_swap_b32_e32 v37, v39
	global_store_dwordx4 v242, v[44:47], s[98:99]
	global_store_dwordx4 v242, v[36:39], s[98:99] offset:64
	s_add_u32 s98, s98, s7
	s_addc_u32 s99, s99, 0
	global_store_dwordx4 v243, v[28:31], s[2:3]
	global_store_dwordx4 v243, v[24:27], s[2:3] offset:64
	global_store_dwordx4 v243, v[20:23], s[2:3] offset:128
	global_store_dwordx4 v243, v[16:19], s[2:3] offset:192
	s_add_u32 s2, s2, 0x10000
	s_addc_u32 s3, s3, 0
	v_cvt_pk_bf16_f32 v28, v28, v29
	v_cvt_pk_bf16_f32 v29, v30, v31
	v_cvt_pk_bf16_f32 v30, v24, v25
	v_cvt_pk_bf16_f32 v31, v26, v27
	v_cvt_pk_bf16_f32 v20, v20, v21
	v_cvt_pk_bf16_f32 v21, v22, v23
	v_cvt_pk_bf16_f32 v22, v16, v17
	v_cvt_pk_bf16_f32 v23, v18, v19
	v_permlane16_swap_b32_e32 v28, v30
	v_permlane16_swap_b32_e32 v29, v31
	v_permlane16_swap_b32_e32 v20, v22
	v_permlane16_swap_b32_e32 v21, v23
	global_store_dwordx4 v242, v[28:31], s[98:99]
	global_store_dwordx4 v242, v[20:23], s[98:99] offset:64
	s_add_u32 s98, s98, s7
	s_addc_u32 s99, s99, 0
	global_store_dwordx4 v243, v[12:15], s[2:3]
	global_store_dwordx4 v243, v[8:11], s[2:3] offset:64
	global_store_dwordx4 v243, v[4:7], s[2:3] offset:128
	global_store_dwordx4 v243, v[0:3], s[2:3] offset:192
	v_cvt_pk_bf16_f32 v12, v12, v13
	v_cvt_pk_bf16_f32 v13, v14, v15
	v_cvt_pk_bf16_f32 v14, v8, v9
	v_cvt_pk_bf16_f32 v15, v10, v11
	v_cvt_pk_bf16_f32 v4, v4, v5
	v_cvt_pk_bf16_f32 v5, v6, v7
	v_cvt_pk_bf16_f32 v6, v0, v1
	v_cvt_pk_bf16_f32 v7, v2, v3
	v_permlane16_swap_b32_e32 v12, v14
	v_permlane16_swap_b32_e32 v13, v15
	v_permlane16_swap_b32_e32 v4, v6
	v_permlane16_swap_b32_e32 v5, v7
	global_store_dwordx4 v242, v[12:15], s[98:99]
	global_store_dwordx4 v242, v[4:7], s[98:99] offset:64
	s_branch .LBB0_1600
.Lepi19_krope:
	s_sub_i32 s3, s101, 0x2000
	s_sub_i32 s4, s36, 0x2000
	s_lshr_b32 s4, s4, 11
	s_lshl_b32 s5, s4, 9
	s_add_i32 s5, s5, s3
	s_lshl_b32 s5, s5, 11
	s_sub_i32 s4, s58, 0x400
	s_add_i32 s4, s4, s100
	s_lshl_b32 s4, s4, 1
	s_add_u32 s5, s5, s4
	s_add_u32 s98, s22, s5
	s_addc_u32 s99, s23, 0
	s_sub_i32 s3, s101, 0x2000
	s_and_b32 s3, s3, 0x7ff
	s_lshl_b32 s3, s3, 8
	s_add_u32 s2, s16, s3
	s_addc_u32 s3, s17, 0
	v_and_b32_e32 v243, 15, v178
	v_bfe_u32 v244, v178, 4, 2
	v_lshlrev_b32_e32 v243, 8, v243
	v_lshl_add_u32 v243, v244, 4, v243
	global_load_dwordx4 v[150:153], v243, s[2:3]
	global_load_dwordx4 v[196:199], v243, s[2:3] offset:64
	global_load_dwordx4 v[200:203], v243, s[2:3] offset:128
	global_load_dwordx4 v[204:207], v243, s[2:3] offset:192
	s_add_u32 s2, s2, 0x1000
	s_addc_u32 s3, s3, 0
	global_load_dwordx4 v[142:145], v243, s[2:3]
	global_load_dwordx4 v[246:249], v243, s[2:3] offset:64
	global_load_dwordx4 v[250:253], v243, s[2:3] offset:128
	s_waitcnt vmcnt(6)
	v_mul_f32_e32 v244, v125, v151
	v_mul_f32_e32 v245, v124, v151
	v_mul_f32_e32 v124, v124, v150
	v_fma_f32 v125, v125, v150, v245
	v_sub_f32_e32 v124, v124, v244
	v_mul_f32_e32 v244, v127, v153
	v_mul_f32_e32 v245, v126, v153
	v_fma_f32 v126, v126, v152, -v244
	v_fma_f32 v127, v127, v152, v245
	global_load_dwordx4 v[150:153], v243, s[2:3] offset:192
	s_waitcnt vmcnt(6)
	v_mul_f32_e32 v244, v121, v197
	v_mul_f32_e32 v245, v120, v197
	v_mul_f32_e32 v120, v120, v196
	v_fma_f32 v121, v121, v196, v245
	v_sub_f32_e32 v120, v120, v244
	v_mul_f32_e32 v244, v123, v199
	v_mul_f32_e32 v245, v122, v199
	v_fma_f32 v122, v122, v198, -v244
	v_fma_f32 v123, v123, v198, v245
	s_add_u32 s2, s2, 0x1000
	s_addc_u32 s3, s3, 0
	global_load_dwordx4 v[196:199], v243, s[2:3]
	s_waitcnt vmcnt(6)
	v_mul_f32_e32 v244, v117, v201
	v_mul_f32_e32 v245, v116, v201
	v_mul_f32_e32 v116, v116, v200
	v_fma_f32 v117, v117, v200, v245
	v_sub_f32_e32 v116, v116, v244
	v_mul_f32_e32 v244, v119, v203
	v_mul_f32_e32 v245, v118, v203
	v_fma_f32 v118, v118, v202, -v244
	v_fma_f32 v119, v119, v202, v245
	global_load_dwordx4 v[200:203], v243, s[2:3] offset:64
	s_waitcnt vmcnt(6)
	v_mul_f32_e32 v244, v113, v205
	v_mul_f32_e32 v245, v112, v205
	v_mul_f32_e32 v112, v112, v204
	v_fma_f32 v113, v113, v204, v245
	v_sub_f32_e32 v112, v112, v244
	v_mul_f32_e32 v244, v115, v207
	v_mul_f32_e32 v245, v114, v207
	v_fma_f32 v114, v114, v206, -v244
	v_fma_f32 v115, v115, v206, v245
	v_cvt_pk_bf16_f32 v124, v124, v125
	v_cvt_pk_bf16_f32 v125, v126, v127
	v_cvt_pk_bf16_f32 v126, v120, v121
	v_cvt_pk_bf16_f32 v127, v122, v123
	v_cvt_pk_bf16_f32 v116, v116, v117
	v_cvt_pk_bf16_f32 v117, v118, v119
	v_cvt_pk_bf16_f32 v118, v112, v113
	v_cvt_pk_bf16_f32 v119, v114, v115
	v_permlane16_swap_b32_e32 v124, v126
	v_permlane16_swap_b32_e32 v125, v127
	v_permlane16_swap_b32_e32 v116, v118
	v_permlane16_swap_b32_e32 v117, v119
	global_store_dwordx4 v242, v[124:127], s[98:99]
	global_store_dwordx4 v242, v[116:119], s[98:99] offset:64
	s_add_u32 s98, s98, s7
	s_addc_u32 s99, s99, 0
	global_load_dwordx4 v[204:207], v243, s[2:3] offset:128
	s_waitcnt vmcnt(8)
	v_mul_f32_e32 v244, v109, v143
	v_mul_f32_e32 v245, v108, v143
	v_mul_f32_e32 v108, v108, v142
	v_fma_f32 v109, v109, v142, v245
	v_sub_f32_e32 v108, v108, v244
	v_mul_f32_e32 v244, v111, v145
	v_mul_f32_e32 v245, v110, v145
	v_fma_f32 v110, v110, v144, -v244
	v_fma_f32 v111, v111, v144, v245
	global_load_dwordx4 v[142:145], v243, s[2:3] offset:192
	s_waitcnt vmcnt(8)
	v_mul_f32_e32 v244, v105, v247
	v_mul_f32_e32 v245, v104, v247
	v_mul_f32_e32 v104, v104, v246
	v_fma_f32 v105, v105, v246, v245
	v_sub_f32_e32 v104, v104, v244
	v_mul_f32_e32 v244, v107, v249
	v_mul_f32_e32 v245, v106, v249
	v_fma_f32 v106, v106, v248, -v244
	v_fma_f32 v107, v107, v248, v245
	s_add_u32 s2, s2, 0x1000
	s_addc_u32 s3, s3, 0
	global_load_dwordx4 v[246:249], v243, s[2:3]
	s_waitcnt vmcnt(8)
	v_mul_f32_e32 v244, v101, v251
	v_mul_f32_e32 v245, v100, v251
	v_mul_f32_e32 v100, v100, v250
	v_fma_f32 v101, v101, v250, v245
	v_sub_f32_e32 v100, v100, v244
	v_mul_f32_e32 v244, v103, v253
	v_mul_f32_e32 v245, v102, v253
	v_fma_f32 v102, v102, v252, -v244
	v_fma_f32 v103, v103, v252, v245
	global_load_dwordx4 v[250:253], v243, s[2:3] offset:64
	s_waitcnt vmcnt(8)
	v_mul_f32_e32 v244, v97, v151
	v_mul_f32_e32 v245, v96, v151
	v_mul_f32_e32 v96, v96, v150
	v_fma_f32 v97, v97, v150, v245
	v_sub_f32_e32 v96, v96, v244
	v_mul_f32_e32 v244, v99, v153
	v_mul_f32_e32 v245, v98, v153
	v_fma_f32 v98, v98, v152, -v244
	v_fma_f32 v99, v99, v152, v245
	v_cvt_pk_bf16_f32 v108, v108, v109
	v_cvt_pk_bf16_f32 v109, v110, v111
	v_cvt_pk_bf16_f32 v110, v104, v105
	v_cvt_pk_bf16_f32 v111, v106, v107
	v_cvt_pk_bf16_f32 v100, v100, v101
	v_cvt_pk_bf16_f32 v101, v102, v103
	v_cvt_pk_bf16_f32 v102, v96, v97
	v_cvt_pk_bf16_f32 v103, v98, v99
	v_permlane16_swap_b32_e32 v108, v110
	v_permlane16_swap_b32_e32 v109, v111
	v_permlane16_swap_b32_e32 v100, v102
	v_permlane16_swap_b32_e32 v101, v103
	global_store_dwordx4 v242, v[108:111], s[98:99]
	global_store_dwordx4 v242, v[100:103], s[98:99] offset:64
	s_add_u32 s98, s98, s7
	s_addc_u32 s99, s99, 0
	global_load_dwordx4 v[150:153], v243, s[2:3] offset:128
	s_waitcnt vmcnt(10)
	v_mul_f32_e32 v244, v93, v197
	v_mul_f32_e32 v245, v92, v197
	v_mul_f32_e32 v92, v92, v196
	v_fma_f32 v93, v93, v196, v245
	v_sub_f32_e32 v92, v92, v244
	v_mul_f32_e32 v244, v95, v199
	v_mul_f32_e32 v245, v94, v199
	v_fma_f32 v94, v94, v198, -v244
	v_fma_f32 v95, v95, v198, v245
	global_load_dwordx4 v[196:199], v243, s[2:3] offset:192
	s_waitcnt vmcnt(10)
	v_mul_f32_e32 v244, v89, v201
	v_mul_f32_e32 v245, v88, v201
	v_mul_f32_e32 v88, v88, v200
	v_fma_f32 v89, v89, v200, v245
	v_sub_f32_e32 v88, v88, v244
	v_mul_f32_e32 v244, v91, v203
	v_mul_f32_e32 v245, v90, v203
	v_fma_f32 v90, v90, v202, -v244
	v_fma_f32 v91, v91, v202, v245
	s_add_u32 s2, s2, 0x1000
	s_addc_u32 s3, s3, 0
	global_load_dwordx4 v[200:203], v243, s[2:3]
	s_waitcnt vmcnt(8)
	v_mul_f32_e32 v244, v85, v205
	v_mul_f32_e32 v245, v84, v205
	v_mul_f32_e32 v84, v84, v204
	v_fma_f32 v85, v85, v204, v245
	v_sub_f32_e32 v84, v84, v244
	v_mul_f32_e32 v244, v87, v207
	v_mul_f32_e32 v245, v86, v207
	v_fma_f32 v86, v86, v206, -v244
	v_fma_f32 v87, v87, v206, v245
	global_load_dwordx4 v[204:207], v243, s[2:3] offset:64
	s_waitcnt vmcnt(8)
	v_mul_f32_e32 v244, v81, v143
	v_mul_f32_e32 v245, v80, v143
	v_mul_f32_e32 v80, v80, v142
	v_fma_f32 v81, v81, v142, v245
	v_sub_f32_e32 v80, v80, v244
	v_mul_f32_e32 v244, v83, v145
	v_mul_f32_e32 v245, v82, v145
	v_fma_f32 v82, v82, v144, -v244
	v_fma_f32 v83, v83, v144, v245
	v_cvt_pk_bf16_f32 v92, v92, v93
	v_cvt_pk_bf16_f32 v93, v94, v95
	v_cvt_pk_bf16_f32 v94, v88, v89
	v_cvt_pk_bf16_f32 v95, v90, v91
	v_cvt_pk_bf16_f32 v84, v84, v85
	v_cvt_pk_bf16_f32 v85, v86, v87
	v_cvt_pk_bf16_f32 v86, v80, v81
	v_cvt_pk_bf16_f32 v87, v82, v83
	v_permlane16_swap_b32_e32 v92, v94
	v_permlane16_swap_b32_e32 v93, v95
	v_permlane16_swap_b32_e32 v84, v86
	v_permlane16_swap_b32_e32 v85, v87
	global_store_dwordx4 v242, v[92:95], s[98:99]
	global_store_dwordx4 v242, v[84:87], s[98:99] offset:64
	s_add_u32 s98, s98, s7
	s_addc_u32 s99, s99, 0
	global_load_dwordx4 v[142:145], v243, s[2:3] offset:128
	s_waitcnt vmcnt(10)
	v_mul_f32_e32 v244, v77, v247
	v_mul_f32_e32 v245, v76, v247
	v_mul_f32_e32 v76, v76, v246
	v_fma_f32 v77, v77, v246, v245
	v_sub_f32_e32 v76, v76, v244
	v_mul_f32_e32 v244, v79, v249
	v_mul_f32_e32 v245, v78, v249
	v_fma_f32 v78, v78, v248, -v244
	v_fma_f32 v79, v79, v248, v245
	global_load_dwordx4 v[246:249], v243, s[2:3] offset:192
	s_waitcnt vmcnt(10)
	v_mul_f32_e32 v244, v73, v251
	v_mul_f32_e32 v245, v72, v251
	v_mul_f32_e32 v72, v72, v250
	v_fma_f32 v73, v73, v250, v245
	v_sub_f32_e32 v72, v72, v244
	v_mul_f32_e32 v244, v75, v253
	v_mul_f32_e32 v245, v74, v253
	v_fma_f32 v74, v74, v252, -v244
	v_fma_f32 v75, v75, v252, v245
	s_add_u32 s2, s2, 0x1000
	s_addc_u32 s3, s3, 0
	global_load_dwordx4 v[250:253], v243, s[2:3]
	s_waitcnt vmcnt(8)
	v_mul_f32_e32 v244, v69, v151
	v_mul_f32_e32 v245, v68, v151
	v_mul_f32_e32 v68, v68, v150
	v_fma_f32 v69, v69, v150, v245
	v_sub_f32_e32 v68, v68, v244
	v_mul_f32_e32 v244, v71, v153
	v_mul_f32_e32 v245, v70, v153
	v_fma_f32 v70, v70, v152, -v244
	v_fma_f32 v71, v71, v152, v245
	global_load_dwordx4 v[150:153], v243, s[2:3] offset:64
	s_waitcnt vmcnt(8)
	v_mul_f32_e32 v244, v65, v197
	v_mul_f32_e32 v245, v64, v197
	v_mul_f32_e32 v64, v64, v196
	v_fma_f32 v65, v65, v196, v245
	v_sub_f32_e32 v64, v64, v244
	v_mul_f32_e32 v244, v67, v199
	v_mul_f32_e32 v245, v66, v199
	v_fma_f32 v66, v66, v198, -v244
	v_fma_f32 v67, v67, v198, v245
	v_cvt_pk_bf16_f32 v76, v76, v77
	v_cvt_pk_bf16_f32 v77, v78, v79
	v_cvt_pk_bf16_f32 v78, v72, v73
	v_cvt_pk_bf16_f32 v79, v74, v75
	v_cvt_pk_bf16_f32 v68, v68, v69
	v_cvt_pk_bf16_f32 v69, v70, v71
	v_cvt_pk_bf16_f32 v70, v64, v65
	v_cvt_pk_bf16_f32 v71, v66, v67
	v_permlane16_swap_b32_e32 v76, v78
	v_permlane16_swap_b32_e32 v77, v79
	v_permlane16_swap_b32_e32 v68, v70
	v_permlane16_swap_b32_e32 v69, v71
	global_store_dwordx4 v242, v[76:79], s[98:99]
	global_store_dwordx4 v242, v[68:71], s[98:99] offset:64
	s_add_u32 s98, s98, s7
	s_addc_u32 s99, s99, 0
	global_load_dwordx4 v[196:199], v243, s[2:3] offset:128
	s_waitcnt vmcnt(10)
	v_mul_f32_e32 v244, v61, v201
	v_mul_f32_e32 v245, v60, v201
	v_mul_f32_e32 v60, v60, v200
	v_fma_f32 v61, v61, v200, v245
	v_sub_f32_e32 v60, v60, v244
	v_mul_f32_e32 v244, v63, v203
	v_mul_f32_e32 v245, v62, v203
	v_fma_f32 v62, v62, v202, -v244
	v_fma_f32 v63, v63, v202, v245
	global_load_dwordx4 v[200:203], v243, s[2:3] offset:192
	s_waitcnt vmcnt(10)
	v_mul_f32_e32 v244, v57, v205
	v_mul_f32_e32 v245, v56, v205
	v_mul_f32_e32 v56, v56, v204
	v_fma_f32 v57, v57, v204, v245
	v_sub_f32_e32 v56, v56, v244
	v_mul_f32_e32 v244, v59, v207
	v_mul_f32_e32 v245, v58, v207
	v_fma_f32 v58, v58, v206, -v244
	v_fma_f32 v59, v59, v206, v245
	s_add_u32 s2, s2, 0x1000
	s_addc_u32 s3, s3, 0
	global_load_dwordx4 v[204:207], v243, s[2:3]
	s_waitcnt vmcnt(8)
	v_mul_f32_e32 v244, v53, v143
	v_mul_f32_e32 v245, v52, v143
	v_mul_f32_e32 v52, v52, v142
	v_fma_f32 v53, v53, v142, v245
	v_sub_f32_e32 v52, v52, v244
	v_mul_f32_e32 v244, v55, v145
	v_mul_f32_e32 v245, v54, v145
	v_fma_f32 v54, v54, v144, -v244
	v_fma_f32 v55, v55, v144, v245
	global_load_dwordx4 v[142:145], v243, s[2:3] offset:64
	s_waitcnt vmcnt(8)
	v_mul_f32_e32 v244, v49, v247
	v_mul_f32_e32 v245, v48, v247
	v_mul_f32_e32 v48, v48, v246
	v_fma_f32 v49, v49, v246, v245
	v_sub_f32_e32 v48, v48, v244
	v_mul_f32_e32 v244, v51, v249
	v_mul_f32_e32 v245, v50, v249
	v_fma_f32 v50, v50, v248, -v244
	v_fma_f32 v51, v51, v248, v245
	v_cvt_pk_bf16_f32 v60, v60, v61
	v_cvt_pk_bf16_f32 v61, v62, v63
	v_cvt_pk_bf16_f32 v62, v56, v57
	v_cvt_pk_bf16_f32 v63, v58, v59
	v_cvt_pk_bf16_f32 v52, v52, v53
	v_cvt_pk_bf16_f32 v53, v54, v55
	v_cvt_pk_bf16_f32 v54, v48, v49
	v_cvt_pk_bf16_f32 v55, v50, v51
	v_permlane16_swap_b32_e32 v60, v62
	v_permlane16_swap_b32_e32 v61, v63
	v_permlane16_swap_b32_e32 v52, v54
	v_permlane16_swap_b32_e32 v53, v55
	global_store_dwordx4 v242, v[60:63], s[98:99]
	global_store_dwordx4 v242, v[52:55], s[98:99] offset:64
	s_add_u32 s98, s98, s7
	s_addc_u32 s99, s99, 0
	global_load_dwordx4 v[246:249], v243, s[2:3] offset:128
	s_waitcnt vmcnt(10)
	v_mul_f32_e32 v244, v45, v251
	v_mul_f32_e32 v245, v44, v251
	v_mul_f32_e32 v44, v44, v250
	v_fma_f32 v45, v45, v250, v245
	v_sub_f32_e32 v44, v44, v244
	v_mul_f32_e32 v244, v47, v253
	v_mul_f32_e32 v245, v46, v253
	v_fma_f32 v46, v46, v252, -v244
	v_fma_f32 v47, v47, v252, v245
	global_load_dwordx4 v[250:253], v243, s[2:3] offset:192
	s_waitcnt vmcnt(10)
	v_mul_f32_e32 v244, v41, v151
	v_mul_f32_e32 v245, v40, v151
	v_mul_f32_e32 v40, v40, v150
	v_fma_f32 v41, v41, v150, v245
	v_sub_f32_e32 v40, v40, v244
	v_mul_f32_e32 v244, v43, v153
	v_mul_f32_e32 v245, v42, v153
	v_fma_f32 v42, v42, v152, -v244
	v_fma_f32 v43, v43, v152, v245
	s_add_u32 s2, s2, 0x1000
	s_addc_u32 s3, s3, 0
	global_load_dwordx4 v[150:153], v243, s[2:3]
	s_waitcnt vmcnt(8)
	v_mul_f32_e32 v244, v37, v197
	v_mul_f32_e32 v245, v36, v197
	v_mul_f32_e32 v36, v36, v196
	v_fma_f32 v37, v37, v196, v245
	v_sub_f32_e32 v36, v36, v244
	v_mul_f32_e32 v244, v39, v199
	v_mul_f32_e32 v245, v38, v199
	v_fma_f32 v38, v38, v198, -v244
	v_fma_f32 v39, v39, v198, v245
	global_load_dwordx4 v[196:199], v243, s[2:3] offset:64
	s_waitcnt vmcnt(8)
	v_mul_f32_e32 v244, v33, v201
	v_mul_f32_e32 v245, v32, v201
	v_mul_f32_e32 v32, v32, v200
	v_fma_f32 v33, v33, v200, v245
	v_sub_f32_e32 v32, v32, v244
	v_mul_f32_e32 v244, v35, v203
	v_mul_f32_e32 v245, v34, v203
	v_fma_f32 v34, v34, v202, -v244
	v_fma_f32 v35, v35, v202, v245
	v_cvt_pk_bf16_f32 v44, v44, v45
	v_cvt_pk_bf16_f32 v45, v46, v47
	v_cvt_pk_bf16_f32 v46, v40, v41
	v_cvt_pk_bf16_f32 v47, v42, v43
	v_cvt_pk_bf16_f32 v36, v36, v37
	v_cvt_pk_bf16_f32 v37, v38, v39
	v_cvt_pk_bf16_f32 v38, v32, v33
	v_cvt_pk_bf16_f32 v39, v34, v35
	v_permlane16_swap_b32_e32 v44, v46
	v_permlane16_swap_b32_e32 v45, v47
	v_permlane16_swap_b32_e32 v36, v38
	v_permlane16_swap_b32_e32 v37, v39
	global_store_dwordx4 v242, v[44:47], s[98:99]
	global_store_dwordx4 v242, v[36:39], s[98:99] offset:64
	s_add_u32 s98, s98, s7
	s_addc_u32 s99, s99, 0
	global_load_dwordx4 v[200:203], v243, s[2:3] offset:128
	s_waitcnt vmcnt(10)
	v_mul_f32_e32 v244, v29, v205
	v_mul_f32_e32 v245, v28, v205
	v_mul_f32_e32 v28, v28, v204
	v_fma_f32 v29, v29, v204, v245
	v_sub_f32_e32 v28, v28, v244
	v_mul_f32_e32 v244, v31, v207
	v_mul_f32_e32 v245, v30, v207
	v_fma_f32 v30, v30, v206, -v244
	v_fma_f32 v31, v31, v206, v245
	global_load_dwordx4 v[204:207], v243, s[2:3] offset:192
	s_waitcnt vmcnt(10)
	v_mul_f32_e32 v244, v25, v143
	v_mul_f32_e32 v245, v24, v143
	v_mul_f32_e32 v24, v24, v142
	v_fma_f32 v25, v25, v142, v245
	v_sub_f32_e32 v24, v24, v244
	v_mul_f32_e32 v244, v27, v145
	v_mul_f32_e32 v245, v26, v145
	v_fma_f32 v26, v26, v144, -v244
	v_fma_f32 v27, v27, v144, v245
	s_waitcnt vmcnt(7)
	v_mul_f32_e32 v244, v21, v247
	v_mul_f32_e32 v245, v20, v247
	v_mul_f32_e32 v20, v20, v246
	v_fma_f32 v21, v21, v246, v245
	v_sub_f32_e32 v20, v20, v244
	v_mul_f32_e32 v244, v23, v249
	v_mul_f32_e32 v245, v22, v249
	v_fma_f32 v22, v22, v248, -v244
	v_fma_f32 v23, v23, v248, v245
	s_waitcnt vmcnt(6)
	v_mul_f32_e32 v244, v17, v251
	v_mul_f32_e32 v245, v16, v251
	v_mul_f32_e32 v16, v16, v250
	v_fma_f32 v17, v17, v250, v245
	v_sub_f32_e32 v16, v16, v244
	v_mul_f32_e32 v244, v19, v253
	v_mul_f32_e32 v245, v18, v253
	v_fma_f32 v18, v18, v252, -v244
	v_fma_f32 v19, v19, v252, v245
	v_cvt_pk_bf16_f32 v28, v28, v29
	v_cvt_pk_bf16_f32 v29, v30, v31
	v_cvt_pk_bf16_f32 v30, v24, v25
	v_cvt_pk_bf16_f32 v31, v26, v27
	v_cvt_pk_bf16_f32 v20, v20, v21
	v_cvt_pk_bf16_f32 v21, v22, v23
	v_cvt_pk_bf16_f32 v22, v16, v17
	v_cvt_pk_bf16_f32 v23, v18, v19
	v_permlane16_swap_b32_e32 v28, v30
	v_permlane16_swap_b32_e32 v29, v31
	v_permlane16_swap_b32_e32 v20, v22
	v_permlane16_swap_b32_e32 v21, v23
	global_store_dwordx4 v242, v[28:31], s[98:99]
	global_store_dwordx4 v242, v[20:23], s[98:99] offset:64
	s_add_u32 s98, s98, s7
	s_addc_u32 s99, s99, 0
	s_waitcnt vmcnt(7)
	v_mul_f32_e32 v244, v13, v151
	v_mul_f32_e32 v245, v12, v151
	v_mul_f32_e32 v12, v12, v150
	v_fma_f32 v13, v13, v150, v245
	v_sub_f32_e32 v12, v12, v244
	v_mul_f32_e32 v244, v15, v153
	v_mul_f32_e32 v245, v14, v153
	v_fma_f32 v14, v14, v152, -v244
	v_fma_f32 v15, v15, v152, v245
	s_waitcnt vmcnt(6)
	v_mul_f32_e32 v244, v9, v197
	v_mul_f32_e32 v245, v8, v197
	v_mul_f32_e32 v8, v8, v196
	v_fma_f32 v9, v9, v196, v245
	v_sub_f32_e32 v8, v8, v244
	v_mul_f32_e32 v244, v11, v199
	v_mul_f32_e32 v245, v10, v199
	v_fma_f32 v10, v10, v198, -v244
	v_fma_f32 v11, v11, v198, v245
	s_waitcnt vmcnt(3)
	v_mul_f32_e32 v244, v5, v201
	v_mul_f32_e32 v245, v4, v201
	v_mul_f32_e32 v4, v4, v200
	v_fma_f32 v5, v5, v200, v245
	v_sub_f32_e32 v4, v4, v244
	v_mul_f32_e32 v244, v7, v203
	v_mul_f32_e32 v245, v6, v203
	v_fma_f32 v6, v6, v202, -v244
	v_fma_f32 v7, v7, v202, v245
	s_waitcnt vmcnt(2)
	v_mul_f32_e32 v244, v1, v205
	v_mul_f32_e32 v245, v0, v205
	v_mul_f32_e32 v0, v0, v204
	v_fma_f32 v1, v1, v204, v245
	v_sub_f32_e32 v0, v0, v244
	v_mul_f32_e32 v244, v3, v207
	v_mul_f32_e32 v245, v2, v207
	v_fma_f32 v2, v2, v206, -v244
	v_fma_f32 v3, v3, v206, v245
	v_cvt_pk_bf16_f32 v12, v12, v13
	v_cvt_pk_bf16_f32 v13, v14, v15
	v_cvt_pk_bf16_f32 v14, v8, v9
	v_cvt_pk_bf16_f32 v15, v10, v11
	v_cvt_pk_bf16_f32 v4, v4, v5
	v_cvt_pk_bf16_f32 v5, v6, v7
	v_cvt_pk_bf16_f32 v6, v0, v1
	v_cvt_pk_bf16_f32 v7, v2, v3
	v_permlane16_swap_b32_e32 v12, v14
	v_permlane16_swap_b32_e32 v13, v15
	v_permlane16_swap_b32_e32 v4, v6
	v_permlane16_swap_b32_e32 v5, v7
	global_store_dwordx4 v242, v[12:15], s[98:99]
	global_store_dwordx4 v242, v[4:7], s[98:99] offset:64
	s_branch .LBB0_1600
